# v12 + open barrier after the first chained MFMA pair (2 MFMAs before the barrier)
# baseline (speedup 1.0000x reference)
.LBB0_642:
	ds_read_b128 v[148:151], v139
	ds_read_b128 v[152:155], v139 offset:1024
	ds_read_b128 v[156:159], v139 offset:2048
	ds_read_b128 v[160:163], v139 offset:3072
	ds_read_b128 v[164:167], v140
	ds_read_b128 v[168:171], v140 offset:1024
	ds_read_b128 v[172:175], v140 offset:2048
	ds_read_b128 v[176:179], v140 offset:3072
	s_add_i32 s18, s71, 0xffe80080
	s_cmp_eq_u32 s58, s73
	s_cselect_b32 s74, s69, s18
	s_cselect_b32 s76, s70, s72
	s_or_b32 s75, s74, 0x80
	s_add_i32 s18, s71, 0xfff80000
	s_mov_b32 m0, s59
	ds_read_b128 v[180:183], v141
	ds_read_b128 v[184:187], v141 offset:1024
	ds_read_b128 v[188:191], v141 offset:2048
	ds_read_b128 v[192:195], v141 offset:3072
	ds_read_b128 v[196:199], v141 offset:4096
	ds_read_b128 v[200:203], v141 offset:5120
	ds_read_b128 v[204:207], v141 offset:6144
	ds_read_b128 v[208:211], v141 offset:7168
	buffer_load_dwordx4 v137, s[12:15], s18 offen lds
	s_mov_b32 m0, s60
	s_nop 0
	buffer_load_dwordx4 v137, s[12:15], s71 offen lds
	s_waitcnt vmcnt(8)
	s_waitcnt lgkmcnt(0)
	s_setprio 1
	v_mfma_f32_16x16x32_bf16 v[118:121], v[148:151], v[180:183], v[118:121]
	v_mfma_f32_16x16x32_bf16 v[118:121], v[152:155], v[184:187], v[118:121]
	s_barrier
	v_mfma_f32_16x16x32_bf16 v[114:117], v[156:159], v[180:183], v[114:117]
	v_mfma_f32_16x16x32_bf16 v[114:117], v[160:163], v[184:187], v[114:117]
	v_mfma_f32_16x16x32_bf16 v[126:129], v[164:167], v[180:183], v[126:129]
	v_mfma_f32_16x16x32_bf16 v[126:129], v[168:171], v[184:187], v[126:129]
	v_mfma_f32_16x16x32_bf16 v[122:125], v[172:175], v[180:183], v[122:125]
	v_mfma_f32_16x16x32_bf16 v[122:125], v[176:179], v[184:187], v[122:125]
	v_mfma_f32_16x16x32_bf16 v[98:101], v[172:175], v[188:191], v[98:101]
	v_mfma_f32_16x16x32_bf16 v[98:101], v[176:179], v[192:195], v[98:101]
	v_mfma_f32_16x16x32_bf16 v[106:109], v[164:167], v[188:191], v[106:109]
	v_mfma_f32_16x16x32_bf16 v[106:109], v[168:171], v[192:195], v[106:109]
	v_mfma_f32_16x16x32_bf16 v[102:105], v[156:159], v[188:191], v[102:105]
	v_mfma_f32_16x16x32_bf16 v[102:105], v[160:163], v[192:195], v[102:105]
	v_mfma_f32_16x16x32_bf16 v[110:113], v[148:151], v[188:191], v[110:113]
	v_mfma_f32_16x16x32_bf16 v[110:113], v[152:155], v[192:195], v[110:113]
	v_mfma_f32_16x16x32_bf16 v[94:97], v[148:151], v[196:199], v[94:97]
	v_mfma_f32_16x16x32_bf16 v[94:97], v[152:155], v[200:203], v[94:97]
	v_mfma_f32_16x16x32_bf16 v[86:89], v[156:159], v[196:199], v[86:89]
	v_mfma_f32_16x16x32_bf16 v[86:89], v[160:163], v[200:203], v[86:89]
	v_mfma_f32_16x16x32_bf16 v[90:93], v[164:167], v[196:199], v[90:93]
	v_mfma_f32_16x16x32_bf16 v[90:93], v[168:171], v[200:203], v[90:93]
	v_mfma_f32_16x16x32_bf16 v[82:85], v[172:175], v[196:199], v[82:85]
	v_mfma_f32_16x16x32_bf16 v[82:85], v[176:179], v[200:203], v[82:85]
	v_mfma_f32_16x16x32_bf16 v[70:73], v[172:175], v[204:207], v[70:73]
	v_mfma_f32_16x16x32_bf16 v[70:73], v[176:179], v[208:211], v[70:73]
	v_mfma_f32_16x16x32_bf16 v[74:77], v[164:167], v[204:207], v[74:77]
	v_mfma_f32_16x16x32_bf16 v[74:77], v[168:171], v[208:211], v[74:77]
	v_mfma_f32_16x16x32_bf16 v[66:69], v[156:159], v[204:207], v[66:69]
	v_mfma_f32_16x16x32_bf16 v[66:69], v[160:163], v[208:211], v[66:69]
	v_mfma_f32_16x16x32_bf16 v[78:81], v[148:151], v[204:207], v[78:81]
	v_mfma_f32_16x16x32_bf16 v[78:81], v[152:155], v[208:211], v[78:81]
	s_setprio 0
	s_barrier
	s_mov_b32 m0, s30
	s_mov_b32 s18, s14
	s_mov_b32 s19, s15
	ds_read_b128 v[180:183], v141 offset:16384
	ds_read_b128 v[184:187], v141 offset:17408
	ds_read_b128 v[188:191], v141 offset:18432
	ds_read_b128 v[192:195], v141 offset:19456
	ds_read_b128 v[196:199], v141 offset:20480
	ds_read_b128 v[200:203], v141 offset:21504
	ds_read_b128 v[204:207], v141 offset:22528
	ds_read_b128 v[208:211], v141 offset:23552
	buffer_load_dwordx4 v138, s[16:19], s76 offen lds
	s_add_i32 s77, s76, 0x80000
	s_mov_b32 m0, s31
	s_nop 0
	buffer_load_dwordx4 v138, s[16:19], s77 offen lds
	s_add_i32 s77, s76, 0x100000
	s_mov_b32 m0, s44
	s_nop 0
	buffer_load_dwordx4 v138, s[16:19], s77 offen lds
	s_add_i32 s77, s76, 0x180000
	s_mov_b32 m0, s45
	s_nop 0
	buffer_load_dwordx4 v138, s[16:19], s77 offen lds
	s_mov_b32 m0, s27
	s_add_i32 s77, s74, 0x80000
	buffer_load_dwordx4 v137, s[12:15], s74 offen lds
	s_mov_b32 m0, s46
	s_nop 0
	buffer_load_dwordx4 v137, s[12:15], s77 offen lds
	s_waitcnt vmcnt(8)
	s_waitcnt lgkmcnt(0)
	s_setprio 1
	v_mfma_f32_16x16x32_bf16 v[62:65], v[148:151], v[180:183], v[62:65]
	v_mfma_f32_16x16x32_bf16 v[62:65], v[152:155], v[184:187], v[62:65]
	s_barrier
	v_mfma_f32_16x16x32_bf16 v[54:57], v[156:159], v[180:183], v[54:57]
	v_mfma_f32_16x16x32_bf16 v[54:57], v[160:163], v[184:187], v[54:57]
	v_mfma_f32_16x16x32_bf16 v[58:61], v[164:167], v[180:183], v[58:61]
	v_mfma_f32_16x16x32_bf16 v[58:61], v[168:171], v[184:187], v[58:61]
	v_mfma_f32_16x16x32_bf16 v[50:53], v[172:175], v[180:183], v[50:53]
	v_mfma_f32_16x16x32_bf16 v[50:53], v[176:179], v[184:187], v[50:53]
	v_mfma_f32_16x16x32_bf16 v[34:37], v[172:175], v[188:191], v[34:37]
	v_mfma_f32_16x16x32_bf16 v[34:37], v[176:179], v[192:195], v[34:37]
	v_mfma_f32_16x16x32_bf16 v[42:45], v[164:167], v[188:191], v[42:45]
	v_mfma_f32_16x16x32_bf16 v[42:45], v[168:171], v[192:195], v[42:45]
	v_mfma_f32_16x16x32_bf16 v[38:41], v[156:159], v[188:191], v[38:41]
	v_mfma_f32_16x16x32_bf16 v[38:41], v[160:163], v[192:195], v[38:41]
	v_mfma_f32_16x16x32_bf16 v[46:49], v[148:151], v[188:191], v[46:49]
	v_mfma_f32_16x16x32_bf16 v[46:49], v[152:155], v[192:195], v[46:49]
	v_mfma_f32_16x16x32_bf16 v[30:33], v[148:151], v[196:199], v[30:33]
	v_mfma_f32_16x16x32_bf16 v[30:33], v[152:155], v[200:203], v[30:33]
	v_mfma_f32_16x16x32_bf16 v[22:25], v[156:159], v[196:199], v[22:25]
	v_mfma_f32_16x16x32_bf16 v[22:25], v[160:163], v[200:203], v[22:25]
	v_mfma_f32_16x16x32_bf16 v[26:29], v[164:167], v[196:199], v[26:29]
	v_mfma_f32_16x16x32_bf16 v[26:29], v[168:171], v[200:203], v[26:29]
	v_mfma_f32_16x16x32_bf16 v[18:21], v[172:175], v[196:199], v[18:21]
	v_mfma_f32_16x16x32_bf16 v[18:21], v[176:179], v[200:203], v[18:21]
	v_mfma_f32_16x16x32_bf16 v[2:5], v[172:175], v[204:207], v[2:5]
	v_mfma_f32_16x16x32_bf16 v[2:5], v[176:179], v[208:211], v[2:5]
	v_mfma_f32_16x16x32_bf16 v[10:13], v[164:167], v[204:207], v[10:13]
	v_mfma_f32_16x16x32_bf16 v[10:13], v[168:171], v[208:211], v[10:13]
	v_mfma_f32_16x16x32_bf16 v[6:9], v[156:159], v[204:207], v[6:9]
	v_mfma_f32_16x16x32_bf16 v[6:9], v[160:163], v[208:211], v[6:9]
	v_mfma_f32_16x16x32_bf16 v[14:17], v[148:151], v[204:207], v[14:17]
	v_mfma_f32_16x16x32_bf16 v[14:17], v[152:155], v[208:211], v[14:17]
	s_setprio 0
	s_barrier
	ds_read_b128 v[148:151], v142
	ds_read_b128 v[152:155], v142 offset:1024
	ds_read_b128 v[156:159], v142 offset:2048
	ds_read_b128 v[160:163], v142 offset:3072
	ds_read_b128 v[164:167], v143
	ds_read_b128 v[168:171], v143 offset:1024
	ds_read_b128 v[172:175], v143 offset:2048
	ds_read_b128 v[176:179], v143 offset:3072
	s_mov_b32 m0, s47
	s_add_i32 s77, s74, 0x100000
	ds_read_b128 v[180:183], v141 offset:32768
	ds_read_b128 v[184:187], v141 offset:33792
	ds_read_b128 v[188:191], v141 offset:34816
	ds_read_b128 v[192:195], v141 offset:35840
	ds_read_b128 v[196:199], v141 offset:36864
	ds_read_b128 v[200:203], v141 offset:37888
	ds_read_b128 v[204:207], v141 offset:38912
	ds_read_b128 v[208:211], v141 offset:39936
	buffer_load_dwordx4 v137, s[12:15], s77 offen lds
	s_add_i32 s77, s74, 0x180000
	s_mov_b32 m0, s48
	s_nop 0
	buffer_load_dwordx4 v137, s[12:15], s77 offen lds
	s_waitcnt vmcnt(8)
	s_waitcnt lgkmcnt(0)
	s_setprio 1
	v_mfma_f32_16x16x32_bf16 v[118:121], v[148:151], v[180:183], v[118:121]
	v_mfma_f32_16x16x32_bf16 v[118:121], v[152:155], v[184:187], v[118:121]
	s_barrier
	v_mfma_f32_16x16x32_bf16 v[114:117], v[156:159], v[180:183], v[114:117]
	v_mfma_f32_16x16x32_bf16 v[114:117], v[160:163], v[184:187], v[114:117]
	v_mfma_f32_16x16x32_bf16 v[126:129], v[164:167], v[180:183], v[126:129]
	v_mfma_f32_16x16x32_bf16 v[126:129], v[168:171], v[184:187], v[126:129]
	v_mfma_f32_16x16x32_bf16 v[122:125], v[172:175], v[180:183], v[122:125]
	v_mfma_f32_16x16x32_bf16 v[122:125], v[176:179], v[184:187], v[122:125]
	v_mfma_f32_16x16x32_bf16 v[98:101], v[172:175], v[188:191], v[98:101]
	v_mfma_f32_16x16x32_bf16 v[98:101], v[176:179], v[192:195], v[98:101]
	v_mfma_f32_16x16x32_bf16 v[106:109], v[164:167], v[188:191], v[106:109]
	v_mfma_f32_16x16x32_bf16 v[106:109], v[168:171], v[192:195], v[106:109]
	v_mfma_f32_16x16x32_bf16 v[102:105], v[156:159], v[188:191], v[102:105]
	v_mfma_f32_16x16x32_bf16 v[102:105], v[160:163], v[192:195], v[102:105]
	v_mfma_f32_16x16x32_bf16 v[110:113], v[148:151], v[188:191], v[110:113]
	v_mfma_f32_16x16x32_bf16 v[110:113], v[152:155], v[192:195], v[110:113]
	v_mfma_f32_16x16x32_bf16 v[94:97], v[148:151], v[196:199], v[94:97]
	v_mfma_f32_16x16x32_bf16 v[94:97], v[152:155], v[200:203], v[94:97]
	v_mfma_f32_16x16x32_bf16 v[86:89], v[156:159], v[196:199], v[86:89]
	v_mfma_f32_16x16x32_bf16 v[86:89], v[160:163], v[200:203], v[86:89]
	v_mfma_f32_16x16x32_bf16 v[90:93], v[164:167], v[196:199], v[90:93]
	v_mfma_f32_16x16x32_bf16 v[90:93], v[168:171], v[200:203], v[90:93]
	v_mfma_f32_16x16x32_bf16 v[82:85], v[172:175], v[196:199], v[82:85]
	v_mfma_f32_16x16x32_bf16 v[82:85], v[176:179], v[200:203], v[82:85]
	v_mfma_f32_16x16x32_bf16 v[70:73], v[172:175], v[204:207], v[70:73]
	v_mfma_f32_16x16x32_bf16 v[70:73], v[176:179], v[208:211], v[70:73]
	v_mfma_f32_16x16x32_bf16 v[74:77], v[164:167], v[204:207], v[74:77]
	v_mfma_f32_16x16x32_bf16 v[74:77], v[168:171], v[208:211], v[74:77]
	v_mfma_f32_16x16x32_bf16 v[66:69], v[156:159], v[204:207], v[66:69]
	v_mfma_f32_16x16x32_bf16 v[66:69], v[160:163], v[208:211], v[66:69]
	v_mfma_f32_16x16x32_bf16 v[78:81], v[148:151], v[204:207], v[78:81]
	v_mfma_f32_16x16x32_bf16 v[78:81], v[152:155], v[208:211], v[78:81]
	s_setprio 0
	s_barrier
	s_mov_b32 m0, s50
	s_or_b32 s77, s76, 0x80
	ds_read_b128 v[180:183], v141 offset:49152
	ds_read_b128 v[184:187], v141 offset:50176
	ds_read_b128 v[188:191], v141 offset:51200
	ds_read_b128 v[192:195], v141 offset:52224
	ds_read_b128 v[196:199], v141 offset:53248
	ds_read_b128 v[200:203], v141 offset:54272
	ds_read_b128 v[204:207], v141 offset:55296
	ds_read_b128 v[208:211], v141 offset:56320
	buffer_load_dwordx4 v138, s[16:19], s77 offen lds
	s_add_i32 s77, s76, 0x80080
	s_mov_b32 m0, s51
	s_add_i32 s74, s74, 0x80080
	buffer_load_dwordx4 v138, s[16:19], s77 offen lds
	s_add_i32 s77, s76, 0x100080
	s_mov_b32 m0, s54
	s_add_i32 s76, s76, 0x180080
	buffer_load_dwordx4 v138, s[16:19], s77 offen lds
	s_mov_b32 m0, s55
	s_nop 0
	buffer_load_dwordx4 v138, s[16:19], s76 offen lds
	s_mov_b32 m0, s52
	s_nop 0
	buffer_load_dwordx4 v137, s[12:15], s75 offen lds
	s_mov_b32 m0, s53
	s_nop 0
	buffer_load_dwordx4 v137, s[12:15], s74 offen lds
	s_waitcnt vmcnt(8)
	s_waitcnt lgkmcnt(0)
	s_setprio 1
	v_mfma_f32_16x16x32_bf16 v[62:65], v[148:151], v[180:183], v[62:65]
	v_mfma_f32_16x16x32_bf16 v[62:65], v[152:155], v[184:187], v[62:65]
	s_barrier
	v_mfma_f32_16x16x32_bf16 v[54:57], v[156:159], v[180:183], v[54:57]
	v_mfma_f32_16x16x32_bf16 v[54:57], v[160:163], v[184:187], v[54:57]
	v_mfma_f32_16x16x32_bf16 v[58:61], v[164:167], v[180:183], v[58:61]
	v_mfma_f32_16x16x32_bf16 v[58:61], v[168:171], v[184:187], v[58:61]
	v_mfma_f32_16x16x32_bf16 v[50:53], v[172:175], v[180:183], v[50:53]
	v_mfma_f32_16x16x32_bf16 v[50:53], v[176:179], v[184:187], v[50:53]
	v_mfma_f32_16x16x32_bf16 v[34:37], v[172:175], v[188:191], v[34:37]
	v_mfma_f32_16x16x32_bf16 v[34:37], v[176:179], v[192:195], v[34:37]
	v_mfma_f32_16x16x32_bf16 v[42:45], v[164:167], v[188:191], v[42:45]
	v_mfma_f32_16x16x32_bf16 v[42:45], v[168:171], v[192:195], v[42:45]
	v_mfma_f32_16x16x32_bf16 v[38:41], v[156:159], v[188:191], v[38:41]
	v_mfma_f32_16x16x32_bf16 v[38:41], v[160:163], v[192:195], v[38:41]
	v_mfma_f32_16x16x32_bf16 v[46:49], v[148:151], v[188:191], v[46:49]
	v_mfma_f32_16x16x32_bf16 v[46:49], v[152:155], v[192:195], v[46:49]
	v_mfma_f32_16x16x32_bf16 v[30:33], v[148:151], v[196:199], v[30:33]
	v_mfma_f32_16x16x32_bf16 v[30:33], v[152:155], v[200:203], v[30:33]
	v_mfma_f32_16x16x32_bf16 v[22:25], v[156:159], v[196:199], v[22:25]
	v_mfma_f32_16x16x32_bf16 v[22:25], v[160:163], v[200:203], v[22:25]
	v_mfma_f32_16x16x32_bf16 v[26:29], v[164:167], v[196:199], v[26:29]
	v_mfma_f32_16x16x32_bf16 v[26:29], v[168:171], v[200:203], v[26:29]
	v_mfma_f32_16x16x32_bf16 v[18:21], v[172:175], v[196:199], v[18:21]
	v_mfma_f32_16x16x32_bf16 v[18:21], v[176:179], v[200:203], v[18:21]
	v_mfma_f32_16x16x32_bf16 v[2:5], v[172:175], v[204:207], v[2:5]
	v_mfma_f32_16x16x32_bf16 v[2:5], v[176:179], v[208:211], v[2:5]
	v_mfma_f32_16x16x32_bf16 v[10:13], v[164:167], v[204:207], v[10:13]
	v_mfma_f32_16x16x32_bf16 v[10:13], v[168:171], v[208:211], v[10:13]
	v_mfma_f32_16x16x32_bf16 v[6:9], v[156:159], v[204:207], v[6:9]
	v_mfma_f32_16x16x32_bf16 v[6:9], v[160:163], v[208:211], v[6:9]
	v_mfma_f32_16x16x32_bf16 v[14:17], v[148:151], v[204:207], v[14:17]
	v_mfma_f32_16x16x32_bf16 v[14:17], v[152:155], v[208:211], v[14:17]
	s_setprio 0
	s_barrier
	s_add_i32 s73, s73, 2
	s_addk_i32 s71, 0x100
	s_addk_i32 s72, 0x100
	s_cmp_ge_i32 s73, s3
	s_cbranch_scc0 .LBB0_642
	s_and_b64 vcc, exec, s[42:43]
	s_cbranch_vccz .LBB0_645

.LBB0_799:
	ds_read_b128 v[134:137], v210
	ds_read_b128 v[138:141], v210 offset:1024
	ds_read_b128 v[142:145], v210 offset:2048
	ds_read_b128 v[148:151], v210 offset:3072
	ds_read_b128 v[152:155], v211
	ds_read_b128 v[156:159], v211 offset:1024
	ds_read_b128 v[160:163], v211 offset:2048
	ds_read_b128 v[164:167], v211 offset:3072
	s_add_i32 s18, s77, 0xffbf8080
	s_cmp_eq_u32 s62, s79
	s_cselect_b32 s80, s6, s18
	s_cselect_b32 s82, s7, s78
	s_or_b32 s81, s80, 0x80
	s_add_i32 s18, s77, 0xffea8000
	s_mov_b32 m0, s63
	ds_read_b128 v[168:171], v212
	ds_read_b128 v[172:175], v212 offset:1024
	ds_read_b128 v[176:179], v212 offset:2048
	ds_read_b128 v[180:183], v212 offset:3072
	ds_read_b128 v[184:187], v212 offset:4096
	ds_read_b128 v[188:191], v212 offset:5120
	ds_read_b128 v[192:195], v212 offset:6144
	ds_read_b128 v[196:199], v212 offset:7168
	buffer_load_dwordx4 v208, s[12:15], s18 offen lds
	s_mov_b32 m0, s66
	s_nop 0
	buffer_load_dwordx4 v208, s[12:15], s77 offen lds
	s_waitcnt vmcnt(8)
	s_waitcnt lgkmcnt(0)
	s_setprio 1
	v_mfma_f32_16x16x32_bf16 v[126:129], v[134:137], v[168:171], v[126:129]
	v_mfma_f32_16x16x32_bf16 v[126:129], v[138:141], v[172:175], v[126:129]
	s_barrier
	v_mfma_f32_16x16x32_bf16 v[122:125], v[142:145], v[168:171], v[122:125]
	v_mfma_f32_16x16x32_bf16 v[122:125], v[148:151], v[172:175], v[122:125]
	v_mfma_f32_16x16x32_bf16 v[110:113], v[152:155], v[168:171], v[110:113]
	v_mfma_f32_16x16x32_bf16 v[110:113], v[156:159], v[172:175], v[110:113]
	v_mfma_f32_16x16x32_bf16 v[102:105], v[160:163], v[168:171], v[102:105]
	v_mfma_f32_16x16x32_bf16 v[102:105], v[164:167], v[172:175], v[102:105]
	v_mfma_f32_16x16x32_bf16 v[86:89], v[160:163], v[176:179], v[86:89]
	v_mfma_f32_16x16x32_bf16 v[86:89], v[164:167], v[180:183], v[86:89]
	v_mfma_f32_16x16x32_bf16 v[94:97], v[152:155], v[176:179], v[94:97]
	v_mfma_f32_16x16x32_bf16 v[94:97], v[156:159], v[180:183], v[94:97]
	v_mfma_f32_16x16x32_bf16 v[114:117], v[142:145], v[176:179], v[114:117]
	v_mfma_f32_16x16x32_bf16 v[114:117], v[148:151], v[180:183], v[114:117]
	v_mfma_f32_16x16x32_bf16 v[118:121], v[134:137], v[176:179], v[118:121]
	v_mfma_f32_16x16x32_bf16 v[118:121], v[138:141], v[180:183], v[118:121]
	v_mfma_f32_16x16x32_bf16 v[106:109], v[134:137], v[184:187], v[106:109]
	v_mfma_f32_16x16x32_bf16 v[106:109], v[138:141], v[188:191], v[106:109]
	v_mfma_f32_16x16x32_bf16 v[98:101], v[142:145], v[184:187], v[98:101]
	v_mfma_f32_16x16x32_bf16 v[98:101], v[148:151], v[188:191], v[98:101]
	v_mfma_f32_16x16x32_bf16 v[78:81], v[152:155], v[184:187], v[78:81]
	v_mfma_f32_16x16x32_bf16 v[78:81], v[156:159], v[188:191], v[78:81]
	v_mfma_f32_16x16x32_bf16 v[74:77], v[160:163], v[184:187], v[74:77]
	v_mfma_f32_16x16x32_bf16 v[74:77], v[164:167], v[188:191], v[74:77]
	v_mfma_f32_16x16x32_bf16 v[66:69], v[160:163], v[192:195], v[66:69]
	v_mfma_f32_16x16x32_bf16 v[66:69], v[164:167], v[196:199], v[66:69]
	v_mfma_f32_16x16x32_bf16 v[70:73], v[152:155], v[192:195], v[70:73]
	v_mfma_f32_16x16x32_bf16 v[70:73], v[156:159], v[196:199], v[70:73]
	v_mfma_f32_16x16x32_bf16 v[82:85], v[142:145], v[192:195], v[82:85]
	v_mfma_f32_16x16x32_bf16 v[82:85], v[148:151], v[196:199], v[82:85]
	v_mfma_f32_16x16x32_bf16 v[90:93], v[134:137], v[192:195], v[90:93]
	v_mfma_f32_16x16x32_bf16 v[90:93], v[138:141], v[196:199], v[90:93]
	s_setprio 0
	s_barrier
	s_mov_b32 m0, s25
	s_mov_b32 s18, s14
	s_mov_b32 s19, s15
	ds_read_b128 v[168:171], v212 offset:16384
	ds_read_b128 v[172:175], v212 offset:17408
	ds_read_b128 v[176:179], v212 offset:18432
	ds_read_b128 v[180:183], v212 offset:19456
	ds_read_b128 v[184:187], v212 offset:20480
	ds_read_b128 v[188:191], v212 offset:21504
	ds_read_b128 v[192:195], v212 offset:22528
	ds_read_b128 v[196:199], v212 offset:23552
	buffer_load_dwordx4 v209, s[16:19], s82 offen lds
	s_add_i32 s83, s82, 0x158000
	s_mov_b32 m0, s27
	s_nop 0
	buffer_load_dwordx4 v209, s[16:19], s83 offen lds
	s_add_i32 s83, s82, 0x2b0000
	s_mov_b32 m0, s30
	s_nop 0
	buffer_load_dwordx4 v209, s[16:19], s83 offen lds
	s_add_i32 s83, s82, 0x408000
	s_mov_b32 m0, s31
	s_nop 0
	buffer_load_dwordx4 v209, s[16:19], s83 offen lds
	s_mov_b32 m0, s21
	s_add_i32 s83, s80, 0x158000
	buffer_load_dwordx4 v208, s[12:15], s80 offen lds
	s_mov_b32 m0, s48
	s_nop 0
	buffer_load_dwordx4 v208, s[12:15], s83 offen lds
	s_waitcnt vmcnt(8)
	s_waitcnt lgkmcnt(0)
	s_setprio 1
	v_mfma_f32_16x16x32_bf16 v[62:65], v[134:137], v[168:171], v[62:65]
	v_mfma_f32_16x16x32_bf16 v[62:65], v[138:141], v[172:175], v[62:65]
	s_barrier
	v_mfma_f32_16x16x32_bf16 v[58:61], v[142:145], v[168:171], v[58:61]
	v_mfma_f32_16x16x32_bf16 v[58:61], v[148:151], v[172:175], v[58:61]
	v_mfma_f32_16x16x32_bf16 v[46:49], v[152:155], v[168:171], v[46:49]
	v_mfma_f32_16x16x32_bf16 v[46:49], v[156:159], v[172:175], v[46:49]
	v_mfma_f32_16x16x32_bf16 v[38:41], v[160:163], v[168:171], v[38:41]
	v_mfma_f32_16x16x32_bf16 v[38:41], v[164:167], v[172:175], v[38:41]
	v_mfma_f32_16x16x32_bf16 v[22:25], v[160:163], v[176:179], v[22:25]
	v_mfma_f32_16x16x32_bf16 v[22:25], v[164:167], v[180:183], v[22:25]
	v_mfma_f32_16x16x32_bf16 v[30:33], v[152:155], v[176:179], v[30:33]
	v_mfma_f32_16x16x32_bf16 v[30:33], v[156:159], v[180:183], v[30:33]
	v_mfma_f32_16x16x32_bf16 v[50:53], v[142:145], v[176:179], v[50:53]
	v_mfma_f32_16x16x32_bf16 v[50:53], v[148:151], v[180:183], v[50:53]
	v_mfma_f32_16x16x32_bf16 v[54:57], v[134:137], v[176:179], v[54:57]
	v_mfma_f32_16x16x32_bf16 v[54:57], v[138:141], v[180:183], v[54:57]
	v_mfma_f32_16x16x32_bf16 v[42:45], v[134:137], v[184:187], v[42:45]
	v_mfma_f32_16x16x32_bf16 v[42:45], v[138:141], v[188:191], v[42:45]
	v_mfma_f32_16x16x32_bf16 v[34:37], v[142:145], v[184:187], v[34:37]
	v_mfma_f32_16x16x32_bf16 v[34:37], v[148:151], v[188:191], v[34:37]
	v_mfma_f32_16x16x32_bf16 v[14:17], v[152:155], v[184:187], v[14:17]
	v_mfma_f32_16x16x32_bf16 v[14:17], v[156:159], v[188:191], v[14:17]
	v_mfma_f32_16x16x32_bf16 v[10:13], v[160:163], v[184:187], v[10:13]
	v_mfma_f32_16x16x32_bf16 v[10:13], v[164:167], v[188:191], v[10:13]
	v_mfma_f32_16x16x32_bf16 v[2:5], v[160:163], v[192:195], v[2:5]
	v_mfma_f32_16x16x32_bf16 v[2:5], v[164:167], v[196:199], v[2:5]
	v_mfma_f32_16x16x32_bf16 v[6:9], v[152:155], v[192:195], v[6:9]
	v_mfma_f32_16x16x32_bf16 v[6:9], v[156:159], v[196:199], v[6:9]
	v_mfma_f32_16x16x32_bf16 v[18:21], v[142:145], v[192:195], v[18:21]
	v_mfma_f32_16x16x32_bf16 v[18:21], v[148:151], v[196:199], v[18:21]
	v_mfma_f32_16x16x32_bf16 v[26:29], v[134:137], v[192:195], v[26:29]
	v_mfma_f32_16x16x32_bf16 v[26:29], v[138:141], v[196:199], v[26:29]
	s_setprio 0
	s_barrier
	ds_read_b128 v[134:137], v213
	ds_read_b128 v[138:141], v213 offset:1024
	ds_read_b128 v[142:145], v213 offset:2048
	ds_read_b128 v[148:151], v213 offset:3072
	ds_read_b128 v[152:155], v214
	ds_read_b128 v[156:159], v214 offset:1024
	ds_read_b128 v[160:163], v214 offset:2048
	ds_read_b128 v[164:167], v214 offset:3072
	s_mov_b32 m0, s49
	s_add_i32 s83, s80, 0x2b0000
	ds_read_b128 v[168:171], v212 offset:32768
	ds_read_b128 v[172:175], v212 offset:33792
	ds_read_b128 v[176:179], v212 offset:34816
	ds_read_b128 v[180:183], v212 offset:35840
	ds_read_b128 v[184:187], v212 offset:36864
	ds_read_b128 v[188:191], v212 offset:37888
	ds_read_b128 v[192:195], v212 offset:38912
	ds_read_b128 v[196:199], v212 offset:39936
	buffer_load_dwordx4 v208, s[12:15], s83 offen lds
	s_add_i32 s83, s80, 0x408000
	s_mov_b32 m0, s50
	s_nop 0
	buffer_load_dwordx4 v208, s[12:15], s83 offen lds
	s_waitcnt vmcnt(8)
	s_waitcnt lgkmcnt(0)
	s_setprio 1
	v_mfma_f32_16x16x32_bf16 v[126:129], v[134:137], v[168:171], v[126:129]
	v_mfma_f32_16x16x32_bf16 v[126:129], v[138:141], v[172:175], v[126:129]
	s_barrier
	v_mfma_f32_16x16x32_bf16 v[122:125], v[142:145], v[168:171], v[122:125]
	v_mfma_f32_16x16x32_bf16 v[122:125], v[148:151], v[172:175], v[122:125]
	v_mfma_f32_16x16x32_bf16 v[110:113], v[152:155], v[168:171], v[110:113]
	v_mfma_f32_16x16x32_bf16 v[110:113], v[156:159], v[172:175], v[110:113]
	v_mfma_f32_16x16x32_bf16 v[102:105], v[160:163], v[168:171], v[102:105]
	v_mfma_f32_16x16x32_bf16 v[102:105], v[164:167], v[172:175], v[102:105]
	v_mfma_f32_16x16x32_bf16 v[86:89], v[160:163], v[176:179], v[86:89]
	v_mfma_f32_16x16x32_bf16 v[86:89], v[164:167], v[180:183], v[86:89]
	v_mfma_f32_16x16x32_bf16 v[94:97], v[152:155], v[176:179], v[94:97]
	v_mfma_f32_16x16x32_bf16 v[94:97], v[156:159], v[180:183], v[94:97]
	v_mfma_f32_16x16x32_bf16 v[114:117], v[142:145], v[176:179], v[114:117]
	v_mfma_f32_16x16x32_bf16 v[114:117], v[148:151], v[180:183], v[114:117]
	v_mfma_f32_16x16x32_bf16 v[118:121], v[134:137], v[176:179], v[118:121]
	v_mfma_f32_16x16x32_bf16 v[118:121], v[138:141], v[180:183], v[118:121]
	v_mfma_f32_16x16x32_bf16 v[106:109], v[134:137], v[184:187], v[106:109]
	v_mfma_f32_16x16x32_bf16 v[106:109], v[138:141], v[188:191], v[106:109]
	v_mfma_f32_16x16x32_bf16 v[98:101], v[142:145], v[184:187], v[98:101]
	v_mfma_f32_16x16x32_bf16 v[98:101], v[148:151], v[188:191], v[98:101]
	v_mfma_f32_16x16x32_bf16 v[78:81], v[152:155], v[184:187], v[78:81]
	v_mfma_f32_16x16x32_bf16 v[78:81], v[156:159], v[188:191], v[78:81]
	v_mfma_f32_16x16x32_bf16 v[74:77], v[160:163], v[184:187], v[74:77]
	v_mfma_f32_16x16x32_bf16 v[74:77], v[164:167], v[188:191], v[74:77]
	v_mfma_f32_16x16x32_bf16 v[66:69], v[160:163], v[192:195], v[66:69]
	v_mfma_f32_16x16x32_bf16 v[66:69], v[164:167], v[196:199], v[66:69]
	v_mfma_f32_16x16x32_bf16 v[70:73], v[152:155], v[192:195], v[70:73]
	v_mfma_f32_16x16x32_bf16 v[70:73], v[156:159], v[196:199], v[70:73]
	v_mfma_f32_16x16x32_bf16 v[82:85], v[142:145], v[192:195], v[82:85]
	v_mfma_f32_16x16x32_bf16 v[82:85], v[148:151], v[196:199], v[82:85]
	v_mfma_f32_16x16x32_bf16 v[90:93], v[134:137], v[192:195], v[90:93]
	v_mfma_f32_16x16x32_bf16 v[90:93], v[138:141], v[196:199], v[90:93]
	s_setprio 0
	s_barrier
	s_mov_b32 m0, s54
	s_or_b32 s83, s82, 0x80
	ds_read_b128 v[168:171], v212 offset:49152
	ds_read_b128 v[172:175], v212 offset:50176
	ds_read_b128 v[176:179], v212 offset:51200
	ds_read_b128 v[180:183], v212 offset:52224
	ds_read_b128 v[184:187], v212 offset:53248
	ds_read_b128 v[188:191], v212 offset:54272
	ds_read_b128 v[192:195], v212 offset:55296
	ds_read_b128 v[196:199], v212 offset:56320
	buffer_load_dwordx4 v209, s[16:19], s83 offen lds
	s_add_i32 s83, s82, 0x158080
	s_mov_b32 m0, s55
	s_add_i32 s80, s80, 0x158080
	buffer_load_dwordx4 v209, s[16:19], s83 offen lds
	s_add_i32 s83, s82, 0x2b0080
	s_mov_b32 m0, s58
	s_add_i32 s82, s82, 0x408080
	buffer_load_dwordx4 v209, s[16:19], s83 offen lds
	s_mov_b32 m0, s59
	s_nop 0
	buffer_load_dwordx4 v209, s[16:19], s82 offen lds
	s_mov_b32 m0, s56
	s_nop 0
	buffer_load_dwordx4 v208, s[12:15], s81 offen lds
	s_mov_b32 m0, s57
	s_nop 0
	buffer_load_dwordx4 v208, s[12:15], s80 offen lds
	s_waitcnt vmcnt(8)
	s_waitcnt lgkmcnt(0)
	s_setprio 1
	v_mfma_f32_16x16x32_bf16 v[62:65], v[134:137], v[168:171], v[62:65]
	v_mfma_f32_16x16x32_bf16 v[62:65], v[138:141], v[172:175], v[62:65]
	s_barrier
	v_mfma_f32_16x16x32_bf16 v[58:61], v[142:145], v[168:171], v[58:61]
	v_mfma_f32_16x16x32_bf16 v[58:61], v[148:151], v[172:175], v[58:61]
	v_mfma_f32_16x16x32_bf16 v[46:49], v[152:155], v[168:171], v[46:49]
	v_mfma_f32_16x16x32_bf16 v[46:49], v[156:159], v[172:175], v[46:49]
	v_mfma_f32_16x16x32_bf16 v[38:41], v[160:163], v[168:171], v[38:41]
	v_mfma_f32_16x16x32_bf16 v[38:41], v[164:167], v[172:175], v[38:41]
	v_mfma_f32_16x16x32_bf16 v[22:25], v[160:163], v[176:179], v[22:25]
	v_mfma_f32_16x16x32_bf16 v[22:25], v[164:167], v[180:183], v[22:25]
	v_mfma_f32_16x16x32_bf16 v[30:33], v[152:155], v[176:179], v[30:33]
	v_mfma_f32_16x16x32_bf16 v[30:33], v[156:159], v[180:183], v[30:33]
	v_mfma_f32_16x16x32_bf16 v[50:53], v[142:145], v[176:179], v[50:53]
	v_mfma_f32_16x16x32_bf16 v[50:53], v[148:151], v[180:183], v[50:53]
	v_mfma_f32_16x16x32_bf16 v[54:57], v[134:137], v[176:179], v[54:57]
	v_mfma_f32_16x16x32_bf16 v[54:57], v[138:141], v[180:183], v[54:57]
	v_mfma_f32_16x16x32_bf16 v[42:45], v[134:137], v[184:187], v[42:45]
	v_mfma_f32_16x16x32_bf16 v[42:45], v[138:141], v[188:191], v[42:45]
	v_mfma_f32_16x16x32_bf16 v[34:37], v[142:145], v[184:187], v[34:37]
	v_mfma_f32_16x16x32_bf16 v[34:37], v[148:151], v[188:191], v[34:37]
	v_mfma_f32_16x16x32_bf16 v[14:17], v[152:155], v[184:187], v[14:17]
	v_mfma_f32_16x16x32_bf16 v[14:17], v[156:159], v[188:191], v[14:17]
	v_mfma_f32_16x16x32_bf16 v[10:13], v[160:163], v[184:187], v[10:13]
	v_mfma_f32_16x16x32_bf16 v[10:13], v[164:167], v[188:191], v[10:13]
	v_mfma_f32_16x16x32_bf16 v[2:5], v[160:163], v[192:195], v[2:5]
	v_mfma_f32_16x16x32_bf16 v[2:5], v[164:167], v[196:199], v[2:5]
	v_mfma_f32_16x16x32_bf16 v[6:9], v[152:155], v[192:195], v[6:9]
	v_mfma_f32_16x16x32_bf16 v[6:9], v[156:159], v[196:199], v[6:9]
	v_mfma_f32_16x16x32_bf16 v[18:21], v[142:145], v[192:195], v[18:21]
	v_mfma_f32_16x16x32_bf16 v[18:21], v[148:151], v[196:199], v[18:21]
	v_mfma_f32_16x16x32_bf16 v[26:29], v[134:137], v[192:195], v[26:29]
	v_mfma_f32_16x16x32_bf16 v[26:29], v[138:141], v[196:199], v[26:29]
	s_setprio 0
	s_barrier
	s_add_i32 s79, s79, 2
	s_addk_i32 s77, 0x100
	s_addk_i32 s78, 0x100
	s_cmp_ge_i32 s79, s3
	s_cbranch_scc0 .LBB0_799
	v_pk_mul_f32 v[184:185], v[128:129], 0.5 op_sel_hi:[1,0]
	v_pk_mul_f32 v[186:187], v[126:127], 0.5 op_sel_hi:[1,0]
	v_pk_mul_f32 v[188:189], v[124:125], 0.5 op_sel_hi:[1,0]
	v_pk_mul_f32 v[190:191], v[122:123], 0.5 op_sel_hi:[1,0]
	v_pk_mul_f32 v[198:199], v[112:113], 0.5 op_sel_hi:[1,0]
	v_pk_mul_f32 v[196:197], v[110:111], 0.5 op_sel_hi:[1,0]
	v_pk_mul_f32 v[194:195], v[104:105], 0.5 op_sel_hi:[1,0]
	v_pk_mul_f32 v[192:193], v[102:103], 0.5 op_sel_hi:[1,0]
	v_pk_mul_f32 v[182:183], v[120:121], 0.5 op_sel_hi:[1,0]
	v_pk_mul_f32 v[180:181], v[118:119], 0.5 op_sel_hi:[1,0]
	v_pk_mul_f32 v[178:179], v[116:117], 0.5 op_sel_hi:[1,0]
	v_pk_mul_f32 v[176:177], v[114:115], 0.5 op_sel_hi:[1,0]
	v_pk_mul_f32 v[172:173], v[96:97], 0.5 op_sel_hi:[1,0]
	v_pk_mul_f32 v[170:171], v[94:95], 0.5 op_sel_hi:[1,0]
	v_pk_mul_f32 v[168:169], v[88:89], 0.5 op_sel_hi:[1,0]
	v_pk_mul_f32 v[166:167], v[86:87], 0.5 op_sel_hi:[1,0]
	v_pk_mul_f32 v[164:165], v[108:109], 0.5 op_sel_hi:[1,0]
	v_pk_mul_f32 v[162:163], v[106:107], 0.5 op_sel_hi:[1,0]
	v_pk_mul_f32 v[160:161], v[100:101], 0.5 op_sel_hi:[1,0]
	v_pk_mul_f32 v[158:159], v[98:99], 0.5 op_sel_hi:[1,0]
	v_pk_mul_f32 v[156:157], v[80:81], 0.5 op_sel_hi:[1,0]
	v_pk_mul_f32 v[154:155], v[78:79], 0.5 op_sel_hi:[1,0]
	v_pk_mul_f32 v[152:153], v[76:77], 0.5 op_sel_hi:[1,0]
	v_pk_mul_f32 v[150:151], v[74:75], 0.5 op_sel_hi:[1,0]
	v_pk_mul_f32 v[144:145], v[92:93], 0.5 op_sel_hi:[1,0]
	v_pk_mul_f32 v[142:143], v[90:91], 0.5 op_sel_hi:[1,0]
	v_pk_mul_f32 v[140:141], v[84:85], 0.5 op_sel_hi:[1,0]
	v_pk_mul_f32 v[138:139], v[82:83], 0.5 op_sel_hi:[1,0]
	v_pk_mul_f32 v[136:137], v[72:73], 0.5 op_sel_hi:[1,0]
	v_pk_mul_f32 v[134:135], v[70:71], 0.5 op_sel_hi:[1,0]
	v_pk_mul_f32 v[128:129], v[68:69], 0.5 op_sel_hi:[1,0]
	v_pk_mul_f32 v[126:127], v[66:67], 0.5 op_sel_hi:[1,0]
	v_pk_mul_f32 v[122:123], v[64:65], 0.5 op_sel_hi:[1,0]
	v_pk_mul_f32 v[120:121], v[62:63], 0.5 op_sel_hi:[1,0]
	v_pk_mul_f32 v[118:119], v[60:61], 0.5 op_sel_hi:[1,0]
	v_pk_mul_f32 v[116:117], v[58:59], 0.5 op_sel_hi:[1,0]
	v_pk_mul_f32 v[112:113], v[48:49], 0.5 op_sel_hi:[1,0]
	v_pk_mul_f32 v[110:111], v[46:47], 0.5 op_sel_hi:[1,0]
	v_pk_mul_f32 v[108:109], v[40:41], 0.5 op_sel_hi:[1,0]
	v_pk_mul_f32 v[106:107], v[38:39], 0.5 op_sel_hi:[1,0]
	v_pk_mul_f32 v[104:105], v[56:57], 0.5 op_sel_hi:[1,0]
	v_pk_mul_f32 v[102:103], v[54:55], 0.5 op_sel_hi:[1,0]
	v_pk_mul_f32 v[100:101], v[52:53], 0.5 op_sel_hi:[1,0]
	v_pk_mul_f32 v[98:99], v[50:51], 0.5 op_sel_hi:[1,0]
	v_pk_mul_f32 v[96:97], v[32:33], 0.5 op_sel_hi:[1,0]
	v_pk_mul_f32 v[94:95], v[30:31], 0.5 op_sel_hi:[1,0]
	v_pk_mul_f32 v[92:93], v[24:25], 0.5 op_sel_hi:[1,0]
	v_pk_mul_f32 v[90:91], v[22:23], 0.5 op_sel_hi:[1,0]
	v_pk_mul_f32 v[88:89], v[44:45], 0.5 op_sel_hi:[1,0]
	v_pk_mul_f32 v[86:87], v[42:43], 0.5 op_sel_hi:[1,0]
	v_pk_mul_f32 v[84:85], v[36:37], 0.5 op_sel_hi:[1,0]
	v_pk_mul_f32 v[82:83], v[34:35], 0.5 op_sel_hi:[1,0]
	v_pk_mul_f32 v[80:81], v[16:17], 0.5 op_sel_hi:[1,0]
	v_pk_mul_f32 v[78:79], v[14:15], 0.5 op_sel_hi:[1,0]
	v_pk_mul_f32 v[76:77], v[12:13], 0.5 op_sel_hi:[1,0]
	v_pk_mul_f32 v[74:75], v[10:11], 0.5 op_sel_hi:[1,0]
	v_pk_mul_f32 v[72:73], v[28:29], 0.5 op_sel_hi:[1,0]
	v_pk_mul_f32 v[70:71], v[26:27], 0.5 op_sel_hi:[1,0]
	v_pk_mul_f32 v[68:69], v[20:21], 0.5 op_sel_hi:[1,0]
	v_pk_mul_f32 v[66:67], v[18:19], 0.5 op_sel_hi:[1,0]
	v_pk_mul_f32 v[64:65], v[8:9], 0.5 op_sel_hi:[1,0]
	v_pk_mul_f32 v[62:63], v[6:7], 0.5 op_sel_hi:[1,0]
	v_pk_mul_f32 v[60:61], v[4:5], 0.5 op_sel_hi:[1,0]
	v_pk_mul_f32 v[58:59], v[2:3], 0.5 op_sel_hi:[1,0]
	s_and_b64 vcc, exec, s[38:39]
	s_cbranch_vccz .LBB0_802

.LBB0_892:
	ds_read_b128 v[130:133], v172
	ds_read_b128 v[134:137], v172 offset:1024
	ds_read_b128 v[148:151], v172 offset:2048
	ds_read_b128 v[152:155], v172 offset:3072
	ds_read_b128 v[156:159], v173
	ds_read_b128 v[160:163], v173 offset:1024
	ds_read_b128 v[164:167], v173 offset:2048
	ds_read_b128 v[180:183], v173 offset:3072
	s_add_i32 s18, s8, 0xffe80080
	s_cmp_eq_u32 s77, s52
	s_cselect_b32 s53, s6, s18
	s_cselect_b32 s58, s7, s9
	s_or_b32 s57, s53, 0x80
	s_add_i32 s18, s8, 0xfff80000
	s_mov_b32 m0, s78
	ds_read_b128 v[184:187], v174
	ds_read_b128 v[188:191], v174 offset:1024
	ds_read_b128 v[192:195], v174 offset:2048
	ds_read_b128 v[196:199], v174 offset:3072
	ds_read_b128 v[200:203], v174 offset:4096
	ds_read_b128 v[204:207], v174 offset:5120
	ds_read_b128 v[208:211], v174 offset:6144
	ds_read_b128 v[212:215], v174 offset:7168
	buffer_load_dwordx4 v170, s[12:15], s18 offen lds
	s_mov_b32 m0, s79
	s_nop 0
	buffer_load_dwordx4 v170, s[12:15], s8 offen lds
	s_waitcnt vmcnt(8)
	s_waitcnt lgkmcnt(0)
	s_setprio 1
	v_mfma_f32_16x16x32_bf16 v[126:129], v[130:133], v[184:187], v[126:129]
	v_mfma_f32_16x16x32_bf16 v[126:129], v[134:137], v[188:191], v[126:129]
	s_barrier
	v_mfma_f32_16x16x32_bf16 v[118:121], v[148:151], v[184:187], v[118:121]
	v_mfma_f32_16x16x32_bf16 v[118:121], v[152:155], v[188:191], v[118:121]
	v_mfma_f32_16x16x32_bf16 v[122:125], v[156:159], v[184:187], v[122:125]
	v_mfma_f32_16x16x32_bf16 v[122:125], v[160:163], v[188:191], v[122:125]
	v_mfma_f32_16x16x32_bf16 v[114:117], v[164:167], v[184:187], v[114:117]
	v_mfma_f32_16x16x32_bf16 v[114:117], v[180:183], v[188:191], v[114:117]
	v_mfma_f32_16x16x32_bf16 v[98:101], v[164:167], v[192:195], v[98:101]
	v_mfma_f32_16x16x32_bf16 v[98:101], v[180:183], v[196:199], v[98:101]
	v_mfma_f32_16x16x32_bf16 v[106:109], v[156:159], v[192:195], v[106:109]
	v_mfma_f32_16x16x32_bf16 v[106:109], v[160:163], v[196:199], v[106:109]
	v_mfma_f32_16x16x32_bf16 v[102:105], v[148:151], v[192:195], v[102:105]
	v_mfma_f32_16x16x32_bf16 v[102:105], v[152:155], v[196:199], v[102:105]
	v_mfma_f32_16x16x32_bf16 v[110:113], v[130:133], v[192:195], v[110:113]
	v_mfma_f32_16x16x32_bf16 v[110:113], v[134:137], v[196:199], v[110:113]
	v_mfma_f32_16x16x32_bf16 v[94:97], v[130:133], v[200:203], v[94:97]
	v_mfma_f32_16x16x32_bf16 v[94:97], v[134:137], v[204:207], v[94:97]
	v_mfma_f32_16x16x32_bf16 v[90:93], v[148:151], v[200:203], v[90:93]
	v_mfma_f32_16x16x32_bf16 v[90:93], v[152:155], v[204:207], v[90:93]
	v_mfma_f32_16x16x32_bf16 v[86:89], v[156:159], v[200:203], v[86:89]
	v_mfma_f32_16x16x32_bf16 v[86:89], v[160:163], v[204:207], v[86:89]
	v_mfma_f32_16x16x32_bf16 v[82:85], v[164:167], v[200:203], v[82:85]
	v_mfma_f32_16x16x32_bf16 v[82:85], v[180:183], v[204:207], v[82:85]
	v_mfma_f32_16x16x32_bf16 v[66:69], v[164:167], v[208:211], v[66:69]
	v_mfma_f32_16x16x32_bf16 v[66:69], v[180:183], v[212:215], v[66:69]
	v_mfma_f32_16x16x32_bf16 v[74:77], v[156:159], v[208:211], v[74:77]
	v_mfma_f32_16x16x32_bf16 v[74:77], v[160:163], v[212:215], v[74:77]
	v_mfma_f32_16x16x32_bf16 v[70:73], v[148:151], v[208:211], v[70:73]
	v_mfma_f32_16x16x32_bf16 v[70:73], v[152:155], v[212:215], v[70:73]
	v_mfma_f32_16x16x32_bf16 v[78:81], v[130:133], v[208:211], v[78:81]
	v_mfma_f32_16x16x32_bf16 v[78:81], v[134:137], v[212:215], v[78:81]
	s_setprio 0
	s_barrier
	s_mov_b32 m0, s27
	s_mov_b32 s18, s14
	s_mov_b32 s19, s15
	ds_read_b128 v[184:187], v174 offset:16384
	ds_read_b128 v[188:191], v174 offset:17408
	ds_read_b128 v[192:195], v174 offset:18432
	ds_read_b128 v[196:199], v174 offset:19456
	ds_read_b128 v[200:203], v174 offset:20480
	ds_read_b128 v[204:207], v174 offset:21504
	ds_read_b128 v[208:211], v174 offset:22528
	ds_read_b128 v[212:215], v174 offset:23552
	buffer_load_dwordx4 v171, s[16:19], s58 offen lds
	s_add_i32 s59, s58, 0x80000
	s_mov_b32 m0, s60
	s_nop 0
	buffer_load_dwordx4 v171, s[16:19], s59 offen lds
	s_add_i32 s59, s58, 0x100000
	s_mov_b32 m0, s61
	s_nop 0
	buffer_load_dwordx4 v171, s[16:19], s59 offen lds
	s_add_i32 s59, s58, 0x180000
	s_mov_b32 m0, s62
	s_nop 0
	buffer_load_dwordx4 v171, s[16:19], s59 offen lds
	s_mov_b32 m0, s25
	s_add_i32 s59, s53, 0x80000
	buffer_load_dwordx4 v170, s[12:15], s53 offen lds
	s_mov_b32 m0, s63
	s_nop 0
	buffer_load_dwordx4 v170, s[12:15], s59 offen lds
	s_waitcnt vmcnt(8)
	s_waitcnt lgkmcnt(0)
	s_setprio 1
	v_mfma_f32_16x16x32_bf16 v[62:65], v[130:133], v[184:187], v[62:65]
	v_mfma_f32_16x16x32_bf16 v[62:65], v[134:137], v[188:191], v[62:65]
	s_barrier
	v_mfma_f32_16x16x32_bf16 v[54:57], v[148:151], v[184:187], v[54:57]
	v_mfma_f32_16x16x32_bf16 v[54:57], v[152:155], v[188:191], v[54:57]
	v_mfma_f32_16x16x32_bf16 v[58:61], v[156:159], v[184:187], v[58:61]
	v_mfma_f32_16x16x32_bf16 v[58:61], v[160:163], v[188:191], v[58:61]
	v_mfma_f32_16x16x32_bf16 v[50:53], v[164:167], v[184:187], v[50:53]
	v_mfma_f32_16x16x32_bf16 v[50:53], v[180:183], v[188:191], v[50:53]
	v_mfma_f32_16x16x32_bf16 v[34:37], v[164:167], v[192:195], v[34:37]
	v_mfma_f32_16x16x32_bf16 v[34:37], v[180:183], v[196:199], v[34:37]
	v_mfma_f32_16x16x32_bf16 v[42:45], v[156:159], v[192:195], v[42:45]
	v_mfma_f32_16x16x32_bf16 v[42:45], v[160:163], v[196:199], v[42:45]
	v_mfma_f32_16x16x32_bf16 v[38:41], v[148:151], v[192:195], v[38:41]
	v_mfma_f32_16x16x32_bf16 v[38:41], v[152:155], v[196:199], v[38:41]
	v_mfma_f32_16x16x32_bf16 v[46:49], v[130:133], v[192:195], v[46:49]
	v_mfma_f32_16x16x32_bf16 v[46:49], v[134:137], v[196:199], v[46:49]
	v_mfma_f32_16x16x32_bf16 v[30:33], v[130:133], v[200:203], v[30:33]
	v_mfma_f32_16x16x32_bf16 v[30:33], v[134:137], v[204:207], v[30:33]
	v_mfma_f32_16x16x32_bf16 v[22:25], v[148:151], v[200:203], v[22:25]
	v_mfma_f32_16x16x32_bf16 v[22:25], v[152:155], v[204:207], v[22:25]
	v_mfma_f32_16x16x32_bf16 v[26:29], v[156:159], v[200:203], v[26:29]
	v_mfma_f32_16x16x32_bf16 v[26:29], v[160:163], v[204:207], v[26:29]
	v_mfma_f32_16x16x32_bf16 v[18:21], v[164:167], v[200:203], v[18:21]
	v_mfma_f32_16x16x32_bf16 v[18:21], v[180:183], v[204:207], v[18:21]
	v_mfma_f32_16x16x32_bf16 v[2:5], v[164:167], v[208:211], v[2:5]
	v_mfma_f32_16x16x32_bf16 v[2:5], v[180:183], v[212:215], v[2:5]
	v_mfma_f32_16x16x32_bf16 v[10:13], v[156:159], v[208:211], v[10:13]
	v_mfma_f32_16x16x32_bf16 v[10:13], v[160:163], v[212:215], v[10:13]
	v_mfma_f32_16x16x32_bf16 v[6:9], v[148:151], v[208:211], v[6:9]
	v_mfma_f32_16x16x32_bf16 v[6:9], v[152:155], v[212:215], v[6:9]
	v_mfma_f32_16x16x32_bf16 v[14:17], v[130:133], v[208:211], v[14:17]
	v_mfma_f32_16x16x32_bf16 v[14:17], v[134:137], v[212:215], v[14:17]
	s_setprio 0
	s_barrier
	ds_read_b128 v[130:133], v175
	ds_read_b128 v[134:137], v175 offset:1024
	ds_read_b128 v[148:151], v175 offset:2048
	ds_read_b128 v[152:155], v175 offset:3072
	ds_read_b128 v[156:159], v176
	ds_read_b128 v[160:163], v176 offset:1024
	ds_read_b128 v[164:167], v176 offset:2048
	ds_read_b128 v[180:183], v176 offset:3072
	s_mov_b32 m0, s64
	s_add_i32 s59, s53, 0x100000
	ds_read_b128 v[184:187], v174 offset:32768
	ds_read_b128 v[188:191], v174 offset:33792
	ds_read_b128 v[192:195], v174 offset:34816
	ds_read_b128 v[196:199], v174 offset:35840
	ds_read_b128 v[200:203], v174 offset:36864
	ds_read_b128 v[204:207], v174 offset:37888
	ds_read_b128 v[208:211], v174 offset:38912
	ds_read_b128 v[212:215], v174 offset:39936
	buffer_load_dwordx4 v170, s[12:15], s59 offen lds
	s_add_i32 s59, s53, 0x180000
	s_mov_b32 m0, s65
	s_nop 0
	buffer_load_dwordx4 v170, s[12:15], s59 offen lds
	s_waitcnt vmcnt(8)
	s_waitcnt lgkmcnt(0)
	s_setprio 1
	v_mfma_f32_16x16x32_bf16 v[126:129], v[130:133], v[184:187], v[126:129]
	v_mfma_f32_16x16x32_bf16 v[126:129], v[134:137], v[188:191], v[126:129]
	s_barrier
	v_mfma_f32_16x16x32_bf16 v[118:121], v[148:151], v[184:187], v[118:121]
	v_mfma_f32_16x16x32_bf16 v[118:121], v[152:155], v[188:191], v[118:121]
	v_mfma_f32_16x16x32_bf16 v[122:125], v[156:159], v[184:187], v[122:125]
	v_mfma_f32_16x16x32_bf16 v[122:125], v[160:163], v[188:191], v[122:125]
	v_mfma_f32_16x16x32_bf16 v[114:117], v[164:167], v[184:187], v[114:117]
	v_mfma_f32_16x16x32_bf16 v[114:117], v[180:183], v[188:191], v[114:117]
	v_mfma_f32_16x16x32_bf16 v[98:101], v[164:167], v[192:195], v[98:101]
	v_mfma_f32_16x16x32_bf16 v[98:101], v[180:183], v[196:199], v[98:101]
	v_mfma_f32_16x16x32_bf16 v[106:109], v[156:159], v[192:195], v[106:109]
	v_mfma_f32_16x16x32_bf16 v[106:109], v[160:163], v[196:199], v[106:109]
	v_mfma_f32_16x16x32_bf16 v[102:105], v[148:151], v[192:195], v[102:105]
	v_mfma_f32_16x16x32_bf16 v[102:105], v[152:155], v[196:199], v[102:105]
	v_mfma_f32_16x16x32_bf16 v[110:113], v[130:133], v[192:195], v[110:113]
	v_mfma_f32_16x16x32_bf16 v[110:113], v[134:137], v[196:199], v[110:113]
	v_mfma_f32_16x16x32_bf16 v[94:97], v[130:133], v[200:203], v[94:97]
	v_mfma_f32_16x16x32_bf16 v[94:97], v[134:137], v[204:207], v[94:97]
	v_mfma_f32_16x16x32_bf16 v[90:93], v[148:151], v[200:203], v[90:93]
	v_mfma_f32_16x16x32_bf16 v[90:93], v[152:155], v[204:207], v[90:93]
	v_mfma_f32_16x16x32_bf16 v[86:89], v[156:159], v[200:203], v[86:89]
	v_mfma_f32_16x16x32_bf16 v[86:89], v[160:163], v[204:207], v[86:89]
	v_mfma_f32_16x16x32_bf16 v[82:85], v[164:167], v[200:203], v[82:85]
	v_mfma_f32_16x16x32_bf16 v[82:85], v[180:183], v[204:207], v[82:85]
	v_mfma_f32_16x16x32_bf16 v[66:69], v[164:167], v[208:211], v[66:69]
	v_mfma_f32_16x16x32_bf16 v[66:69], v[180:183], v[212:215], v[66:69]
	v_mfma_f32_16x16x32_bf16 v[74:77], v[156:159], v[208:211], v[74:77]
	v_mfma_f32_16x16x32_bf16 v[74:77], v[160:163], v[212:215], v[74:77]
	v_mfma_f32_16x16x32_bf16 v[70:73], v[148:151], v[208:211], v[70:73]
	v_mfma_f32_16x16x32_bf16 v[70:73], v[152:155], v[212:215], v[70:73]
	v_mfma_f32_16x16x32_bf16 v[78:81], v[130:133], v[208:211], v[78:81]
	v_mfma_f32_16x16x32_bf16 v[78:81], v[134:137], v[212:215], v[78:81]
	s_setprio 0
	s_barrier
	s_mov_b32 m0, s70
	s_or_b32 s59, s58, 0x80
	ds_read_b128 v[184:187], v174 offset:49152
	ds_read_b128 v[188:191], v174 offset:50176
	ds_read_b128 v[192:195], v174 offset:51200
	ds_read_b128 v[196:199], v174 offset:52224
	ds_read_b128 v[200:203], v174 offset:53248
	ds_read_b128 v[204:207], v174 offset:54272
	ds_read_b128 v[208:211], v174 offset:55296
	ds_read_b128 v[212:215], v174 offset:56320
	buffer_load_dwordx4 v171, s[16:19], s59 offen lds
	s_add_i32 s59, s58, 0x80080
	s_mov_b32 m0, s71
	s_add_i32 s53, s53, 0x80080
	buffer_load_dwordx4 v171, s[16:19], s59 offen lds
	s_add_i32 s59, s58, 0x100080
	s_mov_b32 m0, s74
	s_add_i32 s58, s58, 0x180080
	buffer_load_dwordx4 v171, s[16:19], s59 offen lds
	s_mov_b32 m0, s75
	s_nop 0
	buffer_load_dwordx4 v171, s[16:19], s58 offen lds
	s_mov_b32 m0, s72
	s_nop 0
	buffer_load_dwordx4 v170, s[12:15], s57 offen lds
	s_mov_b32 m0, s73
	s_nop 0
	buffer_load_dwordx4 v170, s[12:15], s53 offen lds
	s_waitcnt vmcnt(8)
	s_waitcnt lgkmcnt(0)
	s_setprio 1
	v_mfma_f32_16x16x32_bf16 v[62:65], v[130:133], v[184:187], v[62:65]
	v_mfma_f32_16x16x32_bf16 v[62:65], v[134:137], v[188:191], v[62:65]
	s_barrier
	v_mfma_f32_16x16x32_bf16 v[54:57], v[148:151], v[184:187], v[54:57]
	v_mfma_f32_16x16x32_bf16 v[54:57], v[152:155], v[188:191], v[54:57]
	v_mfma_f32_16x16x32_bf16 v[58:61], v[156:159], v[184:187], v[58:61]
	v_mfma_f32_16x16x32_bf16 v[58:61], v[160:163], v[188:191], v[58:61]
	v_mfma_f32_16x16x32_bf16 v[50:53], v[164:167], v[184:187], v[50:53]
	v_mfma_f32_16x16x32_bf16 v[50:53], v[180:183], v[188:191], v[50:53]
	v_mfma_f32_16x16x32_bf16 v[34:37], v[164:167], v[192:195], v[34:37]
	v_mfma_f32_16x16x32_bf16 v[34:37], v[180:183], v[196:199], v[34:37]
	v_mfma_f32_16x16x32_bf16 v[42:45], v[156:159], v[192:195], v[42:45]
	v_mfma_f32_16x16x32_bf16 v[42:45], v[160:163], v[196:199], v[42:45]
	v_mfma_f32_16x16x32_bf16 v[38:41], v[148:151], v[192:195], v[38:41]
	v_mfma_f32_16x16x32_bf16 v[38:41], v[152:155], v[196:199], v[38:41]
	v_mfma_f32_16x16x32_bf16 v[46:49], v[130:133], v[192:195], v[46:49]
	v_mfma_f32_16x16x32_bf16 v[46:49], v[134:137], v[196:199], v[46:49]
	v_mfma_f32_16x16x32_bf16 v[30:33], v[130:133], v[200:203], v[30:33]
	v_mfma_f32_16x16x32_bf16 v[30:33], v[134:137], v[204:207], v[30:33]
	v_mfma_f32_16x16x32_bf16 v[22:25], v[148:151], v[200:203], v[22:25]
	v_mfma_f32_16x16x32_bf16 v[22:25], v[152:155], v[204:207], v[22:25]
	v_mfma_f32_16x16x32_bf16 v[26:29], v[156:159], v[200:203], v[26:29]
	v_mfma_f32_16x16x32_bf16 v[26:29], v[160:163], v[204:207], v[26:29]
	v_mfma_f32_16x16x32_bf16 v[18:21], v[164:167], v[200:203], v[18:21]
	v_mfma_f32_16x16x32_bf16 v[18:21], v[180:183], v[204:207], v[18:21]
	v_mfma_f32_16x16x32_bf16 v[2:5], v[164:167], v[208:211], v[2:5]
	v_mfma_f32_16x16x32_bf16 v[2:5], v[180:183], v[212:215], v[2:5]
	v_mfma_f32_16x16x32_bf16 v[10:13], v[156:159], v[208:211], v[10:13]
	v_mfma_f32_16x16x32_bf16 v[10:13], v[160:163], v[212:215], v[10:13]
	v_mfma_f32_16x16x32_bf16 v[6:9], v[148:151], v[208:211], v[6:9]
	v_mfma_f32_16x16x32_bf16 v[6:9], v[152:155], v[212:215], v[6:9]
	v_mfma_f32_16x16x32_bf16 v[14:17], v[130:133], v[208:211], v[14:17]
	v_mfma_f32_16x16x32_bf16 v[14:17], v[134:137], v[212:215], v[14:17]
	s_setprio 0
	s_barrier
	s_add_i32 s52, s52, 2
	s_addk_i32 s8, 0x100
	s_addk_i32 s9, 0x100
	s_cmp_ge_i32 s52, s21
	s_cbranch_scc0 .LBB0_892
	s_and_b64 vcc, exec, s[48:49]
	s_cbranch_vccz .LBB0_895

.LBB0_1020:
	v_add_u32_e32 v142, 0x10000, v162
	v_add_u32_e32 v150, 0x14000, v162
	ds_read_b128 v[130:133], v142
	ds_read_b128 v[134:137], v142 offset:1024
	ds_read_b128 v[138:141], v142 offset:2048
	ds_read_b128 v[142:145], v142 offset:3072
	ds_read_b128 v[154:157], v150
	ds_read_b128 v[164:167], v150 offset:1024
	ds_read_b128 v[168:171], v150 offset:2048
	ds_read_b128 v[172:175], v150 offset:3072
	s_add_i32 s90, s6, 0x100
	s_add_i32 s7, s88, s6
	s_cmp_eq_u32 s81, s89
	s_cselect_b32 s91, 0, s90
	s_cselect_b32 s93, s87, s7
	s_add_i32 s91, s91, s70
	s_or_b32 s92, s91, 0x80
	s_add_i32 s6, s3, s6
	s_mov_b32 m0, s82
	s_add_i32 s7, s6, 0x20080
	ds_read_b128 v[176:179], v163
	ds_read_b128 v[180:183], v163 offset:1024
	ds_read_b128 v[184:187], v163 offset:2048
	ds_read_b128 v[188:191], v163 offset:3072
	ds_read_b128 v[192:195], v163 offset:4096
	ds_read_b128 v[196:199], v163 offset:5120
	ds_read_b128 v[200:203], v163 offset:6144
	ds_read_b128 v[204:207], v163 offset:7168
	buffer_load_dwordx4 v161, s[12:15], s7 offen lds
	s_add_i32 s6, s6, 0x30080
	s_mov_b32 m0, s83
	s_nop 0
	buffer_load_dwordx4 v161, s[12:15], s6 offen lds
	s_waitcnt vmcnt(8)
	s_waitcnt lgkmcnt(0)
	s_setprio 1
	v_mfma_f32_16x16x32_bf16 v[126:129], v[130:133], v[176:179], v[126:129]
	v_mfma_f32_16x16x32_bf16 v[126:129], v[134:137], v[180:183], v[126:129]
	s_barrier
	v_mfma_f32_16x16x32_bf16 v[122:125], v[138:141], v[176:179], v[122:125]
	v_mfma_f32_16x16x32_bf16 v[122:125], v[142:145], v[180:183], v[122:125]
	v_mfma_f32_16x16x32_bf16 v[118:121], v[154:157], v[176:179], v[118:121]
	v_mfma_f32_16x16x32_bf16 v[118:121], v[164:167], v[180:183], v[118:121]
	v_mfma_f32_16x16x32_bf16 v[114:117], v[168:171], v[176:179], v[114:117]
	v_mfma_f32_16x16x32_bf16 v[114:117], v[172:175], v[180:183], v[114:117]
	v_mfma_f32_16x16x32_bf16 v[98:101], v[168:171], v[184:187], v[98:101]
	v_mfma_f32_16x16x32_bf16 v[98:101], v[172:175], v[188:191], v[98:101]
	v_mfma_f32_16x16x32_bf16 v[102:105], v[154:157], v[184:187], v[102:105]
	v_mfma_f32_16x16x32_bf16 v[102:105], v[164:167], v[188:191], v[102:105]
	v_mfma_f32_16x16x32_bf16 v[106:109], v[138:141], v[184:187], v[106:109]
	v_mfma_f32_16x16x32_bf16 v[106:109], v[142:145], v[188:191], v[106:109]
	v_mfma_f32_16x16x32_bf16 v[110:113], v[130:133], v[184:187], v[110:113]
	v_mfma_f32_16x16x32_bf16 v[110:113], v[134:137], v[188:191], v[110:113]
	v_mfma_f32_16x16x32_bf16 v[94:97], v[130:133], v[192:195], v[94:97]
	v_mfma_f32_16x16x32_bf16 v[94:97], v[134:137], v[196:199], v[94:97]
	v_mfma_f32_16x16x32_bf16 v[90:93], v[138:141], v[192:195], v[90:93]
	v_mfma_f32_16x16x32_bf16 v[90:93], v[142:145], v[196:199], v[90:93]
	v_mfma_f32_16x16x32_bf16 v[86:89], v[154:157], v[192:195], v[86:89]
	v_mfma_f32_16x16x32_bf16 v[86:89], v[164:167], v[196:199], v[86:89]
	v_mfma_f32_16x16x32_bf16 v[82:85], v[168:171], v[192:195], v[82:85]
	v_mfma_f32_16x16x32_bf16 v[82:85], v[172:175], v[196:199], v[82:85]
	v_mfma_f32_16x16x32_bf16 v[66:69], v[168:171], v[200:203], v[66:69]
	v_mfma_f32_16x16x32_bf16 v[66:69], v[172:175], v[204:207], v[66:69]
	v_mfma_f32_16x16x32_bf16 v[70:73], v[154:157], v[200:203], v[70:73]
	v_mfma_f32_16x16x32_bf16 v[70:73], v[164:167], v[204:207], v[70:73]
	v_mfma_f32_16x16x32_bf16 v[74:77], v[138:141], v[200:203], v[74:77]
	v_mfma_f32_16x16x32_bf16 v[74:77], v[142:145], v[204:207], v[74:77]
	v_mfma_f32_16x16x32_bf16 v[78:81], v[130:133], v[200:203], v[78:81]
	v_mfma_f32_16x16x32_bf16 v[78:81], v[134:137], v[204:207], v[78:81]
	s_setprio 0
	s_barrier
	s_mov_b32 m0, s66
	s_mov_b32 s6, s14
	s_mov_b32 s7, s15
	ds_read_b128 v[176:179], v163 offset:16384
	ds_read_b128 v[180:183], v163 offset:17408
	ds_read_b128 v[184:187], v163 offset:18432
	ds_read_b128 v[188:191], v163 offset:19456
	ds_read_b128 v[192:195], v163 offset:20480
	ds_read_b128 v[196:199], v163 offset:21504
	ds_read_b128 v[200:203], v163 offset:22528
	ds_read_b128 v[204:207], v163 offset:23552
	buffer_load_dwordx4 v160, s[4:7], s93 offen lds
	s_add_i32 s94, s93, 0x10000
	s_mov_b32 m0, s67
	s_nop 0
	buffer_load_dwordx4 v160, s[4:7], s94 offen lds
	s_add_i32 s94, s93, 0x20000
	s_mov_b32 m0, s68
	s_nop 0
	buffer_load_dwordx4 v160, s[4:7], s94 offen lds
	s_add_i32 s94, s93, 0x30000
	s_mov_b32 m0, s69
	s_nop 0
	buffer_load_dwordx4 v160, s[4:7], s94 offen lds
	s_mov_b32 m0, s65
	s_add_i32 s94, s91, 0x10000
	buffer_load_dwordx4 v161, s[12:15], s91 offen lds
	s_mov_b32 m0, s71
	s_nop 0
	buffer_load_dwordx4 v161, s[12:15], s94 offen lds
	s_waitcnt vmcnt(8)
	s_waitcnt lgkmcnt(0)
	s_setprio 1
	v_mfma_f32_16x16x32_bf16 v[62:65], v[130:133], v[176:179], v[62:65]
	v_mfma_f32_16x16x32_bf16 v[62:65], v[134:137], v[180:183], v[62:65]
	s_barrier
	v_mfma_f32_16x16x32_bf16 v[58:61], v[138:141], v[176:179], v[58:61]
	v_mfma_f32_16x16x32_bf16 v[58:61], v[142:145], v[180:183], v[58:61]
	v_mfma_f32_16x16x32_bf16 v[54:57], v[154:157], v[176:179], v[54:57]
	v_mfma_f32_16x16x32_bf16 v[54:57], v[164:167], v[180:183], v[54:57]
	v_mfma_f32_16x16x32_bf16 v[50:53], v[168:171], v[176:179], v[50:53]
	v_mfma_f32_16x16x32_bf16 v[50:53], v[172:175], v[180:183], v[50:53]
	v_mfma_f32_16x16x32_bf16 v[34:37], v[168:171], v[184:187], v[34:37]
	v_mfma_f32_16x16x32_bf16 v[34:37], v[172:175], v[188:191], v[34:37]
	v_mfma_f32_16x16x32_bf16 v[38:41], v[154:157], v[184:187], v[38:41]
	v_mfma_f32_16x16x32_bf16 v[38:41], v[164:167], v[188:191], v[38:41]
	v_mfma_f32_16x16x32_bf16 v[42:45], v[138:141], v[184:187], v[42:45]
	v_mfma_f32_16x16x32_bf16 v[42:45], v[142:145], v[188:191], v[42:45]
	v_mfma_f32_16x16x32_bf16 v[46:49], v[130:133], v[184:187], v[46:49]
	v_mfma_f32_16x16x32_bf16 v[46:49], v[134:137], v[188:191], v[46:49]
	v_mfma_f32_16x16x32_bf16 v[30:33], v[130:133], v[192:195], v[30:33]
	v_mfma_f32_16x16x32_bf16 v[30:33], v[134:137], v[196:199], v[30:33]
	v_mfma_f32_16x16x32_bf16 v[26:29], v[138:141], v[192:195], v[26:29]
	v_mfma_f32_16x16x32_bf16 v[26:29], v[142:145], v[196:199], v[26:29]
	v_mfma_f32_16x16x32_bf16 v[22:25], v[154:157], v[192:195], v[22:25]
	v_mfma_f32_16x16x32_bf16 v[22:25], v[164:167], v[196:199], v[22:25]
	v_mfma_f32_16x16x32_bf16 v[18:21], v[168:171], v[192:195], v[18:21]
	v_mfma_f32_16x16x32_bf16 v[18:21], v[172:175], v[196:199], v[18:21]
	v_mfma_f32_16x16x32_bf16 v[2:5], v[168:171], v[200:203], v[2:5]
	v_mfma_f32_16x16x32_bf16 v[2:5], v[172:175], v[204:207], v[2:5]
	v_mfma_f32_16x16x32_bf16 v[6:9], v[154:157], v[200:203], v[6:9]
	v_mfma_f32_16x16x32_bf16 v[6:9], v[164:167], v[204:207], v[6:9]
	v_mfma_f32_16x16x32_bf16 v[10:13], v[138:141], v[200:203], v[10:13]
	v_mfma_f32_16x16x32_bf16 v[10:13], v[142:145], v[204:207], v[10:13]
	v_mfma_f32_16x16x32_bf16 v[14:17], v[130:133], v[200:203], v[14:17]
	v_mfma_f32_16x16x32_bf16 v[14:17], v[134:137], v[204:207], v[14:17]
	s_setprio 0
	s_barrier
	v_add_u32_e32 v142, 0x18000, v162
	v_add_u32_e32 v150, 0x1c000, v162
	ds_read_b128 v[130:133], v142
	ds_read_b128 v[134:137], v142 offset:1024
	ds_read_b128 v[138:141], v142 offset:2048
	ds_read_b128 v[142:145], v142 offset:3072
	ds_read_b128 v[154:157], v150
	ds_read_b128 v[164:167], v150 offset:1024
	ds_read_b128 v[168:171], v150 offset:2048
	ds_read_b128 v[172:175], v150 offset:3072
	s_mov_b32 m0, s72
	s_add_i32 s94, s91, 0x20000
	ds_read_b128 v[176:179], v163 offset:32768
	ds_read_b128 v[180:183], v163 offset:33792
	ds_read_b128 v[184:187], v163 offset:34816
	ds_read_b128 v[188:191], v163 offset:35840
	ds_read_b128 v[192:195], v163 offset:36864
	ds_read_b128 v[196:199], v163 offset:37888
	ds_read_b128 v[200:203], v163 offset:38912
	ds_read_b128 v[204:207], v163 offset:39936
	buffer_load_dwordx4 v161, s[12:15], s94 offen lds
	s_add_i32 s94, s91, 0x30000
	s_mov_b32 m0, s73
	s_nop 0
	buffer_load_dwordx4 v161, s[12:15], s94 offen lds
	s_waitcnt vmcnt(8)
	s_waitcnt lgkmcnt(0)
	s_setprio 1
	v_mfma_f32_16x16x32_bf16 v[126:129], v[130:133], v[176:179], v[126:129]
	v_mfma_f32_16x16x32_bf16 v[126:129], v[134:137], v[180:183], v[126:129]
	s_barrier
	v_mfma_f32_16x16x32_bf16 v[122:125], v[138:141], v[176:179], v[122:125]
	v_mfma_f32_16x16x32_bf16 v[122:125], v[142:145], v[180:183], v[122:125]
	v_mfma_f32_16x16x32_bf16 v[118:121], v[154:157], v[176:179], v[118:121]
	v_mfma_f32_16x16x32_bf16 v[118:121], v[164:167], v[180:183], v[118:121]
	v_mfma_f32_16x16x32_bf16 v[114:117], v[168:171], v[176:179], v[114:117]
	v_mfma_f32_16x16x32_bf16 v[114:117], v[172:175], v[180:183], v[114:117]
	v_mfma_f32_16x16x32_bf16 v[98:101], v[168:171], v[184:187], v[98:101]
	v_mfma_f32_16x16x32_bf16 v[98:101], v[172:175], v[188:191], v[98:101]
	v_mfma_f32_16x16x32_bf16 v[102:105], v[154:157], v[184:187], v[102:105]
	v_mfma_f32_16x16x32_bf16 v[102:105], v[164:167], v[188:191], v[102:105]
	v_mfma_f32_16x16x32_bf16 v[106:109], v[138:141], v[184:187], v[106:109]
	v_mfma_f32_16x16x32_bf16 v[106:109], v[142:145], v[188:191], v[106:109]
	v_mfma_f32_16x16x32_bf16 v[110:113], v[130:133], v[184:187], v[110:113]
	v_mfma_f32_16x16x32_bf16 v[110:113], v[134:137], v[188:191], v[110:113]
	v_mfma_f32_16x16x32_bf16 v[94:97], v[130:133], v[192:195], v[94:97]
	v_mfma_f32_16x16x32_bf16 v[94:97], v[134:137], v[196:199], v[94:97]
	v_mfma_f32_16x16x32_bf16 v[90:93], v[138:141], v[192:195], v[90:93]
	v_mfma_f32_16x16x32_bf16 v[90:93], v[142:145], v[196:199], v[90:93]
	v_mfma_f32_16x16x32_bf16 v[86:89], v[154:157], v[192:195], v[86:89]
	v_mfma_f32_16x16x32_bf16 v[86:89], v[164:167], v[196:199], v[86:89]
	v_mfma_f32_16x16x32_bf16 v[82:85], v[168:171], v[192:195], v[82:85]
	v_mfma_f32_16x16x32_bf16 v[82:85], v[172:175], v[196:199], v[82:85]
	v_mfma_f32_16x16x32_bf16 v[66:69], v[168:171], v[200:203], v[66:69]
	v_mfma_f32_16x16x32_bf16 v[66:69], v[172:175], v[204:207], v[66:69]
	v_mfma_f32_16x16x32_bf16 v[70:73], v[154:157], v[200:203], v[70:73]
	v_mfma_f32_16x16x32_bf16 v[70:73], v[164:167], v[204:207], v[70:73]
	v_mfma_f32_16x16x32_bf16 v[74:77], v[138:141], v[200:203], v[74:77]
	v_mfma_f32_16x16x32_bf16 v[74:77], v[142:145], v[204:207], v[74:77]
	v_mfma_f32_16x16x32_bf16 v[78:81], v[130:133], v[200:203], v[78:81]
	v_mfma_f32_16x16x32_bf16 v[78:81], v[134:137], v[204:207], v[78:81]
	s_setprio 0
	s_barrier
	s_mov_b32 m0, s74
	s_or_b32 s94, s93, 0x80
	ds_read_b128 v[176:179], v163 offset:49152
	ds_read_b128 v[180:183], v163 offset:50176
	ds_read_b128 v[184:187], v163 offset:51200
	ds_read_b128 v[188:191], v163 offset:52224
	ds_read_b128 v[192:195], v163 offset:53248
	ds_read_b128 v[196:199], v163 offset:54272
	ds_read_b128 v[200:203], v163 offset:55296
	ds_read_b128 v[204:207], v163 offset:56320
	buffer_load_dwordx4 v160, s[4:7], s94 offen lds
	s_add_i32 s94, s93, 0x10080
	s_mov_b32 m0, s75
	s_add_i32 s91, s91, 0x10080
	buffer_load_dwordx4 v160, s[4:7], s94 offen lds
	s_add_i32 s94, s93, 0x20080
	s_mov_b32 m0, s78
	s_add_i32 s93, s93, 0x30080
	buffer_load_dwordx4 v160, s[4:7], s94 offen lds
	s_mov_b32 m0, s79
	s_nop 0
	buffer_load_dwordx4 v160, s[4:7], s93 offen lds
	s_mov_b32 m0, s76
	s_nop 0
	buffer_load_dwordx4 v161, s[12:15], s92 offen lds
	s_mov_b32 m0, s77
	s_nop 0
	buffer_load_dwordx4 v161, s[12:15], s91 offen lds
	s_waitcnt vmcnt(8)
	s_waitcnt lgkmcnt(0)
	s_setprio 1
	v_mfma_f32_16x16x32_bf16 v[62:65], v[130:133], v[176:179], v[62:65]
	v_mfma_f32_16x16x32_bf16 v[62:65], v[134:137], v[180:183], v[62:65]
	s_barrier
	v_mfma_f32_16x16x32_bf16 v[58:61], v[138:141], v[176:179], v[58:61]
	v_mfma_f32_16x16x32_bf16 v[58:61], v[142:145], v[180:183], v[58:61]
	v_mfma_f32_16x16x32_bf16 v[54:57], v[154:157], v[176:179], v[54:57]
	v_mfma_f32_16x16x32_bf16 v[54:57], v[164:167], v[180:183], v[54:57]
	v_mfma_f32_16x16x32_bf16 v[50:53], v[168:171], v[176:179], v[50:53]
	v_mfma_f32_16x16x32_bf16 v[50:53], v[172:175], v[180:183], v[50:53]
	v_mfma_f32_16x16x32_bf16 v[34:37], v[168:171], v[184:187], v[34:37]
	v_mfma_f32_16x16x32_bf16 v[34:37], v[172:175], v[188:191], v[34:37]
	v_mfma_f32_16x16x32_bf16 v[38:41], v[154:157], v[184:187], v[38:41]
	v_mfma_f32_16x16x32_bf16 v[38:41], v[164:167], v[188:191], v[38:41]
	v_mfma_f32_16x16x32_bf16 v[42:45], v[138:141], v[184:187], v[42:45]
	v_mfma_f32_16x16x32_bf16 v[42:45], v[142:145], v[188:191], v[42:45]
	v_mfma_f32_16x16x32_bf16 v[46:49], v[130:133], v[184:187], v[46:49]
	v_mfma_f32_16x16x32_bf16 v[46:49], v[134:137], v[188:191], v[46:49]
	v_mfma_f32_16x16x32_bf16 v[30:33], v[130:133], v[192:195], v[30:33]
	v_mfma_f32_16x16x32_bf16 v[30:33], v[134:137], v[196:199], v[30:33]
	v_mfma_f32_16x16x32_bf16 v[26:29], v[138:141], v[192:195], v[26:29]
	v_mfma_f32_16x16x32_bf16 v[26:29], v[142:145], v[196:199], v[26:29]
	v_mfma_f32_16x16x32_bf16 v[22:25], v[154:157], v[192:195], v[22:25]
	v_mfma_f32_16x16x32_bf16 v[22:25], v[164:167], v[196:199], v[22:25]
	v_mfma_f32_16x16x32_bf16 v[18:21], v[168:171], v[192:195], v[18:21]
	v_mfma_f32_16x16x32_bf16 v[18:21], v[172:175], v[196:199], v[18:21]
	v_mfma_f32_16x16x32_bf16 v[2:5], v[168:171], v[200:203], v[2:5]
	v_mfma_f32_16x16x32_bf16 v[2:5], v[172:175], v[204:207], v[2:5]
	v_mfma_f32_16x16x32_bf16 v[6:9], v[154:157], v[200:203], v[6:9]
	v_mfma_f32_16x16x32_bf16 v[6:9], v[164:167], v[204:207], v[6:9]
	v_mfma_f32_16x16x32_bf16 v[10:13], v[138:141], v[200:203], v[10:13]
	v_mfma_f32_16x16x32_bf16 v[10:13], v[142:145], v[204:207], v[10:13]
	v_mfma_f32_16x16x32_bf16 v[14:17], v[130:133], v[200:203], v[14:17]
	v_mfma_f32_16x16x32_bf16 v[14:17], v[134:137], v[204:207], v[14:17]
	s_setprio 0
	s_barrier
	s_add_i32 s89, s89, 2
	s_cmp_ge_i32 s89, s63
	s_mov_b32 s6, s90
	s_cbranch_scc0 .LBB0_1020
	s_and_b64 vcc, exec, s[54:55]
	s_cbranch_vccz .LBB0_1023

.LBB0_1035:
	ds_read_b128 v[140:143], v134
	ds_read_b128 v[148:151], v134 offset:1024
	ds_read_b128 v[152:155], v134 offset:2048
	ds_read_b128 v[156:159], v134 offset:3072
	ds_read_b128 v[160:163], v135
	ds_read_b128 v[164:167], v135 offset:1024
	ds_read_b128 v[168:171], v135 offset:2048
	ds_read_b128 v[172:175], v135 offset:3072
	s_add_i32 s73, s70, 0xfffb8080
	s_cmp_eq_u32 s53, s72
	s_cselect_b32 s73, s68, s73
	s_cselect_b32 s75, s69, s71
	s_add_i32 s74, s73, 0x80
	s_add_i32 s76, s70, 0xfffe8000
	s_mov_b32 m0, s54
	ds_read_b128 v[176:179], v136
	ds_read_b128 v[180:183], v136 offset:1024
	ds_read_b128 v[184:187], v136 offset:2048
	ds_read_b128 v[188:191], v136 offset:3072
	ds_read_b128 v[192:195], v136 offset:4096
	ds_read_b128 v[196:199], v136 offset:5120
	ds_read_b128 v[200:203], v136 offset:6144
	ds_read_b128 v[204:207], v136 offset:7168
	buffer_load_dwordx4 v132, s[12:15], s76 offen lds
	s_mov_b32 m0, s55
	s_nop 0
	buffer_load_dwordx4 v132, s[12:15], s70 offen lds
	s_waitcnt vmcnt(8)
	s_waitcnt lgkmcnt(0)
	s_setprio 1
	v_mfma_f32_16x16x32_bf16 v[126:129], v[140:143], v[176:179], v[126:129]
	v_mfma_f32_16x16x32_bf16 v[126:129], v[148:151], v[180:183], v[126:129]
	s_barrier
	v_mfma_f32_16x16x32_bf16 v[122:125], v[152:155], v[176:179], v[122:125]
	v_mfma_f32_16x16x32_bf16 v[122:125], v[156:159], v[180:183], v[122:125]
	v_mfma_f32_16x16x32_bf16 v[118:121], v[160:163], v[176:179], v[118:121]
	v_mfma_f32_16x16x32_bf16 v[118:121], v[164:167], v[180:183], v[118:121]
	v_mfma_f32_16x16x32_bf16 v[114:117], v[168:171], v[176:179], v[114:117]
	v_mfma_f32_16x16x32_bf16 v[114:117], v[172:175], v[180:183], v[114:117]
	v_mfma_f32_16x16x32_bf16 v[98:101], v[168:171], v[184:187], v[98:101]
	v_mfma_f32_16x16x32_bf16 v[98:101], v[172:175], v[188:191], v[98:101]
	v_mfma_f32_16x16x32_bf16 v[102:105], v[160:163], v[184:187], v[102:105]
	v_mfma_f32_16x16x32_bf16 v[102:105], v[164:167], v[188:191], v[102:105]
	v_mfma_f32_16x16x32_bf16 v[106:109], v[152:155], v[184:187], v[106:109]
	v_mfma_f32_16x16x32_bf16 v[106:109], v[156:159], v[188:191], v[106:109]
	v_mfma_f32_16x16x32_bf16 v[110:113], v[140:143], v[184:187], v[110:113]
	v_mfma_f32_16x16x32_bf16 v[110:113], v[148:151], v[188:191], v[110:113]
	v_mfma_f32_16x16x32_bf16 v[94:97], v[140:143], v[192:195], v[94:97]
	v_mfma_f32_16x16x32_bf16 v[94:97], v[148:151], v[196:199], v[94:97]
	v_mfma_f32_16x16x32_bf16 v[90:93], v[152:155], v[192:195], v[90:93]
	v_mfma_f32_16x16x32_bf16 v[90:93], v[156:159], v[196:199], v[90:93]
	v_mfma_f32_16x16x32_bf16 v[86:89], v[160:163], v[192:195], v[86:89]
	v_mfma_f32_16x16x32_bf16 v[86:89], v[164:167], v[196:199], v[86:89]
	v_mfma_f32_16x16x32_bf16 v[82:85], v[168:171], v[192:195], v[82:85]
	v_mfma_f32_16x16x32_bf16 v[82:85], v[172:175], v[196:199], v[82:85]
	v_mfma_f32_16x16x32_bf16 v[66:69], v[168:171], v[200:203], v[66:69]
	v_mfma_f32_16x16x32_bf16 v[66:69], v[172:175], v[204:207], v[66:69]
	v_mfma_f32_16x16x32_bf16 v[70:73], v[160:163], v[200:203], v[70:73]
	v_mfma_f32_16x16x32_bf16 v[70:73], v[164:167], v[204:207], v[70:73]
	v_mfma_f32_16x16x32_bf16 v[74:77], v[152:155], v[200:203], v[74:77]
	v_mfma_f32_16x16x32_bf16 v[74:77], v[156:159], v[204:207], v[74:77]
	v_mfma_f32_16x16x32_bf16 v[78:81], v[140:143], v[200:203], v[78:81]
	v_mfma_f32_16x16x32_bf16 v[78:81], v[148:151], v[204:207], v[78:81]
	s_setprio 0
	s_barrier
	s_mov_b32 m0, s30
	ds_read_b128 v[176:179], v136 offset:16384
	ds_read_b128 v[180:183], v136 offset:17408
	ds_read_b128 v[184:187], v136 offset:18432
	ds_read_b128 v[188:191], v136 offset:19456
	ds_read_b128 v[192:195], v136 offset:20480
	ds_read_b128 v[196:199], v136 offset:21504
	ds_read_b128 v[200:203], v136 offset:22528
	ds_read_b128 v[204:207], v136 offset:23552
	buffer_load_dwordx4 v133, s[16:19], s75 offen lds
	s_add_i32 s76, s75, 0x200000
	s_mov_b32 m0, s31
	s_nop 0
	buffer_load_dwordx4 v133, s[16:19], s76 offen lds
	s_add_i32 s76, s75, 0x400000
	s_mov_b32 m0, s35
	s_nop 0
	buffer_load_dwordx4 v133, s[16:19], s76 offen lds
	s_add_i32 s76, s75, 0x600000
	s_mov_b32 m0, s42
	s_nop 0
	buffer_load_dwordx4 v133, s[16:19], s76 offen lds
	s_mov_b32 m0, s27
	s_add_i32 s76, s73, 0x18000
	buffer_load_dwordx4 v132, s[12:15], s73 offen lds
	s_mov_b32 m0, s43
	s_nop 0
	buffer_load_dwordx4 v132, s[12:15], s76 offen lds
	s_waitcnt vmcnt(8)
	s_waitcnt lgkmcnt(0)
	s_setprio 1
	v_mfma_f32_16x16x32_bf16 v[62:65], v[140:143], v[176:179], v[62:65]
	v_mfma_f32_16x16x32_bf16 v[62:65], v[148:151], v[180:183], v[62:65]
	s_barrier
	v_mfma_f32_16x16x32_bf16 v[58:61], v[152:155], v[176:179], v[58:61]
	v_mfma_f32_16x16x32_bf16 v[58:61], v[156:159], v[180:183], v[58:61]
	v_mfma_f32_16x16x32_bf16 v[54:57], v[160:163], v[176:179], v[54:57]
	v_mfma_f32_16x16x32_bf16 v[54:57], v[164:167], v[180:183], v[54:57]
	v_mfma_f32_16x16x32_bf16 v[50:53], v[168:171], v[176:179], v[50:53]
	v_mfma_f32_16x16x32_bf16 v[50:53], v[172:175], v[180:183], v[50:53]
	v_mfma_f32_16x16x32_bf16 v[34:37], v[168:171], v[184:187], v[34:37]
	v_mfma_f32_16x16x32_bf16 v[34:37], v[172:175], v[188:191], v[34:37]
	v_mfma_f32_16x16x32_bf16 v[38:41], v[160:163], v[184:187], v[38:41]
	v_mfma_f32_16x16x32_bf16 v[38:41], v[164:167], v[188:191], v[38:41]
	v_mfma_f32_16x16x32_bf16 v[42:45], v[152:155], v[184:187], v[42:45]
	v_mfma_f32_16x16x32_bf16 v[42:45], v[156:159], v[188:191], v[42:45]
	v_mfma_f32_16x16x32_bf16 v[46:49], v[140:143], v[184:187], v[46:49]
	v_mfma_f32_16x16x32_bf16 v[46:49], v[148:151], v[188:191], v[46:49]
	v_mfma_f32_16x16x32_bf16 v[30:33], v[140:143], v[192:195], v[30:33]
	v_mfma_f32_16x16x32_bf16 v[30:33], v[148:151], v[196:199], v[30:33]
	v_mfma_f32_16x16x32_bf16 v[26:29], v[152:155], v[192:195], v[26:29]
	v_mfma_f32_16x16x32_bf16 v[26:29], v[156:159], v[196:199], v[26:29]
	v_mfma_f32_16x16x32_bf16 v[22:25], v[160:163], v[192:195], v[22:25]
	v_mfma_f32_16x16x32_bf16 v[22:25], v[164:167], v[196:199], v[22:25]
	v_mfma_f32_16x16x32_bf16 v[18:21], v[168:171], v[192:195], v[18:21]
	v_mfma_f32_16x16x32_bf16 v[18:21], v[172:175], v[196:199], v[18:21]
	v_mfma_f32_16x16x32_bf16 v[2:5], v[168:171], v[200:203], v[2:5]
	v_mfma_f32_16x16x32_bf16 v[2:5], v[172:175], v[204:207], v[2:5]
	v_mfma_f32_16x16x32_bf16 v[6:9], v[160:163], v[200:203], v[6:9]
	v_mfma_f32_16x16x32_bf16 v[6:9], v[164:167], v[204:207], v[6:9]
	v_mfma_f32_16x16x32_bf16 v[10:13], v[152:155], v[200:203], v[10:13]
	v_mfma_f32_16x16x32_bf16 v[10:13], v[156:159], v[204:207], v[10:13]
	v_mfma_f32_16x16x32_bf16 v[14:17], v[140:143], v[200:203], v[14:17]
	v_mfma_f32_16x16x32_bf16 v[14:17], v[148:151], v[204:207], v[14:17]
	s_setprio 0
	s_barrier
	ds_read_b128 v[140:143], v137
	ds_read_b128 v[148:151], v137 offset:1024
	ds_read_b128 v[152:155], v137 offset:2048
	ds_read_b128 v[156:159], v137 offset:3072
	ds_read_b128 v[160:163], v138
	ds_read_b128 v[164:167], v138 offset:1024
	ds_read_b128 v[168:171], v138 offset:2048
	ds_read_b128 v[172:175], v138 offset:3072
	s_mov_b32 m0, s44
	s_add_i32 s76, s73, 0x30000
	ds_read_b128 v[176:179], v136 offset:32768
	ds_read_b128 v[180:183], v136 offset:33792
	ds_read_b128 v[184:187], v136 offset:34816
	ds_read_b128 v[188:191], v136 offset:35840
	ds_read_b128 v[192:195], v136 offset:36864
	ds_read_b128 v[196:199], v136 offset:37888
	ds_read_b128 v[200:203], v136 offset:38912
	ds_read_b128 v[204:207], v136 offset:39936
	buffer_load_dwordx4 v132, s[12:15], s76 offen lds
	s_add_i32 s76, s73, 0x48000
	s_mov_b32 m0, s45
	s_nop 0
	buffer_load_dwordx4 v132, s[12:15], s76 offen lds
	s_waitcnt vmcnt(8)
	s_waitcnt lgkmcnt(0)
	s_setprio 1
	v_mfma_f32_16x16x32_bf16 v[126:129], v[140:143], v[176:179], v[126:129]
	v_mfma_f32_16x16x32_bf16 v[126:129], v[148:151], v[180:183], v[126:129]
	s_barrier
	v_mfma_f32_16x16x32_bf16 v[122:125], v[152:155], v[176:179], v[122:125]
	v_mfma_f32_16x16x32_bf16 v[122:125], v[156:159], v[180:183], v[122:125]
	v_mfma_f32_16x16x32_bf16 v[118:121], v[160:163], v[176:179], v[118:121]
	v_mfma_f32_16x16x32_bf16 v[118:121], v[164:167], v[180:183], v[118:121]
	v_mfma_f32_16x16x32_bf16 v[114:117], v[168:171], v[176:179], v[114:117]
	v_mfma_f32_16x16x32_bf16 v[114:117], v[172:175], v[180:183], v[114:117]
	v_mfma_f32_16x16x32_bf16 v[98:101], v[168:171], v[184:187], v[98:101]
	v_mfma_f32_16x16x32_bf16 v[98:101], v[172:175], v[188:191], v[98:101]
	v_mfma_f32_16x16x32_bf16 v[102:105], v[160:163], v[184:187], v[102:105]
	v_mfma_f32_16x16x32_bf16 v[102:105], v[164:167], v[188:191], v[102:105]
	v_mfma_f32_16x16x32_bf16 v[106:109], v[152:155], v[184:187], v[106:109]
	v_mfma_f32_16x16x32_bf16 v[106:109], v[156:159], v[188:191], v[106:109]
	v_mfma_f32_16x16x32_bf16 v[110:113], v[140:143], v[184:187], v[110:113]
	v_mfma_f32_16x16x32_bf16 v[110:113], v[148:151], v[188:191], v[110:113]
	v_mfma_f32_16x16x32_bf16 v[94:97], v[140:143], v[192:195], v[94:97]
	v_mfma_f32_16x16x32_bf16 v[94:97], v[148:151], v[196:199], v[94:97]
	v_mfma_f32_16x16x32_bf16 v[90:93], v[152:155], v[192:195], v[90:93]
	v_mfma_f32_16x16x32_bf16 v[90:93], v[156:159], v[196:199], v[90:93]
	v_mfma_f32_16x16x32_bf16 v[86:89], v[160:163], v[192:195], v[86:89]
	v_mfma_f32_16x16x32_bf16 v[86:89], v[164:167], v[196:199], v[86:89]
	v_mfma_f32_16x16x32_bf16 v[82:85], v[168:171], v[192:195], v[82:85]
	v_mfma_f32_16x16x32_bf16 v[82:85], v[172:175], v[196:199], v[82:85]
	v_mfma_f32_16x16x32_bf16 v[66:69], v[168:171], v[200:203], v[66:69]
	v_mfma_f32_16x16x32_bf16 v[66:69], v[172:175], v[204:207], v[66:69]
	v_mfma_f32_16x16x32_bf16 v[70:73], v[160:163], v[200:203], v[70:73]
	v_mfma_f32_16x16x32_bf16 v[70:73], v[164:167], v[204:207], v[70:73]
	v_mfma_f32_16x16x32_bf16 v[74:77], v[152:155], v[200:203], v[74:77]
	v_mfma_f32_16x16x32_bf16 v[74:77], v[156:159], v[204:207], v[74:77]
	v_mfma_f32_16x16x32_bf16 v[78:81], v[140:143], v[200:203], v[78:81]
	v_mfma_f32_16x16x32_bf16 v[78:81], v[148:151], v[204:207], v[78:81]
	s_setprio 0
	s_barrier
	s_mov_b32 m0, s46
	s_add_i32 s76, s75, 0x80
	ds_read_b128 v[176:179], v136 offset:49152
	ds_read_b128 v[180:183], v136 offset:50176
	ds_read_b128 v[184:187], v136 offset:51200
	ds_read_b128 v[188:191], v136 offset:52224
	ds_read_b128 v[192:195], v136 offset:53248
	ds_read_b128 v[196:199], v136 offset:54272
	ds_read_b128 v[200:203], v136 offset:55296
	ds_read_b128 v[204:207], v136 offset:56320
	buffer_load_dwordx4 v133, s[16:19], s76 offen lds
	s_add_i32 s76, s75, 0x200080
	s_mov_b32 m0, s47
	s_add_i32 s73, s73, 0x18080
	buffer_load_dwordx4 v133, s[16:19], s76 offen lds
	s_add_i32 s76, s75, 0x400080
	s_mov_b32 m0, s50
	s_add_i32 s75, s75, 0x600080
	buffer_load_dwordx4 v133, s[16:19], s76 offen lds
	s_mov_b32 m0, s51
	s_nop 0
	buffer_load_dwordx4 v133, s[16:19], s75 offen lds
	s_mov_b32 m0, s48
	s_nop 0
	buffer_load_dwordx4 v132, s[12:15], s74 offen lds
	s_mov_b32 m0, s49
	s_nop 0
	buffer_load_dwordx4 v132, s[12:15], s73 offen lds
	s_waitcnt vmcnt(8)
	s_waitcnt lgkmcnt(0)
	s_setprio 1
	v_mfma_f32_16x16x32_bf16 v[62:65], v[140:143], v[176:179], v[62:65]
	v_mfma_f32_16x16x32_bf16 v[62:65], v[148:151], v[180:183], v[62:65]
	s_barrier
	v_mfma_f32_16x16x32_bf16 v[58:61], v[152:155], v[176:179], v[58:61]
	v_mfma_f32_16x16x32_bf16 v[58:61], v[156:159], v[180:183], v[58:61]
	v_mfma_f32_16x16x32_bf16 v[54:57], v[160:163], v[176:179], v[54:57]
	v_mfma_f32_16x16x32_bf16 v[54:57], v[164:167], v[180:183], v[54:57]
	v_mfma_f32_16x16x32_bf16 v[50:53], v[168:171], v[176:179], v[50:53]
	v_mfma_f32_16x16x32_bf16 v[50:53], v[172:175], v[180:183], v[50:53]
	v_mfma_f32_16x16x32_bf16 v[34:37], v[168:171], v[184:187], v[34:37]
	v_mfma_f32_16x16x32_bf16 v[34:37], v[172:175], v[188:191], v[34:37]
	v_mfma_f32_16x16x32_bf16 v[38:41], v[160:163], v[184:187], v[38:41]
	v_mfma_f32_16x16x32_bf16 v[38:41], v[164:167], v[188:191], v[38:41]
	v_mfma_f32_16x16x32_bf16 v[42:45], v[152:155], v[184:187], v[42:45]
	v_mfma_f32_16x16x32_bf16 v[42:45], v[156:159], v[188:191], v[42:45]
	v_mfma_f32_16x16x32_bf16 v[46:49], v[140:143], v[184:187], v[46:49]
	v_mfma_f32_16x16x32_bf16 v[46:49], v[148:151], v[188:191], v[46:49]
	v_mfma_f32_16x16x32_bf16 v[30:33], v[140:143], v[192:195], v[30:33]
	v_mfma_f32_16x16x32_bf16 v[30:33], v[148:151], v[196:199], v[30:33]
	v_mfma_f32_16x16x32_bf16 v[26:29], v[152:155], v[192:195], v[26:29]
	v_mfma_f32_16x16x32_bf16 v[26:29], v[156:159], v[196:199], v[26:29]
	v_mfma_f32_16x16x32_bf16 v[22:25], v[160:163], v[192:195], v[22:25]
	v_mfma_f32_16x16x32_bf16 v[22:25], v[164:167], v[196:199], v[22:25]
	v_mfma_f32_16x16x32_bf16 v[18:21], v[168:171], v[192:195], v[18:21]
	v_mfma_f32_16x16x32_bf16 v[18:21], v[172:175], v[196:199], v[18:21]
	v_mfma_f32_16x16x32_bf16 v[2:5], v[168:171], v[200:203], v[2:5]
	v_mfma_f32_16x16x32_bf16 v[2:5], v[172:175], v[204:207], v[2:5]
	v_mfma_f32_16x16x32_bf16 v[6:9], v[160:163], v[200:203], v[6:9]
	v_mfma_f32_16x16x32_bf16 v[6:9], v[164:167], v[204:207], v[6:9]
	v_mfma_f32_16x16x32_bf16 v[10:13], v[152:155], v[200:203], v[10:13]
	v_mfma_f32_16x16x32_bf16 v[10:13], v[156:159], v[204:207], v[10:13]
	v_mfma_f32_16x16x32_bf16 v[14:17], v[140:143], v[200:203], v[14:17]
	v_mfma_f32_16x16x32_bf16 v[14:17], v[148:151], v[204:207], v[14:17]
	s_setprio 0
	s_barrier
	s_add_i32 s72, s72, 2
	s_addk_i32 s70, 0x100
	s_addk_i32 s71, 0x100
	s_cmp_ge_i32 s72, s21
	s_cbranch_scc0 .LBB0_1035

.LBB0_1050:
	ds_read_b128 v[132:135], v142
	ds_read_b128 v[136:139], v142 offset:1024
	ds_read_b128 v[148:151], v142 offset:2048
	ds_read_b128 v[152:155], v142 offset:3072
	ds_read_b128 v[156:159], v143
	ds_read_b128 v[160:163], v143 offset:1024
	ds_read_b128 v[164:167], v143 offset:2048
	ds_read_b128 v[168:171], v143 offset:3072
	s_add_i32 s18, s61, 0xfff40080
	s_cmp_eq_u32 s54, s62
	s_cselect_b32 s64, s35, s18
	s_add_i32 s63, s64, 0x80
	s_add_i32 s18, s61, 0xfffc0000
	s_mov_b32 m0, s55
	ds_read_b128 v[172:175], v144
	ds_read_b128 v[176:179], v144 offset:1024
	ds_read_b128 v[180:183], v144 offset:2048
	ds_read_b128 v[184:187], v144 offset:3072
	ds_read_b128 v[188:191], v144 offset:4096
	ds_read_b128 v[192:195], v144 offset:5120
	ds_read_b128 v[196:199], v144 offset:6144
	ds_read_b128 v[200:203], v144 offset:7168
	buffer_load_dwordx4 v140, s[12:15], s18 offen lds
	s_mov_b32 m0, s56
	s_nop 0
	buffer_load_dwordx4 v140, s[12:15], s61 offen lds
	s_waitcnt vmcnt(8)
	s_waitcnt lgkmcnt(0)
	s_setprio 1
	v_mfma_f32_16x16x32_bf16 v[126:129], v[132:135], v[172:175], v[126:129]
	v_mfma_f32_16x16x32_bf16 v[126:129], v[136:139], v[176:179], v[126:129]
	s_barrier
	v_mfma_f32_16x16x32_bf16 v[122:125], v[148:151], v[172:175], v[122:125]
	v_mfma_f32_16x16x32_bf16 v[122:125], v[152:155], v[176:179], v[122:125]
	v_mfma_f32_16x16x32_bf16 v[118:121], v[156:159], v[172:175], v[118:121]
	v_mfma_f32_16x16x32_bf16 v[118:121], v[160:163], v[176:179], v[118:121]
	v_mfma_f32_16x16x32_bf16 v[114:117], v[164:167], v[172:175], v[114:117]
	v_mfma_f32_16x16x32_bf16 v[114:117], v[168:171], v[176:179], v[114:117]
	v_mfma_f32_16x16x32_bf16 v[98:101], v[164:167], v[180:183], v[98:101]
	v_mfma_f32_16x16x32_bf16 v[98:101], v[168:171], v[184:187], v[98:101]
	v_mfma_f32_16x16x32_bf16 v[102:105], v[156:159], v[180:183], v[102:105]
	v_mfma_f32_16x16x32_bf16 v[102:105], v[160:163], v[184:187], v[102:105]
	v_mfma_f32_16x16x32_bf16 v[106:109], v[148:151], v[180:183], v[106:109]
	v_mfma_f32_16x16x32_bf16 v[106:109], v[152:155], v[184:187], v[106:109]
	v_mfma_f32_16x16x32_bf16 v[110:113], v[132:135], v[180:183], v[110:113]
	v_mfma_f32_16x16x32_bf16 v[110:113], v[136:139], v[184:187], v[110:113]
	v_mfma_f32_16x16x32_bf16 v[94:97], v[132:135], v[188:191], v[94:97]
	v_mfma_f32_16x16x32_bf16 v[94:97], v[136:139], v[192:195], v[94:97]
	v_mfma_f32_16x16x32_bf16 v[90:93], v[148:151], v[188:191], v[90:93]
	v_mfma_f32_16x16x32_bf16 v[90:93], v[152:155], v[192:195], v[90:93]
	v_mfma_f32_16x16x32_bf16 v[86:89], v[156:159], v[188:191], v[86:89]
	v_mfma_f32_16x16x32_bf16 v[86:89], v[160:163], v[192:195], v[86:89]
	v_mfma_f32_16x16x32_bf16 v[82:85], v[164:167], v[188:191], v[82:85]
	v_mfma_f32_16x16x32_bf16 v[82:85], v[168:171], v[192:195], v[82:85]
	v_mfma_f32_16x16x32_bf16 v[66:69], v[164:167], v[196:199], v[66:69]
	v_mfma_f32_16x16x32_bf16 v[66:69], v[168:171], v[200:203], v[66:69]
	v_mfma_f32_16x16x32_bf16 v[70:73], v[156:159], v[196:199], v[70:73]
	v_mfma_f32_16x16x32_bf16 v[70:73], v[160:163], v[200:203], v[70:73]
	v_mfma_f32_16x16x32_bf16 v[74:77], v[148:151], v[196:199], v[74:77]
	v_mfma_f32_16x16x32_bf16 v[74:77], v[152:155], v[200:203], v[74:77]
	v_mfma_f32_16x16x32_bf16 v[78:81], v[132:135], v[196:199], v[78:81]
	v_mfma_f32_16x16x32_bf16 v[78:81], v[136:139], v[200:203], v[78:81]
	s_setprio 0
	s_barrier
	s_mov_b32 m0, s25
	s_mov_b32 s18, s14
	s_mov_b32 s19, s15
	ds_read_b128 v[172:175], v144 offset:16384
	ds_read_b128 v[176:179], v144 offset:17408
	ds_read_b128 v[180:183], v144 offset:18432
	ds_read_b128 v[184:187], v144 offset:19456
	ds_read_b128 v[188:191], v144 offset:20480
	ds_read_b128 v[192:195], v144 offset:21504
	ds_read_b128 v[196:199], v144 offset:22528
	ds_read_b128 v[200:203], v144 offset:23552
	buffer_load_dwordx4 v141, s[16:19], s64 offen lds
	s_add_i32 s65, s64, 0x40000
	s_mov_b32 m0, s27
	s_add_i32 s66, s64, 0x80000
	buffer_load_dwordx4 v141, s[16:19], s65 offen lds
	s_mov_b32 m0, s30
	s_add_i32 s67, s64, 0xc0000
	buffer_load_dwordx4 v141, s[16:19], s66 offen lds
	s_mov_b32 m0, s31
	s_nop 0
	buffer_load_dwordx4 v141, s[16:19], s67 offen lds
	s_mov_b32 m0, s21
	s_nop 0
	buffer_load_dwordx4 v140, s[12:15], s64 offen lds
	s_mov_b32 m0, s38
	s_nop 0
	buffer_load_dwordx4 v140, s[12:15], s65 offen lds
	s_waitcnt vmcnt(8)
	s_waitcnt lgkmcnt(0)
	s_setprio 1
	v_mfma_f32_16x16x32_bf16 v[62:65], v[132:135], v[172:175], v[62:65]
	v_mfma_f32_16x16x32_bf16 v[62:65], v[136:139], v[176:179], v[62:65]
	s_barrier
	v_mfma_f32_16x16x32_bf16 v[58:61], v[148:151], v[172:175], v[58:61]
	v_mfma_f32_16x16x32_bf16 v[58:61], v[152:155], v[176:179], v[58:61]
	v_mfma_f32_16x16x32_bf16 v[54:57], v[156:159], v[172:175], v[54:57]
	v_mfma_f32_16x16x32_bf16 v[54:57], v[160:163], v[176:179], v[54:57]
	v_mfma_f32_16x16x32_bf16 v[50:53], v[164:167], v[172:175], v[50:53]
	v_mfma_f32_16x16x32_bf16 v[50:53], v[168:171], v[176:179], v[50:53]
	v_mfma_f32_16x16x32_bf16 v[34:37], v[164:167], v[180:183], v[34:37]
	v_mfma_f32_16x16x32_bf16 v[34:37], v[168:171], v[184:187], v[34:37]
	v_mfma_f32_16x16x32_bf16 v[38:41], v[156:159], v[180:183], v[38:41]
	v_mfma_f32_16x16x32_bf16 v[38:41], v[160:163], v[184:187], v[38:41]
	v_mfma_f32_16x16x32_bf16 v[42:45], v[148:151], v[180:183], v[42:45]
	v_mfma_f32_16x16x32_bf16 v[42:45], v[152:155], v[184:187], v[42:45]
	v_mfma_f32_16x16x32_bf16 v[46:49], v[132:135], v[180:183], v[46:49]
	v_mfma_f32_16x16x32_bf16 v[46:49], v[136:139], v[184:187], v[46:49]
	v_mfma_f32_16x16x32_bf16 v[30:33], v[132:135], v[188:191], v[30:33]
	v_mfma_f32_16x16x32_bf16 v[30:33], v[136:139], v[192:195], v[30:33]
	v_mfma_f32_16x16x32_bf16 v[26:29], v[148:151], v[188:191], v[26:29]
	v_mfma_f32_16x16x32_bf16 v[26:29], v[152:155], v[192:195], v[26:29]
	v_mfma_f32_16x16x32_bf16 v[22:25], v[156:159], v[188:191], v[22:25]
	v_mfma_f32_16x16x32_bf16 v[22:25], v[160:163], v[192:195], v[22:25]
	v_mfma_f32_16x16x32_bf16 v[18:21], v[164:167], v[188:191], v[18:21]
	v_mfma_f32_16x16x32_bf16 v[18:21], v[168:171], v[192:195], v[18:21]
	v_mfma_f32_16x16x32_bf16 v[2:5], v[164:167], v[196:199], v[2:5]
	v_mfma_f32_16x16x32_bf16 v[2:5], v[168:171], v[200:203], v[2:5]
	v_mfma_f32_16x16x32_bf16 v[6:9], v[156:159], v[196:199], v[6:9]
	v_mfma_f32_16x16x32_bf16 v[6:9], v[160:163], v[200:203], v[6:9]
	v_mfma_f32_16x16x32_bf16 v[10:13], v[148:151], v[196:199], v[10:13]
	v_mfma_f32_16x16x32_bf16 v[10:13], v[152:155], v[200:203], v[10:13]
	v_mfma_f32_16x16x32_bf16 v[14:17], v[132:135], v[196:199], v[14:17]
	v_mfma_f32_16x16x32_bf16 v[14:17], v[136:139], v[200:203], v[14:17]
	s_setprio 0
	s_barrier
	ds_read_b128 v[132:135], v145
	ds_read_b128 v[136:139], v145 offset:1024
	ds_read_b128 v[148:151], v145 offset:2048
	ds_read_b128 v[152:155], v145 offset:3072
	ds_read_b128 v[156:159], v147
	ds_read_b128 v[160:163], v147 offset:1024
	ds_read_b128 v[164:167], v147 offset:2048
	ds_read_b128 v[168:171], v147 offset:3072
	s_mov_b32 m0, s39
	ds_read_b128 v[172:175], v144 offset:32768
	ds_read_b128 v[176:179], v144 offset:33792
	ds_read_b128 v[180:183], v144 offset:34816
	ds_read_b128 v[184:187], v144 offset:35840
	ds_read_b128 v[188:191], v144 offset:36864
	ds_read_b128 v[192:195], v144 offset:37888
	ds_read_b128 v[196:199], v144 offset:38912
	ds_read_b128 v[200:203], v144 offset:39936
	buffer_load_dwordx4 v140, s[12:15], s66 offen lds
	s_mov_b32 m0, s40
	s_nop 0
	buffer_load_dwordx4 v140, s[12:15], s67 offen lds
	s_waitcnt vmcnt(8)
	s_waitcnt lgkmcnt(0)
	s_setprio 1
	v_mfma_f32_16x16x32_bf16 v[126:129], v[132:135], v[172:175], v[126:129]
	v_mfma_f32_16x16x32_bf16 v[126:129], v[136:139], v[176:179], v[126:129]
	s_barrier
	v_mfma_f32_16x16x32_bf16 v[122:125], v[148:151], v[172:175], v[122:125]
	v_mfma_f32_16x16x32_bf16 v[122:125], v[152:155], v[176:179], v[122:125]
	v_mfma_f32_16x16x32_bf16 v[118:121], v[156:159], v[172:175], v[118:121]
	v_mfma_f32_16x16x32_bf16 v[118:121], v[160:163], v[176:179], v[118:121]
	v_mfma_f32_16x16x32_bf16 v[114:117], v[164:167], v[172:175], v[114:117]
	v_mfma_f32_16x16x32_bf16 v[114:117], v[168:171], v[176:179], v[114:117]
	v_mfma_f32_16x16x32_bf16 v[98:101], v[164:167], v[180:183], v[98:101]
	v_mfma_f32_16x16x32_bf16 v[98:101], v[168:171], v[184:187], v[98:101]
	v_mfma_f32_16x16x32_bf16 v[102:105], v[156:159], v[180:183], v[102:105]
	v_mfma_f32_16x16x32_bf16 v[102:105], v[160:163], v[184:187], v[102:105]
	v_mfma_f32_16x16x32_bf16 v[106:109], v[148:151], v[180:183], v[106:109]
	v_mfma_f32_16x16x32_bf16 v[106:109], v[152:155], v[184:187], v[106:109]
	v_mfma_f32_16x16x32_bf16 v[110:113], v[132:135], v[180:183], v[110:113]
	v_mfma_f32_16x16x32_bf16 v[110:113], v[136:139], v[184:187], v[110:113]
	v_mfma_f32_16x16x32_bf16 v[94:97], v[132:135], v[188:191], v[94:97]
	v_mfma_f32_16x16x32_bf16 v[94:97], v[136:139], v[192:195], v[94:97]
	v_mfma_f32_16x16x32_bf16 v[90:93], v[148:151], v[188:191], v[90:93]
	v_mfma_f32_16x16x32_bf16 v[90:93], v[152:155], v[192:195], v[90:93]
	v_mfma_f32_16x16x32_bf16 v[86:89], v[156:159], v[188:191], v[86:89]
	v_mfma_f32_16x16x32_bf16 v[86:89], v[160:163], v[192:195], v[86:89]
	v_mfma_f32_16x16x32_bf16 v[82:85], v[164:167], v[188:191], v[82:85]
	v_mfma_f32_16x16x32_bf16 v[82:85], v[168:171], v[192:195], v[82:85]
	v_mfma_f32_16x16x32_bf16 v[66:69], v[164:167], v[196:199], v[66:69]
	v_mfma_f32_16x16x32_bf16 v[66:69], v[168:171], v[200:203], v[66:69]
	v_mfma_f32_16x16x32_bf16 v[70:73], v[156:159], v[196:199], v[70:73]
	v_mfma_f32_16x16x32_bf16 v[70:73], v[160:163], v[200:203], v[70:73]
	v_mfma_f32_16x16x32_bf16 v[74:77], v[148:151], v[196:199], v[74:77]
	v_mfma_f32_16x16x32_bf16 v[74:77], v[152:155], v[200:203], v[74:77]
	v_mfma_f32_16x16x32_bf16 v[78:81], v[132:135], v[196:199], v[78:81]
	v_mfma_f32_16x16x32_bf16 v[78:81], v[136:139], v[200:203], v[78:81]
	s_setprio 0
	s_barrier
	s_mov_b32 m0, s48
	ds_read_b128 v[172:175], v144 offset:49152
	ds_read_b128 v[176:179], v144 offset:50176
	ds_read_b128 v[180:183], v144 offset:51200
	ds_read_b128 v[184:187], v144 offset:52224
	ds_read_b128 v[188:191], v144 offset:53248
	ds_read_b128 v[192:195], v144 offset:54272
	ds_read_b128 v[196:199], v144 offset:55296
	ds_read_b128 v[200:203], v144 offset:56320
	buffer_load_dwordx4 v141, s[16:19], s63 offen lds
	s_add_i32 s65, s64, 0x40080
	s_mov_b32 m0, s49
	s_add_i32 s66, s64, 0x80080
	buffer_load_dwordx4 v141, s[16:19], s65 offen lds
	s_mov_b32 m0, s52
	s_add_i32 s64, s64, 0xc0080
	buffer_load_dwordx4 v141, s[16:19], s66 offen lds
	s_mov_b32 m0, s53
	s_nop 0
	buffer_load_dwordx4 v141, s[16:19], s64 offen lds
	s_mov_b32 m0, s50
	s_nop 0
	buffer_load_dwordx4 v140, s[12:15], s63 offen lds
	s_mov_b32 m0, s51
	s_nop 0
	buffer_load_dwordx4 v140, s[12:15], s65 offen lds
	s_waitcnt vmcnt(8)
	s_waitcnt lgkmcnt(0)
	s_setprio 1
	v_mfma_f32_16x16x32_bf16 v[62:65], v[132:135], v[172:175], v[62:65]
	v_mfma_f32_16x16x32_bf16 v[62:65], v[136:139], v[176:179], v[62:65]
	s_barrier
	v_mfma_f32_16x16x32_bf16 v[58:61], v[148:151], v[172:175], v[58:61]
	v_mfma_f32_16x16x32_bf16 v[58:61], v[152:155], v[176:179], v[58:61]
	v_mfma_f32_16x16x32_bf16 v[54:57], v[156:159], v[172:175], v[54:57]
	v_mfma_f32_16x16x32_bf16 v[54:57], v[160:163], v[176:179], v[54:57]
	v_mfma_f32_16x16x32_bf16 v[50:53], v[164:167], v[172:175], v[50:53]
	v_mfma_f32_16x16x32_bf16 v[50:53], v[168:171], v[176:179], v[50:53]
	v_mfma_f32_16x16x32_bf16 v[34:37], v[164:167], v[180:183], v[34:37]
	v_mfma_f32_16x16x32_bf16 v[34:37], v[168:171], v[184:187], v[34:37]
	v_mfma_f32_16x16x32_bf16 v[38:41], v[156:159], v[180:183], v[38:41]
	v_mfma_f32_16x16x32_bf16 v[38:41], v[160:163], v[184:187], v[38:41]
	v_mfma_f32_16x16x32_bf16 v[42:45], v[148:151], v[180:183], v[42:45]
	v_mfma_f32_16x16x32_bf16 v[42:45], v[152:155], v[184:187], v[42:45]
	v_mfma_f32_16x16x32_bf16 v[46:49], v[132:135], v[180:183], v[46:49]
	v_mfma_f32_16x16x32_bf16 v[46:49], v[136:139], v[184:187], v[46:49]
	v_mfma_f32_16x16x32_bf16 v[30:33], v[132:135], v[188:191], v[30:33]
	v_mfma_f32_16x16x32_bf16 v[30:33], v[136:139], v[192:195], v[30:33]
	v_mfma_f32_16x16x32_bf16 v[26:29], v[148:151], v[188:191], v[26:29]
	v_mfma_f32_16x16x32_bf16 v[26:29], v[152:155], v[192:195], v[26:29]
	v_mfma_f32_16x16x32_bf16 v[22:25], v[156:159], v[188:191], v[22:25]
	v_mfma_f32_16x16x32_bf16 v[22:25], v[160:163], v[192:195], v[22:25]
	v_mfma_f32_16x16x32_bf16 v[18:21], v[164:167], v[188:191], v[18:21]
	v_mfma_f32_16x16x32_bf16 v[18:21], v[168:171], v[192:195], v[18:21]
	v_mfma_f32_16x16x32_bf16 v[2:5], v[164:167], v[196:199], v[2:5]
	v_mfma_f32_16x16x32_bf16 v[2:5], v[168:171], v[200:203], v[2:5]
	v_mfma_f32_16x16x32_bf16 v[6:9], v[156:159], v[196:199], v[6:9]
	v_mfma_f32_16x16x32_bf16 v[6:9], v[160:163], v[200:203], v[6:9]
	v_mfma_f32_16x16x32_bf16 v[10:13], v[148:151], v[196:199], v[10:13]
	v_mfma_f32_16x16x32_bf16 v[10:13], v[152:155], v[200:203], v[10:13]
	v_mfma_f32_16x16x32_bf16 v[14:17], v[132:135], v[196:199], v[14:17]
	v_mfma_f32_16x16x32_bf16 v[14:17], v[136:139], v[200:203], v[14:17]
	s_setprio 0
	s_barrier
	s_add_i32 s62, s62, 2
	s_addk_i32 s61, 0x100
	s_cmp_ge_i32 s62, s3
	s_cbranch_scc0 .LBB0_1050

.LBB0_1181:
	v_add_u32_e32 v2, 0x10000, v232
	ds_read_b128 v[134:137], v2
	ds_read_b128 v[138:141], v2 offset:1024
	ds_read_b128 v[142:145], v2 offset:2048
	ds_read_b128 v[146:149], v2 offset:3072
	v_add_u32_e32 v2, 0x14000, v232
	ds_read_b128 v[150:153], v2
	ds_read_b128 v[154:157], v2 offset:1024
	ds_read_b128 v[158:161], v2 offset:2048
	ds_read_b128 v[162:165], v2 offset:3072
	s_add_i32 s50, s47, s90
	s_and_b64 s[18:19], exec, s[18:19]
	s_cselect_b32 s51, s88, s50
	s_add_i32 s50, s92, 0x80
	s_or_b32 s52, s51, 0x80
	s_add_i32 s18, s89, s93
	s_add_i32 s94, s94, 0x1bfffc80
	s_cmp_lt_u32 s91, 8
	s_cselect_b32 s18, s18, s94
	s_mov_b32 m0, s74
	s_add_i32 s19, s18, 0x80000
	ds_read_b128 v[166:169], v233
	ds_read_b128 v[170:173], v233 offset:1024
	ds_read_b128 v[174:177], v233 offset:2048
	ds_read_b128 v[178:181], v233 offset:3072
	ds_read_b128 v[182:185], v233 offset:4096
	ds_read_b128 v[186:189], v233 offset:5120
	ds_read_b128 v[190:193], v233 offset:6144
	ds_read_b128 v[194:197], v233 offset:7168
	buffer_load_dwordx4 v230, s[12:15], s19 offen lds
	s_add_i32 s18, s18, 0xc0000
	s_mov_b32 m0, s75
	s_nop 0
	buffer_load_dwordx4 v230, s[12:15], s18 offen lds
	s_waitcnt vmcnt(8)
	s_waitcnt lgkmcnt(0)
	s_setprio 1
	v_mfma_f32_16x16x32_bf16 v[130:133], v[134:137], v[166:169], v[130:133]
	v_mfma_f32_16x16x32_bf16 v[130:133], v[138:141], v[170:173], v[130:133]
	s_barrier
	v_mfma_f32_16x16x32_bf16 v[126:129], v[142:145], v[166:169], v[126:129]
	v_mfma_f32_16x16x32_bf16 v[126:129], v[146:149], v[170:173], v[126:129]
	v_mfma_f32_16x16x32_bf16 v[122:125], v[150:153], v[166:169], v[122:125]
	v_mfma_f32_16x16x32_bf16 v[122:125], v[154:157], v[170:173], v[122:125]
	v_mfma_f32_16x16x32_bf16 v[118:121], v[158:161], v[166:169], v[118:121]
	v_mfma_f32_16x16x32_bf16 v[118:121], v[162:165], v[170:173], v[118:121]
	v_mfma_f32_16x16x32_bf16 v[102:105], v[158:161], v[174:177], v[102:105]
	v_mfma_f32_16x16x32_bf16 v[102:105], v[162:165], v[178:181], v[102:105]
	v_mfma_f32_16x16x32_bf16 v[106:109], v[150:153], v[174:177], v[106:109]
	v_mfma_f32_16x16x32_bf16 v[106:109], v[154:157], v[178:181], v[106:109]
	v_mfma_f32_16x16x32_bf16 v[110:113], v[142:145], v[174:177], v[110:113]
	v_mfma_f32_16x16x32_bf16 v[110:113], v[146:149], v[178:181], v[110:113]
	v_mfma_f32_16x16x32_bf16 v[114:117], v[134:137], v[174:177], v[114:117]
	v_mfma_f32_16x16x32_bf16 v[114:117], v[138:141], v[178:181], v[114:117]
	v_mfma_f32_16x16x32_bf16 v[98:101], v[134:137], v[182:185], v[98:101]
	v_mfma_f32_16x16x32_bf16 v[98:101], v[138:141], v[186:189], v[98:101]
	v_mfma_f32_16x16x32_bf16 v[94:97], v[142:145], v[182:185], v[94:97]
	v_mfma_f32_16x16x32_bf16 v[94:97], v[146:149], v[186:189], v[94:97]
	v_mfma_f32_16x16x32_bf16 v[90:93], v[150:153], v[182:185], v[90:93]
	v_mfma_f32_16x16x32_bf16 v[90:93], v[154:157], v[186:189], v[90:93]
	v_mfma_f32_16x16x32_bf16 v[86:89], v[158:161], v[182:185], v[86:89]
	v_mfma_f32_16x16x32_bf16 v[86:89], v[162:165], v[186:189], v[86:89]
	v_mfma_f32_16x16x32_bf16 v[70:73], v[158:161], v[190:193], v[70:73]
	v_mfma_f32_16x16x32_bf16 v[70:73], v[162:165], v[194:197], v[70:73]
	v_mfma_f32_16x16x32_bf16 v[74:77], v[150:153], v[190:193], v[74:77]
	v_mfma_f32_16x16x32_bf16 v[74:77], v[154:157], v[194:197], v[74:77]
	v_mfma_f32_16x16x32_bf16 v[78:81], v[142:145], v[190:193], v[78:81]
	v_mfma_f32_16x16x32_bf16 v[78:81], v[146:149], v[194:197], v[78:81]
	v_mfma_f32_16x16x32_bf16 v[82:85], v[134:137], v[190:193], v[82:85]
	v_mfma_f32_16x16x32_bf16 v[82:85], v[138:141], v[194:197], v[82:85]
	s_setprio 0
	s_barrier
	s_mov_b32 m0, s27
	s_mov_b32 s18, s14
	s_mov_b32 s19, s15
	ds_read_b128 v[166:169], v233 offset:16384
	ds_read_b128 v[170:173], v233 offset:17408
	ds_read_b128 v[174:177], v233 offset:18432
	ds_read_b128 v[178:181], v233 offset:19456
	ds_read_b128 v[182:185], v233 offset:20480
	ds_read_b128 v[186:189], v233 offset:21504
	ds_read_b128 v[190:193], v233 offset:22528
	ds_read_b128 v[194:197], v233 offset:23552
	buffer_load_dwordx4 v231, s[16:19], s51 offen lds
	s_add_i32 s53, s51, 0x18000
	s_mov_b32 m0, s30
	s_nop 0
	buffer_load_dwordx4 v231, s[16:19], s53 offen lds
	s_add_i32 s53, s51, 0x30000
	s_mov_b32 m0, s31
	s_nop 0
	buffer_load_dwordx4 v231, s[16:19], s53 offen lds
	s_add_i32 s53, s51, 0x48000
	s_mov_b32 m0, s54
	s_nop 0
	buffer_load_dwordx4 v231, s[16:19], s53 offen lds
	s_mov_b32 m0, s25
	s_add_i32 s53, s92, 0x40000
	buffer_load_dwordx4 v230, s[12:15], s92 offen lds
	s_mov_b32 m0, s55
	s_nop 0
	buffer_load_dwordx4 v230, s[12:15], s53 offen lds
	s_waitcnt vmcnt(8)
	s_waitcnt lgkmcnt(0)
	s_setprio 1
	v_mfma_f32_16x16x32_bf16 v[66:69], v[134:137], v[166:169], v[66:69]
	v_mfma_f32_16x16x32_bf16 v[62:65], v[142:145], v[166:169], v[62:65]
	s_barrier
	v_mfma_f32_16x16x32_bf16 v[50:53], v[134:137], v[174:177], v[50:53]
	v_mfma_f32_16x16x32_bf16 v[46:49], v[142:145], v[174:177], v[46:49]
	v_mfma_f32_16x16x32_bf16 v[34:37], v[134:137], v[182:185], v[34:37]
	v_mfma_f32_16x16x32_bf16 v[30:33], v[142:145], v[182:185], v[30:33]
	v_mfma_f32_16x16x32_bf16 v[18:21], v[134:137], v[190:193], v[18:21]
	v_mfma_f32_16x16x32_bf16 v[14:17], v[142:145], v[190:193], v[14:17]
	v_mfma_f32_16x16x32_bf16 v[58:61], v[150:153], v[166:169], v[58:61]
	v_mfma_f32_16x16x32_bf16 v[54:57], v[158:161], v[166:169], v[54:57]
	v_mfma_f32_16x16x32_bf16 v[42:45], v[150:153], v[174:177], v[42:45]
	v_mfma_f32_16x16x32_bf16 v[38:41], v[158:161], v[174:177], v[38:41]
	v_mfma_f32_16x16x32_bf16 v[26:29], v[150:153], v[182:185], v[26:29]
	v_mfma_f32_16x16x32_bf16 v[22:25], v[158:161], v[182:185], v[22:25]
	v_mfma_f32_16x16x32_bf16 v[10:13], v[150:153], v[190:193], v[10:13]
	v_mfma_f32_16x16x32_bf16 v[4:7], v[158:161], v[190:193], v[6:9]
	v_mfma_f32_16x16x32_bf16 v[66:69], v[138:141], v[170:173], v[66:69]
	v_mfma_f32_16x16x32_bf16 v[62:65], v[146:149], v[170:173], v[62:65]
	v_mfma_f32_16x16x32_bf16 v[50:53], v[138:141], v[178:181], v[50:53]
	v_mfma_f32_16x16x32_bf16 v[46:49], v[146:149], v[178:181], v[46:49]
	v_mfma_f32_16x16x32_bf16 v[34:37], v[138:141], v[186:189], v[34:37]
	v_mfma_f32_16x16x32_bf16 v[30:33], v[146:149], v[186:189], v[30:33]
	v_mfma_f32_16x16x32_bf16 v[18:21], v[138:141], v[194:197], v[18:21]
	v_mfma_f32_16x16x32_bf16 v[14:17], v[146:149], v[194:197], v[14:17]
	v_mfma_f32_16x16x32_bf16 v[58:61], v[154:157], v[170:173], v[58:61]
	v_mfma_f32_16x16x32_bf16 v[54:57], v[162:165], v[170:173], v[54:57]
	v_mfma_f32_16x16x32_bf16 v[42:45], v[154:157], v[178:181], v[42:45]
	v_mfma_f32_16x16x32_bf16 v[38:41], v[162:165], v[178:181], v[38:41]
	v_mfma_f32_16x16x32_bf16 v[26:29], v[154:157], v[186:189], v[26:29]
	v_mfma_f32_16x16x32_bf16 v[22:25], v[162:165], v[186:189], v[22:25]
	v_mfma_f32_16x16x32_bf16 v[10:13], v[154:157], v[194:197], v[10:13]
	v_mfma_f32_16x16x32_bf16 v[4:7], v[162:165], v[194:197], v[4:7]
	s_setprio 0
	s_barrier
	v_add_u32_e32 v2, 0x18000, v232
	ds_read_b128 v[134:137], v2
	ds_read_b128 v[138:141], v2 offset:1024
	ds_read_b128 v[142:145], v2 offset:2048
	ds_read_b128 v[146:149], v2 offset:3072
	v_add_u32_e32 v2, 0x1c000, v232
	ds_read_b128 v[150:153], v2
	ds_read_b128 v[154:157], v2 offset:1024
	ds_read_b128 v[158:161], v2 offset:2048
	ds_read_b128 v[162:165], v2 offset:3072
	s_mov_b32 m0, s56
	s_add_i32 s53, s92, 0x80000
	ds_read_b128 v[166:169], v233 offset:32768
	ds_read_b128 v[170:173], v233 offset:33792
	ds_read_b128 v[174:177], v233 offset:34816
	ds_read_b128 v[178:181], v233 offset:35840
	ds_read_b128 v[182:185], v233 offset:36864
	ds_read_b128 v[186:189], v233 offset:37888
	ds_read_b128 v[190:193], v233 offset:38912
	ds_read_b128 v[194:197], v233 offset:39936
	buffer_load_dwordx4 v230, s[12:15], s53 offen lds
	s_add_i32 s53, s92, 0xc0000
	s_mov_b32 m0, s57
	s_nop 0
	buffer_load_dwordx4 v230, s[12:15], s53 offen lds
	s_waitcnt vmcnt(8)
	s_waitcnt lgkmcnt(0)
	s_setprio 1
	v_mfma_f32_16x16x32_bf16 v[130:133], v[134:137], v[166:169], v[130:133]
	v_mfma_f32_16x16x32_bf16 v[130:133], v[138:141], v[170:173], v[130:133]
	s_barrier
	v_mfma_f32_16x16x32_bf16 v[126:129], v[142:145], v[166:169], v[126:129]
	v_mfma_f32_16x16x32_bf16 v[126:129], v[146:149], v[170:173], v[126:129]
	v_mfma_f32_16x16x32_bf16 v[122:125], v[150:153], v[166:169], v[122:125]
	v_mfma_f32_16x16x32_bf16 v[122:125], v[154:157], v[170:173], v[122:125]
	v_mfma_f32_16x16x32_bf16 v[118:121], v[158:161], v[166:169], v[118:121]
	v_mfma_f32_16x16x32_bf16 v[118:121], v[162:165], v[170:173], v[118:121]
	v_mfma_f32_16x16x32_bf16 v[102:105], v[158:161], v[174:177], v[102:105]
	v_mfma_f32_16x16x32_bf16 v[102:105], v[162:165], v[178:181], v[102:105]
	v_mfma_f32_16x16x32_bf16 v[106:109], v[150:153], v[174:177], v[106:109]
	v_mfma_f32_16x16x32_bf16 v[106:109], v[154:157], v[178:181], v[106:109]
	v_mfma_f32_16x16x32_bf16 v[110:113], v[142:145], v[174:177], v[110:113]
	v_mfma_f32_16x16x32_bf16 v[110:113], v[146:149], v[178:181], v[110:113]
	v_mfma_f32_16x16x32_bf16 v[114:117], v[134:137], v[174:177], v[114:117]
	v_mfma_f32_16x16x32_bf16 v[114:117], v[138:141], v[178:181], v[114:117]
	v_mfma_f32_16x16x32_bf16 v[98:101], v[134:137], v[182:185], v[98:101]
	v_mfma_f32_16x16x32_bf16 v[98:101], v[138:141], v[186:189], v[98:101]
	v_mfma_f32_16x16x32_bf16 v[94:97], v[142:145], v[182:185], v[94:97]
	v_mfma_f32_16x16x32_bf16 v[94:97], v[146:149], v[186:189], v[94:97]
	v_mfma_f32_16x16x32_bf16 v[90:93], v[150:153], v[182:185], v[90:93]
	v_mfma_f32_16x16x32_bf16 v[90:93], v[154:157], v[186:189], v[90:93]
	v_mfma_f32_16x16x32_bf16 v[86:89], v[158:161], v[182:185], v[86:89]
	v_mfma_f32_16x16x32_bf16 v[86:89], v[162:165], v[186:189], v[86:89]
	v_mfma_f32_16x16x32_bf16 v[70:73], v[158:161], v[190:193], v[70:73]
	v_mfma_f32_16x16x32_bf16 v[70:73], v[162:165], v[194:197], v[70:73]
	v_mfma_f32_16x16x32_bf16 v[74:77], v[150:153], v[190:193], v[74:77]
	v_mfma_f32_16x16x32_bf16 v[74:77], v[154:157], v[194:197], v[74:77]
	v_mfma_f32_16x16x32_bf16 v[78:81], v[142:145], v[190:193], v[78:81]
	v_mfma_f32_16x16x32_bf16 v[78:81], v[146:149], v[194:197], v[78:81]
	v_mfma_f32_16x16x32_bf16 v[82:85], v[134:137], v[190:193], v[82:85]
	v_mfma_f32_16x16x32_bf16 v[82:85], v[138:141], v[194:197], v[82:85]
	s_setprio 0
	s_barrier
	s_mov_b32 m0, s64
	ds_read_b128 v[166:169], v233 offset:49152
	ds_read_b128 v[170:173], v233 offset:50176
	ds_read_b128 v[174:177], v233 offset:51200
	ds_read_b128 v[178:181], v233 offset:52224
	ds_read_b128 v[182:185], v233 offset:53248
	ds_read_b128 v[186:189], v233 offset:54272
	ds_read_b128 v[190:193], v233 offset:55296
	ds_read_b128 v[194:197], v233 offset:56320
	buffer_load_dwordx4 v231, s[16:19], s52 offen lds
	s_add_i32 s52, s51, 0x18080
	s_mov_b32 m0, s65
	s_nop 0
	buffer_load_dwordx4 v231, s[16:19], s52 offen lds
	s_add_i32 s52, s51, 0x30080
	s_mov_b32 m0, s68
	s_add_i32 s51, s51, 0x48080
	buffer_load_dwordx4 v231, s[16:19], s52 offen lds
	s_mov_b32 m0, s69
	s_nop 0
	buffer_load_dwordx4 v231, s[16:19], s51 offen lds
	s_mov_b32 m0, s66
	s_add_i32 s18, s92, 0x40080
	buffer_load_dwordx4 v230, s[12:15], s50 offen lds
	s_mov_b32 m0, s67
	s_nop 0
	buffer_load_dwordx4 v230, s[12:15], s18 offen lds
	s_waitcnt vmcnt(8)
	s_waitcnt lgkmcnt(0)
	s_setprio 1
	v_mfma_f32_16x16x32_bf16 v[66:69], v[134:137], v[166:169], v[66:69]
	v_mfma_f32_16x16x32_bf16 v[62:65], v[142:145], v[166:169], v[62:65]
	s_barrier
	v_mfma_f32_16x16x32_bf16 v[50:53], v[134:137], v[174:177], v[50:53]
	v_mfma_f32_16x16x32_bf16 v[46:49], v[142:145], v[174:177], v[46:49]
	v_mfma_f32_16x16x32_bf16 v[34:37], v[134:137], v[182:185], v[34:37]
	v_mfma_f32_16x16x32_bf16 v[30:33], v[142:145], v[182:185], v[30:33]
	v_mfma_f32_16x16x32_bf16 v[18:21], v[134:137], v[190:193], v[18:21]
	v_mfma_f32_16x16x32_bf16 v[14:17], v[142:145], v[190:193], v[14:17]
	v_mfma_f32_16x16x32_bf16 v[58:61], v[150:153], v[166:169], v[58:61]
	v_mfma_f32_16x16x32_bf16 v[54:57], v[158:161], v[166:169], v[54:57]
	v_mfma_f32_16x16x32_bf16 v[42:45], v[150:153], v[174:177], v[42:45]
	v_mfma_f32_16x16x32_bf16 v[38:41], v[158:161], v[174:177], v[38:41]
	v_mfma_f32_16x16x32_bf16 v[26:29], v[150:153], v[182:185], v[26:29]
	v_mfma_f32_16x16x32_bf16 v[22:25], v[158:161], v[182:185], v[22:25]
	v_mfma_f32_16x16x32_bf16 v[8:11], v[150:153], v[190:193], v[10:13]
	v_mfma_f32_16x16x32_bf16 v[4:7], v[158:161], v[190:193], v[4:7]
	v_mfma_f32_16x16x32_bf16 v[66:69], v[138:141], v[170:173], v[66:69]
	v_mfma_f32_16x16x32_bf16 v[62:65], v[146:149], v[170:173], v[62:65]
	v_mfma_f32_16x16x32_bf16 v[50:53], v[138:141], v[178:181], v[50:53]
	v_mfma_f32_16x16x32_bf16 v[46:49], v[146:149], v[178:181], v[46:49]
	v_mfma_f32_16x16x32_bf16 v[34:37], v[138:141], v[186:189], v[34:37]
	v_mfma_f32_16x16x32_bf16 v[30:33], v[146:149], v[186:189], v[30:33]
	v_mfma_f32_16x16x32_bf16 v[18:21], v[138:141], v[194:197], v[18:21]
	v_mfma_f32_16x16x32_bf16 v[14:17], v[146:149], v[194:197], v[14:17]
	v_mfma_f32_16x16x32_bf16 v[58:61], v[154:157], v[170:173], v[58:61]
	v_mfma_f32_16x16x32_bf16 v[54:57], v[162:165], v[170:173], v[54:57]
	v_mfma_f32_16x16x32_bf16 v[42:45], v[154:157], v[178:181], v[42:45]
	v_mfma_f32_16x16x32_bf16 v[38:41], v[162:165], v[178:181], v[38:41]
	v_mfma_f32_16x16x32_bf16 v[26:29], v[154:157], v[186:189], v[26:29]
	v_mfma_f32_16x16x32_bf16 v[22:25], v[162:165], v[186:189], v[22:25]
	v_mfma_f32_16x16x32_bf16 v[10:13], v[154:157], v[194:197], v[8:11]
	v_mfma_f32_16x16x32_bf16 v[6:9], v[162:165], v[194:197], v[4:7]
	s_setprio 0
	s_barrier
	s_add_i32 s91, s91, 2
	s_addk_i32 s90, 0x100
	s_cmp_ge_i32 s91, s3
	s_cbranch_scc1 .LBB0_1193

.LBB0_1290:
	ds_read_b128 v[106:109], v224
	ds_read_b128 v[118:121], v224 offset:1024
	ds_read_b128 v[130:133], v224 offset:2048
	ds_read_b128 v[138:141], v224 offset:3072
	ds_read_b128 v[146:149], v225
	ds_read_b128 v[150:153], v225 offset:1024
	ds_read_b128 v[154:157], v225 offset:2048
	ds_read_b128 v[158:161], v225 offset:3072
	s_add_i32 s18, s72, 0xffe80080
	s_cmp_eq_u32 s56, s74
	s_cselect_b32 s75, s6, s18
	s_cselect_b32 s77, s7, s73
	s_or_b32 s76, s75, 0x80
	s_add_i32 s18, s72, 0xfff80000
	s_mov_b32 m0, s57
	ds_read_b128 v[162:165], v226
	ds_read_b128 v[166:169], v226 offset:1024
	ds_read_b128 v[170:173], v226 offset:2048
	ds_read_b128 v[174:177], v226 offset:3072
	ds_read_b128 v[178:181], v226 offset:4096
	ds_read_b128 v[182:185], v226 offset:5120
	ds_read_b128 v[190:193], v226 offset:6144
	ds_read_b128 v[194:197], v226 offset:7168
	buffer_load_dwordx4 v222, s[12:15], s18 offen lds
	s_mov_b32 m0, s60
	s_nop 0
	buffer_load_dwordx4 v222, s[12:15], s72 offen lds
	s_waitcnt vmcnt(8)
	s_waitcnt lgkmcnt(0)
	s_setprio 1
	v_mfma_f32_16x16x32_bf16 v[142:145], v[106:109], v[162:165], v[142:145]
	v_mfma_f32_16x16x32_bf16 v[142:145], v[118:121], v[166:169], v[142:145]
	s_barrier
	v_mfma_f32_16x16x32_bf16 v[134:137], v[130:133], v[162:165], v[134:137]
	v_mfma_f32_16x16x32_bf16 v[134:137], v[138:141], v[166:169], v[134:137]
	v_mfma_f32_16x16x32_bf16 v[126:129], v[146:149], v[162:165], v[126:129]
	v_mfma_f32_16x16x32_bf16 v[126:129], v[150:153], v[166:169], v[126:129]
	v_mfma_f32_16x16x32_bf16 v[122:125], v[154:157], v[162:165], v[122:125]
	v_mfma_f32_16x16x32_bf16 v[122:125], v[158:161], v[166:169], v[122:125]
	v_mfma_f32_16x16x32_bf16 v[98:101], v[154:157], v[170:173], v[98:101]
	v_mfma_f32_16x16x32_bf16 v[98:101], v[158:161], v[174:177], v[98:101]
	v_mfma_f32_16x16x32_bf16 v[102:105], v[146:149], v[170:173], v[102:105]
	v_mfma_f32_16x16x32_bf16 v[102:105], v[150:153], v[174:177], v[102:105]
	v_mfma_f32_16x16x32_bf16 v[110:113], v[130:133], v[170:173], v[110:113]
	v_mfma_f32_16x16x32_bf16 v[110:113], v[138:141], v[174:177], v[110:113]
	v_mfma_f32_16x16x32_bf16 v[114:117], v[106:109], v[170:173], v[114:117]
	v_mfma_f32_16x16x32_bf16 v[114:117], v[118:121], v[174:177], v[114:117]
	v_mfma_f32_16x16x32_bf16 v[94:97], v[106:109], v[178:181], v[94:97]
	v_mfma_f32_16x16x32_bf16 v[94:97], v[118:121], v[182:185], v[94:97]
	v_mfma_f32_16x16x32_bf16 v[90:93], v[130:133], v[178:181], v[90:93]
	v_mfma_f32_16x16x32_bf16 v[90:93], v[138:141], v[182:185], v[90:93]
	v_mfma_f32_16x16x32_bf16 v[86:89], v[146:149], v[178:181], v[86:89]
	v_mfma_f32_16x16x32_bf16 v[86:89], v[150:153], v[182:185], v[86:89]
	v_mfma_f32_16x16x32_bf16 v[82:85], v[154:157], v[178:181], v[82:85]
	v_mfma_f32_16x16x32_bf16 v[82:85], v[158:161], v[182:185], v[82:85]
	v_mfma_f32_16x16x32_bf16 v[66:69], v[154:157], v[190:193], v[66:69]
	v_mfma_f32_16x16x32_bf16 v[66:69], v[158:161], v[194:197], v[66:69]
	v_mfma_f32_16x16x32_bf16 v[70:73], v[146:149], v[190:193], v[70:73]
	v_mfma_f32_16x16x32_bf16 v[70:73], v[150:153], v[194:197], v[70:73]
	v_mfma_f32_16x16x32_bf16 v[74:77], v[130:133], v[190:193], v[74:77]
	v_mfma_f32_16x16x32_bf16 v[74:77], v[138:141], v[194:197], v[74:77]
	v_mfma_f32_16x16x32_bf16 v[78:81], v[106:109], v[190:193], v[78:81]
	v_mfma_f32_16x16x32_bf16 v[78:81], v[118:121], v[194:197], v[78:81]
	s_setprio 0
	s_barrier
	s_mov_b32 m0, s27
	s_mov_b32 s18, s14
	s_mov_b32 s19, s15
	ds_read_b128 v[162:165], v226 offset:16384
	ds_read_b128 v[166:169], v226 offset:17408
	ds_read_b128 v[170:173], v226 offset:18432
	ds_read_b128 v[174:177], v226 offset:19456
	ds_read_b128 v[178:181], v226 offset:20480
	ds_read_b128 v[182:185], v226 offset:21504
	ds_read_b128 v[190:193], v226 offset:22528
	ds_read_b128 v[194:197], v226 offset:23552
	buffer_load_dwordx4 v223, s[16:19], s77 offen lds
	s_add_i32 s78, s77, 0x80000
	s_mov_b32 m0, s30
	s_nop 0
	buffer_load_dwordx4 v223, s[16:19], s78 offen lds
	s_add_i32 s78, s77, 0x100000
	s_mov_b32 m0, s31
	s_nop 0
	buffer_load_dwordx4 v223, s[16:19], s78 offen lds
	s_add_i32 s78, s77, 0x180000
	s_mov_b32 m0, s41
	s_nop 0
	buffer_load_dwordx4 v223, s[16:19], s78 offen lds
	s_mov_b32 m0, s25
	s_add_i32 s78, s75, 0x80000
	buffer_load_dwordx4 v222, s[12:15], s75 offen lds
	s_mov_b32 m0, s42
	s_nop 0
	buffer_load_dwordx4 v222, s[12:15], s78 offen lds
	s_waitcnt vmcnt(8)
	s_waitcnt lgkmcnt(0)
	s_setprio 1
	v_mfma_f32_16x16x32_bf16 v[62:65], v[106:109], v[162:165], v[62:65]
	v_mfma_f32_16x16x32_bf16 v[62:65], v[118:121], v[166:169], v[62:65]
	s_barrier
	v_mfma_f32_16x16x32_bf16 v[58:61], v[130:133], v[162:165], v[58:61]
	v_mfma_f32_16x16x32_bf16 v[58:61], v[138:141], v[166:169], v[58:61]
	v_mfma_f32_16x16x32_bf16 v[54:57], v[146:149], v[162:165], v[54:57]
	v_mfma_f32_16x16x32_bf16 v[54:57], v[150:153], v[166:169], v[54:57]
	v_mfma_f32_16x16x32_bf16 v[50:53], v[154:157], v[162:165], v[50:53]
	v_mfma_f32_16x16x32_bf16 v[50:53], v[158:161], v[166:169], v[50:53]
	v_mfma_f32_16x16x32_bf16 v[34:37], v[154:157], v[170:173], v[34:37]
	v_mfma_f32_16x16x32_bf16 v[34:37], v[158:161], v[174:177], v[34:37]
	v_mfma_f32_16x16x32_bf16 v[38:41], v[146:149], v[170:173], v[38:41]
	v_mfma_f32_16x16x32_bf16 v[38:41], v[150:153], v[174:177], v[38:41]
	v_mfma_f32_16x16x32_bf16 v[42:45], v[130:133], v[170:173], v[42:45]
	v_mfma_f32_16x16x32_bf16 v[42:45], v[138:141], v[174:177], v[42:45]
	v_mfma_f32_16x16x32_bf16 v[46:49], v[106:109], v[170:173], v[46:49]
	v_mfma_f32_16x16x32_bf16 v[46:49], v[118:121], v[174:177], v[46:49]
	v_mfma_f32_16x16x32_bf16 v[30:33], v[106:109], v[178:181], v[30:33]
	v_mfma_f32_16x16x32_bf16 v[30:33], v[118:121], v[182:185], v[30:33]
	v_mfma_f32_16x16x32_bf16 v[26:29], v[130:133], v[178:181], v[26:29]
	v_mfma_f32_16x16x32_bf16 v[26:29], v[138:141], v[182:185], v[26:29]
	v_mfma_f32_16x16x32_bf16 v[22:25], v[146:149], v[178:181], v[22:25]
	v_mfma_f32_16x16x32_bf16 v[22:25], v[150:153], v[182:185], v[22:25]
	v_mfma_f32_16x16x32_bf16 v[18:21], v[154:157], v[178:181], v[18:21]
	v_mfma_f32_16x16x32_bf16 v[18:21], v[158:161], v[182:185], v[18:21]
	v_mfma_f32_16x16x32_bf16 v[2:5], v[154:157], v[190:193], v[2:5]
	v_mfma_f32_16x16x32_bf16 v[2:5], v[158:161], v[194:197], v[2:5]
	v_mfma_f32_16x16x32_bf16 v[6:9], v[146:149], v[190:193], v[6:9]
	v_mfma_f32_16x16x32_bf16 v[6:9], v[150:153], v[194:197], v[6:9]
	v_mfma_f32_16x16x32_bf16 v[10:13], v[130:133], v[190:193], v[10:13]
	v_mfma_f32_16x16x32_bf16 v[10:13], v[138:141], v[194:197], v[10:13]
	v_mfma_f32_16x16x32_bf16 v[14:17], v[106:109], v[190:193], v[14:17]
	v_mfma_f32_16x16x32_bf16 v[14:17], v[118:121], v[194:197], v[14:17]
	s_setprio 0
	s_barrier
	ds_read_b128 v[106:109], v227
	ds_read_b128 v[118:121], v227 offset:1024
	ds_read_b128 v[130:133], v227 offset:2048
	ds_read_b128 v[138:141], v227 offset:3072
	ds_read_b128 v[146:149], v228
	ds_read_b128 v[150:153], v228 offset:1024
	ds_read_b128 v[154:157], v228 offset:2048
	ds_read_b128 v[158:161], v228 offset:3072
	s_mov_b32 m0, s43
	s_add_i32 s78, s75, 0x100000
	ds_read_b128 v[162:165], v226 offset:32768
	ds_read_b128 v[166:169], v226 offset:33792
	ds_read_b128 v[170:173], v226 offset:34816
	ds_read_b128 v[174:177], v226 offset:35840
	ds_read_b128 v[178:181], v226 offset:36864
	ds_read_b128 v[182:185], v226 offset:37888
	ds_read_b128 v[190:193], v226 offset:38912
	ds_read_b128 v[194:197], v226 offset:39936
	buffer_load_dwordx4 v222, s[12:15], s78 offen lds
	s_add_i32 s78, s75, 0x180000
	s_mov_b32 m0, s44
	s_nop 0
	buffer_load_dwordx4 v222, s[12:15], s78 offen lds
	s_waitcnt vmcnt(8)
	s_waitcnt lgkmcnt(0)
	s_setprio 1
	v_mfma_f32_16x16x32_bf16 v[142:145], v[106:109], v[162:165], v[142:145]
	v_mfma_f32_16x16x32_bf16 v[142:145], v[118:121], v[166:169], v[142:145]
	s_barrier
	v_mfma_f32_16x16x32_bf16 v[134:137], v[130:133], v[162:165], v[134:137]
	v_mfma_f32_16x16x32_bf16 v[134:137], v[138:141], v[166:169], v[134:137]
	v_mfma_f32_16x16x32_bf16 v[126:129], v[146:149], v[162:165], v[126:129]
	v_mfma_f32_16x16x32_bf16 v[126:129], v[150:153], v[166:169], v[126:129]
	v_mfma_f32_16x16x32_bf16 v[122:125], v[154:157], v[162:165], v[122:125]
	v_mfma_f32_16x16x32_bf16 v[122:125], v[158:161], v[166:169], v[122:125]
	v_mfma_f32_16x16x32_bf16 v[98:101], v[154:157], v[170:173], v[98:101]
	v_mfma_f32_16x16x32_bf16 v[98:101], v[158:161], v[174:177], v[98:101]
	v_mfma_f32_16x16x32_bf16 v[102:105], v[146:149], v[170:173], v[102:105]
	v_mfma_f32_16x16x32_bf16 v[102:105], v[150:153], v[174:177], v[102:105]
	v_mfma_f32_16x16x32_bf16 v[110:113], v[130:133], v[170:173], v[110:113]
	v_mfma_f32_16x16x32_bf16 v[110:113], v[138:141], v[174:177], v[110:113]
	v_mfma_f32_16x16x32_bf16 v[114:117], v[106:109], v[170:173], v[114:117]
	v_mfma_f32_16x16x32_bf16 v[114:117], v[118:121], v[174:177], v[114:117]
	v_mfma_f32_16x16x32_bf16 v[94:97], v[106:109], v[178:181], v[94:97]
	v_mfma_f32_16x16x32_bf16 v[94:97], v[118:121], v[182:185], v[94:97]
	v_mfma_f32_16x16x32_bf16 v[90:93], v[130:133], v[178:181], v[90:93]
	v_mfma_f32_16x16x32_bf16 v[90:93], v[138:141], v[182:185], v[90:93]
	v_mfma_f32_16x16x32_bf16 v[86:89], v[146:149], v[178:181], v[86:89]
	v_mfma_f32_16x16x32_bf16 v[86:89], v[150:153], v[182:185], v[86:89]
	v_mfma_f32_16x16x32_bf16 v[82:85], v[154:157], v[178:181], v[82:85]
	v_mfma_f32_16x16x32_bf16 v[82:85], v[158:161], v[182:185], v[82:85]
	v_mfma_f32_16x16x32_bf16 v[66:69], v[154:157], v[190:193], v[66:69]
	v_mfma_f32_16x16x32_bf16 v[66:69], v[158:161], v[194:197], v[66:69]
	v_mfma_f32_16x16x32_bf16 v[70:73], v[146:149], v[190:193], v[70:73]
	v_mfma_f32_16x16x32_bf16 v[70:73], v[150:153], v[194:197], v[70:73]
	v_mfma_f32_16x16x32_bf16 v[74:77], v[130:133], v[190:193], v[74:77]
	v_mfma_f32_16x16x32_bf16 v[74:77], v[138:141], v[194:197], v[74:77]
	v_mfma_f32_16x16x32_bf16 v[78:81], v[106:109], v[190:193], v[78:81]
	v_mfma_f32_16x16x32_bf16 v[78:81], v[118:121], v[194:197], v[78:81]
	s_setprio 0
	s_barrier
	s_mov_b32 m0, s48
	s_or_b32 s78, s77, 0x80
	ds_read_b128 v[162:165], v226 offset:49152
	ds_read_b128 v[166:169], v226 offset:50176
	ds_read_b128 v[170:173], v226 offset:51200
	ds_read_b128 v[174:177], v226 offset:52224
	ds_read_b128 v[178:181], v226 offset:53248
	ds_read_b128 v[182:185], v226 offset:54272
	ds_read_b128 v[190:193], v226 offset:55296
	ds_read_b128 v[194:197], v226 offset:56320
	buffer_load_dwordx4 v223, s[16:19], s78 offen lds
	s_add_i32 s78, s77, 0x80080
	s_mov_b32 m0, s49
	s_add_i32 s75, s75, 0x80080
	buffer_load_dwordx4 v223, s[16:19], s78 offen lds
	s_add_i32 s78, s77, 0x100080
	s_mov_b32 m0, s52
	s_add_i32 s77, s77, 0x180080
	buffer_load_dwordx4 v223, s[16:19], s78 offen lds
	s_mov_b32 m0, s53
	s_nop 0
	buffer_load_dwordx4 v223, s[16:19], s77 offen lds
	s_mov_b32 m0, s50
	s_nop 0
	buffer_load_dwordx4 v222, s[12:15], s76 offen lds
	s_mov_b32 m0, s51
	s_nop 0
	buffer_load_dwordx4 v222, s[12:15], s75 offen lds
	s_waitcnt vmcnt(8)
	s_waitcnt lgkmcnt(0)
	s_setprio 1
	v_mfma_f32_16x16x32_bf16 v[62:65], v[106:109], v[162:165], v[62:65]
	v_mfma_f32_16x16x32_bf16 v[62:65], v[118:121], v[166:169], v[62:65]
	s_barrier
	v_mfma_f32_16x16x32_bf16 v[58:61], v[130:133], v[162:165], v[58:61]
	v_mfma_f32_16x16x32_bf16 v[58:61], v[138:141], v[166:169], v[58:61]
	v_mfma_f32_16x16x32_bf16 v[54:57], v[146:149], v[162:165], v[54:57]
	v_mfma_f32_16x16x32_bf16 v[54:57], v[150:153], v[166:169], v[54:57]
	v_mfma_f32_16x16x32_bf16 v[50:53], v[154:157], v[162:165], v[50:53]
	v_mfma_f32_16x16x32_bf16 v[50:53], v[158:161], v[166:169], v[50:53]
	v_mfma_f32_16x16x32_bf16 v[34:37], v[154:157], v[170:173], v[34:37]
	v_mfma_f32_16x16x32_bf16 v[34:37], v[158:161], v[174:177], v[34:37]
	v_mfma_f32_16x16x32_bf16 v[38:41], v[146:149], v[170:173], v[38:41]
	v_mfma_f32_16x16x32_bf16 v[38:41], v[150:153], v[174:177], v[38:41]
	v_mfma_f32_16x16x32_bf16 v[42:45], v[130:133], v[170:173], v[42:45]
	v_mfma_f32_16x16x32_bf16 v[42:45], v[138:141], v[174:177], v[42:45]
	v_mfma_f32_16x16x32_bf16 v[46:49], v[106:109], v[170:173], v[46:49]
	v_mfma_f32_16x16x32_bf16 v[46:49], v[118:121], v[174:177], v[46:49]
	v_mfma_f32_16x16x32_bf16 v[30:33], v[106:109], v[178:181], v[30:33]
	v_mfma_f32_16x16x32_bf16 v[30:33], v[118:121], v[182:185], v[30:33]
	v_mfma_f32_16x16x32_bf16 v[26:29], v[130:133], v[178:181], v[26:29]
	v_mfma_f32_16x16x32_bf16 v[26:29], v[138:141], v[182:185], v[26:29]
	v_mfma_f32_16x16x32_bf16 v[22:25], v[146:149], v[178:181], v[22:25]
	v_mfma_f32_16x16x32_bf16 v[22:25], v[150:153], v[182:185], v[22:25]
	v_mfma_f32_16x16x32_bf16 v[18:21], v[154:157], v[178:181], v[18:21]
	v_mfma_f32_16x16x32_bf16 v[18:21], v[158:161], v[182:185], v[18:21]
	v_mfma_f32_16x16x32_bf16 v[2:5], v[154:157], v[190:193], v[2:5]
	v_mfma_f32_16x16x32_bf16 v[2:5], v[158:161], v[194:197], v[2:5]
	v_mfma_f32_16x16x32_bf16 v[6:9], v[146:149], v[190:193], v[6:9]
	v_mfma_f32_16x16x32_bf16 v[6:9], v[150:153], v[194:197], v[6:9]
	v_mfma_f32_16x16x32_bf16 v[10:13], v[130:133], v[190:193], v[10:13]
	v_mfma_f32_16x16x32_bf16 v[10:13], v[138:141], v[194:197], v[10:13]
	v_mfma_f32_16x16x32_bf16 v[14:17], v[106:109], v[190:193], v[14:17]
	v_mfma_f32_16x16x32_bf16 v[14:17], v[118:121], v[194:197], v[14:17]
	s_setprio 0
	s_barrier
	s_add_i32 s74, s74, 2
	s_addk_i32 s72, 0x100
	s_addk_i32 s73, 0x100
	s_cmp_ge_i32 s74, s3
	s_cbranch_scc0 .LBB0_1290
	s_and_b64 vcc, exec, s[38:39]
	s_cbranch_vccz .LBB0_1293

.LBB0_1382:
	ds_read_b128 v[144:147], v138
	ds_read_b128 v[148:151], v138 offset:1024
	ds_read_b128 v[152:155], v138 offset:2048
	ds_read_b128 v[156:159], v138 offset:3072
	ds_read_b128 v[160:163], v139
	ds_read_b128 v[164:167], v139 offset:1024
	ds_read_b128 v[168:171], v139 offset:2048
	ds_read_b128 v[172:175], v139 offset:3072
	s_add_i32 s14, s74, 0xffe80080
	s_cmp_eq_u32 s61, s76
	s_cselect_b32 s77, s72, s14
	s_cselect_b32 s79, s73, s75
	s_or_b32 s78, s77, 0x80
	s_add_i32 s14, s74, 0xfff80000
	s_mov_b32 m0, s62
	ds_read_b128 v[176:179], v140
	ds_read_b128 v[180:183], v140 offset:1024
	ds_read_b128 v[184:187], v140 offset:2048
	ds_read_b128 v[188:191], v140 offset:3072
	ds_read_b128 v[192:195], v140 offset:4096
	ds_read_b128 v[196:199], v140 offset:5120
	ds_read_b128 v[200:203], v140 offset:6144
	ds_read_b128 v[204:207], v140 offset:7168
	buffer_load_dwordx4 v136, s[16:19], s14 offen lds
	s_mov_b32 m0, s63
	s_nop 0
	buffer_load_dwordx4 v136, s[16:19], s74 offen lds
	s_waitcnt vmcnt(8)
	s_waitcnt lgkmcnt(0)
	s_setprio 1
	v_mfma_f32_16x16x32_bf16 v[118:121], v[144:147], v[176:179], v[118:121]
	v_mfma_f32_16x16x32_bf16 v[118:121], v[148:151], v[180:183], v[118:121]
	s_barrier
	v_mfma_f32_16x16x32_bf16 v[114:117], v[152:155], v[176:179], v[114:117]
	v_mfma_f32_16x16x32_bf16 v[114:117], v[156:159], v[180:183], v[114:117]
	v_mfma_f32_16x16x32_bf16 v[126:129], v[160:163], v[176:179], v[126:129]
	v_mfma_f32_16x16x32_bf16 v[126:129], v[164:167], v[180:183], v[126:129]
	v_mfma_f32_16x16x32_bf16 v[122:125], v[168:171], v[176:179], v[122:125]
	v_mfma_f32_16x16x32_bf16 v[122:125], v[172:175], v[180:183], v[122:125]
	v_mfma_f32_16x16x32_bf16 v[98:101], v[168:171], v[184:187], v[98:101]
	v_mfma_f32_16x16x32_bf16 v[98:101], v[172:175], v[188:191], v[98:101]
	v_mfma_f32_16x16x32_bf16 v[106:109], v[160:163], v[184:187], v[106:109]
	v_mfma_f32_16x16x32_bf16 v[106:109], v[164:167], v[188:191], v[106:109]
	v_mfma_f32_16x16x32_bf16 v[102:105], v[152:155], v[184:187], v[102:105]
	v_mfma_f32_16x16x32_bf16 v[102:105], v[156:159], v[188:191], v[102:105]
	v_mfma_f32_16x16x32_bf16 v[110:113], v[144:147], v[184:187], v[110:113]
	v_mfma_f32_16x16x32_bf16 v[110:113], v[148:151], v[188:191], v[110:113]
	v_mfma_f32_16x16x32_bf16 v[94:97], v[144:147], v[192:195], v[94:97]
	v_mfma_f32_16x16x32_bf16 v[94:97], v[148:151], v[196:199], v[94:97]
	v_mfma_f32_16x16x32_bf16 v[86:89], v[152:155], v[192:195], v[86:89]
	v_mfma_f32_16x16x32_bf16 v[86:89], v[156:159], v[196:199], v[86:89]
	v_mfma_f32_16x16x32_bf16 v[90:93], v[160:163], v[192:195], v[90:93]
	v_mfma_f32_16x16x32_bf16 v[90:93], v[164:167], v[196:199], v[90:93]
	v_mfma_f32_16x16x32_bf16 v[82:85], v[168:171], v[192:195], v[82:85]
	v_mfma_f32_16x16x32_bf16 v[82:85], v[172:175], v[196:199], v[82:85]
	v_mfma_f32_16x16x32_bf16 v[70:73], v[168:171], v[200:203], v[70:73]
	v_mfma_f32_16x16x32_bf16 v[70:73], v[172:175], v[204:207], v[70:73]
	v_mfma_f32_16x16x32_bf16 v[74:77], v[160:163], v[200:203], v[74:77]
	v_mfma_f32_16x16x32_bf16 v[74:77], v[164:167], v[204:207], v[74:77]
	v_mfma_f32_16x16x32_bf16 v[66:69], v[152:155], v[200:203], v[66:69]
	v_mfma_f32_16x16x32_bf16 v[66:69], v[156:159], v[204:207], v[66:69]
	v_mfma_f32_16x16x32_bf16 v[78:81], v[144:147], v[200:203], v[78:81]
	v_mfma_f32_16x16x32_bf16 v[78:81], v[148:151], v[204:207], v[78:81]
	s_setprio 0
	s_barrier
	s_mov_b32 m0, s45
	s_mov_b32 s14, s18
	s_mov_b32 s15, s19
	ds_read_b128 v[176:179], v140 offset:16384
	ds_read_b128 v[180:183], v140 offset:17408
	ds_read_b128 v[184:187], v140 offset:18432
	ds_read_b128 v[188:191], v140 offset:19456
	ds_read_b128 v[192:195], v140 offset:20480
	ds_read_b128 v[196:199], v140 offset:21504
	ds_read_b128 v[200:203], v140 offset:22528
	ds_read_b128 v[204:207], v140 offset:23552
	buffer_load_dwordx4 v137, s[12:15], s79 offen lds
	s_add_i32 s80, s79, 0x80000
	s_mov_b32 m0, s46
	s_nop 0
	buffer_load_dwordx4 v137, s[12:15], s80 offen lds
	s_add_i32 s80, s79, 0x100000
	s_mov_b32 m0, s47
	s_nop 0
	buffer_load_dwordx4 v137, s[12:15], s80 offen lds
	s_add_i32 s80, s79, 0x180000
	s_mov_b32 m0, s48
	s_nop 0
	buffer_load_dwordx4 v137, s[12:15], s80 offen lds
	s_mov_b32 m0, s44
	s_add_i32 s80, s77, 0x80000
	buffer_load_dwordx4 v136, s[16:19], s77 offen lds
	s_mov_b32 m0, s49
	s_nop 0
	buffer_load_dwordx4 v136, s[16:19], s80 offen lds
	s_waitcnt vmcnt(8)
	s_waitcnt lgkmcnt(0)
	s_setprio 1
	v_mfma_f32_16x16x32_bf16 v[62:65], v[144:147], v[176:179], v[62:65]
	v_mfma_f32_16x16x32_bf16 v[62:65], v[148:151], v[180:183], v[62:65]
	s_barrier
	v_mfma_f32_16x16x32_bf16 v[54:57], v[152:155], v[176:179], v[54:57]
	v_mfma_f32_16x16x32_bf16 v[54:57], v[156:159], v[180:183], v[54:57]
	v_mfma_f32_16x16x32_bf16 v[58:61], v[160:163], v[176:179], v[58:61]
	v_mfma_f32_16x16x32_bf16 v[58:61], v[164:167], v[180:183], v[58:61]
	v_mfma_f32_16x16x32_bf16 v[50:53], v[168:171], v[176:179], v[50:53]
	v_mfma_f32_16x16x32_bf16 v[50:53], v[172:175], v[180:183], v[50:53]
	v_mfma_f32_16x16x32_bf16 v[34:37], v[168:171], v[184:187], v[34:37]
	v_mfma_f32_16x16x32_bf16 v[34:37], v[172:175], v[188:191], v[34:37]
	v_mfma_f32_16x16x32_bf16 v[42:45], v[160:163], v[184:187], v[42:45]
	v_mfma_f32_16x16x32_bf16 v[42:45], v[164:167], v[188:191], v[42:45]
	v_mfma_f32_16x16x32_bf16 v[38:41], v[152:155], v[184:187], v[38:41]
	v_mfma_f32_16x16x32_bf16 v[38:41], v[156:159], v[188:191], v[38:41]
	v_mfma_f32_16x16x32_bf16 v[46:49], v[144:147], v[184:187], v[46:49]
	v_mfma_f32_16x16x32_bf16 v[46:49], v[148:151], v[188:191], v[46:49]
	v_mfma_f32_16x16x32_bf16 v[30:33], v[144:147], v[192:195], v[30:33]
	v_mfma_f32_16x16x32_bf16 v[30:33], v[148:151], v[196:199], v[30:33]
	v_mfma_f32_16x16x32_bf16 v[22:25], v[152:155], v[192:195], v[22:25]
	v_mfma_f32_16x16x32_bf16 v[22:25], v[156:159], v[196:199], v[22:25]
	v_mfma_f32_16x16x32_bf16 v[26:29], v[160:163], v[192:195], v[26:29]
	v_mfma_f32_16x16x32_bf16 v[26:29], v[164:167], v[196:199], v[26:29]
	v_mfma_f32_16x16x32_bf16 v[18:21], v[168:171], v[192:195], v[18:21]
	v_mfma_f32_16x16x32_bf16 v[18:21], v[172:175], v[196:199], v[18:21]
	v_mfma_f32_16x16x32_bf16 v[2:5], v[168:171], v[200:203], v[2:5]
	v_mfma_f32_16x16x32_bf16 v[2:5], v[172:175], v[204:207], v[2:5]
	v_mfma_f32_16x16x32_bf16 v[10:13], v[160:163], v[200:203], v[10:13]
	v_mfma_f32_16x16x32_bf16 v[10:13], v[164:167], v[204:207], v[10:13]
	v_mfma_f32_16x16x32_bf16 v[6:9], v[152:155], v[200:203], v[6:9]
	v_mfma_f32_16x16x32_bf16 v[6:9], v[156:159], v[204:207], v[6:9]
	v_mfma_f32_16x16x32_bf16 v[14:17], v[144:147], v[200:203], v[14:17]
	v_mfma_f32_16x16x32_bf16 v[14:17], v[148:151], v[204:207], v[14:17]
	s_setprio 0
	s_barrier
	ds_read_b128 v[144:147], v141
	ds_read_b128 v[148:151], v141 offset:1024
	ds_read_b128 v[152:155], v141 offset:2048
	ds_read_b128 v[156:159], v141 offset:3072
	ds_read_b128 v[160:163], v142
	ds_read_b128 v[164:167], v142 offset:1024
	ds_read_b128 v[168:171], v142 offset:2048
	ds_read_b128 v[172:175], v142 offset:3072
	s_mov_b32 m0, s50
	s_add_i32 s80, s77, 0x100000
	ds_read_b128 v[176:179], v140 offset:32768
	ds_read_b128 v[180:183], v140 offset:33792
	ds_read_b128 v[184:187], v140 offset:34816
	ds_read_b128 v[188:191], v140 offset:35840
	ds_read_b128 v[192:195], v140 offset:36864
	ds_read_b128 v[196:199], v140 offset:37888
	ds_read_b128 v[200:203], v140 offset:38912
	ds_read_b128 v[204:207], v140 offset:39936
	buffer_load_dwordx4 v136, s[16:19], s80 offen lds
	s_add_i32 s80, s77, 0x180000
	s_mov_b32 m0, s51
	s_nop 0
	buffer_load_dwordx4 v136, s[16:19], s80 offen lds
	s_waitcnt vmcnt(8)
	s_waitcnt lgkmcnt(0)
	s_setprio 1
	v_mfma_f32_16x16x32_bf16 v[118:121], v[144:147], v[176:179], v[118:121]
	v_mfma_f32_16x16x32_bf16 v[118:121], v[148:151], v[180:183], v[118:121]
	s_barrier
	v_mfma_f32_16x16x32_bf16 v[114:117], v[152:155], v[176:179], v[114:117]
	v_mfma_f32_16x16x32_bf16 v[114:117], v[156:159], v[180:183], v[114:117]
	v_mfma_f32_16x16x32_bf16 v[126:129], v[160:163], v[176:179], v[126:129]
	v_mfma_f32_16x16x32_bf16 v[126:129], v[164:167], v[180:183], v[126:129]
	v_mfma_f32_16x16x32_bf16 v[122:125], v[168:171], v[176:179], v[122:125]
	v_mfma_f32_16x16x32_bf16 v[122:125], v[172:175], v[180:183], v[122:125]
	v_mfma_f32_16x16x32_bf16 v[98:101], v[168:171], v[184:187], v[98:101]
	v_mfma_f32_16x16x32_bf16 v[98:101], v[172:175], v[188:191], v[98:101]
	v_mfma_f32_16x16x32_bf16 v[106:109], v[160:163], v[184:187], v[106:109]
	v_mfma_f32_16x16x32_bf16 v[106:109], v[164:167], v[188:191], v[106:109]
	v_mfma_f32_16x16x32_bf16 v[102:105], v[152:155], v[184:187], v[102:105]
	v_mfma_f32_16x16x32_bf16 v[102:105], v[156:159], v[188:191], v[102:105]
	v_mfma_f32_16x16x32_bf16 v[110:113], v[144:147], v[184:187], v[110:113]
	v_mfma_f32_16x16x32_bf16 v[110:113], v[148:151], v[188:191], v[110:113]
	v_mfma_f32_16x16x32_bf16 v[94:97], v[144:147], v[192:195], v[94:97]
	v_mfma_f32_16x16x32_bf16 v[94:97], v[148:151], v[196:199], v[94:97]
	v_mfma_f32_16x16x32_bf16 v[86:89], v[152:155], v[192:195], v[86:89]
	v_mfma_f32_16x16x32_bf16 v[86:89], v[156:159], v[196:199], v[86:89]
	v_mfma_f32_16x16x32_bf16 v[90:93], v[160:163], v[192:195], v[90:93]
	v_mfma_f32_16x16x32_bf16 v[90:93], v[164:167], v[196:199], v[90:93]
	v_mfma_f32_16x16x32_bf16 v[82:85], v[168:171], v[192:195], v[82:85]
	v_mfma_f32_16x16x32_bf16 v[82:85], v[172:175], v[196:199], v[82:85]
	v_mfma_f32_16x16x32_bf16 v[70:73], v[168:171], v[200:203], v[70:73]
	v_mfma_f32_16x16x32_bf16 v[70:73], v[172:175], v[204:207], v[70:73]
	v_mfma_f32_16x16x32_bf16 v[74:77], v[160:163], v[200:203], v[74:77]
	v_mfma_f32_16x16x32_bf16 v[74:77], v[164:167], v[204:207], v[74:77]
	v_mfma_f32_16x16x32_bf16 v[66:69], v[152:155], v[200:203], v[66:69]
	v_mfma_f32_16x16x32_bf16 v[66:69], v[156:159], v[204:207], v[66:69]
	v_mfma_f32_16x16x32_bf16 v[78:81], v[144:147], v[200:203], v[78:81]
	v_mfma_f32_16x16x32_bf16 v[78:81], v[148:151], v[204:207], v[78:81]
	s_setprio 0
	s_barrier
	s_mov_b32 m0, s53
	s_or_b32 s80, s79, 0x80
	ds_read_b128 v[176:179], v140 offset:49152
	ds_read_b128 v[180:183], v140 offset:50176
	ds_read_b128 v[184:187], v140 offset:51200
	ds_read_b128 v[188:191], v140 offset:52224
	ds_read_b128 v[192:195], v140 offset:53248
	ds_read_b128 v[196:199], v140 offset:54272
	ds_read_b128 v[200:203], v140 offset:55296
	ds_read_b128 v[204:207], v140 offset:56320
	buffer_load_dwordx4 v137, s[12:15], s80 offen lds
	s_add_i32 s80, s79, 0x80080
	s_mov_b32 m0, s54
	s_add_i32 s77, s77, 0x80080
	buffer_load_dwordx4 v137, s[12:15], s80 offen lds
	s_add_i32 s80, s79, 0x100080
	s_mov_b32 m0, s57
	s_add_i32 s79, s79, 0x180080
	buffer_load_dwordx4 v137, s[12:15], s80 offen lds
	s_mov_b32 m0, s58
	s_nop 0
	buffer_load_dwordx4 v137, s[12:15], s79 offen lds
	s_mov_b32 m0, s55
	s_nop 0
	buffer_load_dwordx4 v136, s[16:19], s78 offen lds
	s_mov_b32 m0, s56
	s_nop 0
	buffer_load_dwordx4 v136, s[16:19], s77 offen lds
	s_waitcnt vmcnt(8)
	s_waitcnt lgkmcnt(0)
	s_setprio 1
	v_mfma_f32_16x16x32_bf16 v[62:65], v[144:147], v[176:179], v[62:65]
	v_mfma_f32_16x16x32_bf16 v[62:65], v[148:151], v[180:183], v[62:65]
	s_barrier
	v_mfma_f32_16x16x32_bf16 v[54:57], v[152:155], v[176:179], v[54:57]
	v_mfma_f32_16x16x32_bf16 v[54:57], v[156:159], v[180:183], v[54:57]
	v_mfma_f32_16x16x32_bf16 v[58:61], v[160:163], v[176:179], v[58:61]
	v_mfma_f32_16x16x32_bf16 v[58:61], v[164:167], v[180:183], v[58:61]
	v_mfma_f32_16x16x32_bf16 v[50:53], v[168:171], v[176:179], v[50:53]
	v_mfma_f32_16x16x32_bf16 v[50:53], v[172:175], v[180:183], v[50:53]
	v_mfma_f32_16x16x32_bf16 v[34:37], v[168:171], v[184:187], v[34:37]
	v_mfma_f32_16x16x32_bf16 v[34:37], v[172:175], v[188:191], v[34:37]
	v_mfma_f32_16x16x32_bf16 v[42:45], v[160:163], v[184:187], v[42:45]
	v_mfma_f32_16x16x32_bf16 v[42:45], v[164:167], v[188:191], v[42:45]
	v_mfma_f32_16x16x32_bf16 v[38:41], v[152:155], v[184:187], v[38:41]
	v_mfma_f32_16x16x32_bf16 v[38:41], v[156:159], v[188:191], v[38:41]
	v_mfma_f32_16x16x32_bf16 v[46:49], v[144:147], v[184:187], v[46:49]
	v_mfma_f32_16x16x32_bf16 v[46:49], v[148:151], v[188:191], v[46:49]
	v_mfma_f32_16x16x32_bf16 v[30:33], v[144:147], v[192:195], v[30:33]
	v_mfma_f32_16x16x32_bf16 v[30:33], v[148:151], v[196:199], v[30:33]
	v_mfma_f32_16x16x32_bf16 v[22:25], v[152:155], v[192:195], v[22:25]
	v_mfma_f32_16x16x32_bf16 v[22:25], v[156:159], v[196:199], v[22:25]
	v_mfma_f32_16x16x32_bf16 v[26:29], v[160:163], v[192:195], v[26:29]
	v_mfma_f32_16x16x32_bf16 v[26:29], v[164:167], v[196:199], v[26:29]
	v_mfma_f32_16x16x32_bf16 v[18:21], v[168:171], v[192:195], v[18:21]
	v_mfma_f32_16x16x32_bf16 v[18:21], v[172:175], v[196:199], v[18:21]
	v_mfma_f32_16x16x32_bf16 v[2:5], v[168:171], v[200:203], v[2:5]
	v_mfma_f32_16x16x32_bf16 v[2:5], v[172:175], v[204:207], v[2:5]
	v_mfma_f32_16x16x32_bf16 v[10:13], v[160:163], v[200:203], v[10:13]
	v_mfma_f32_16x16x32_bf16 v[10:13], v[164:167], v[204:207], v[10:13]
	v_mfma_f32_16x16x32_bf16 v[6:9], v[152:155], v[200:203], v[6:9]
	v_mfma_f32_16x16x32_bf16 v[6:9], v[156:159], v[204:207], v[6:9]
	v_mfma_f32_16x16x32_bf16 v[14:17], v[144:147], v[200:203], v[14:17]
	v_mfma_f32_16x16x32_bf16 v[14:17], v[148:151], v[204:207], v[14:17]
	s_setprio 0
	s_barrier
	s_add_i32 s76, s76, 2
	s_addk_i32 s74, 0x100
	s_addk_i32 s75, 0x100
	s_cmp_ge_i32 s76, s27
	s_cbranch_scc0 .LBB0_1382
	s_and_b64 vcc, exec, s[42:43]
	s_cbranch_vccz .LBB0_1385

.LBB0_1402:
	ds_read_b128 v[146:149], v138
	ds_read_b128 v[150:153], v138 offset:1024
	ds_read_b128 v[154:157], v138 offset:2048
	ds_read_b128 v[158:161], v138 offset:3072
	ds_read_b128 v[162:165], v139
	ds_read_b128 v[166:169], v139 offset:1024
	ds_read_b128 v[170:173], v139 offset:2048
	ds_read_b128 v[174:177], v139 offset:3072
	s_add_i32 s22, s75, 0xffe80080
	s_cmp_eq_u32 s62, s77
	s_cselect_b32 s78, s73, s22
	s_cselect_b32 s80, s74, s76
	s_or_b32 s79, s78, 0x80
	s_add_i32 s22, s75, 0xfff80000
	s_mov_b32 m0, s63
	ds_read_b128 v[178:181], v140
	ds_read_b128 v[182:185], v140 offset:1024
	ds_read_b128 v[186:189], v140 offset:2048
	ds_read_b128 v[190:193], v140 offset:3072
	ds_read_b128 v[194:197], v140 offset:4096
	ds_read_b128 v[198:201], v140 offset:5120
	ds_read_b128 v[202:205], v140 offset:6144
	ds_read_b128 v[206:209], v140 offset:7168
	buffer_load_dwordx4 v136, s[16:19], s22 offen lds
	s_mov_b32 m0, s64
	s_nop 0
	buffer_load_dwordx4 v136, s[16:19], s75 offen lds
	s_waitcnt vmcnt(8)
	s_waitcnt lgkmcnt(0)
	s_setprio 1
	v_mfma_f32_16x16x32_bf16 v[118:121], v[146:149], v[178:181], v[118:121]
	v_mfma_f32_16x16x32_bf16 v[118:121], v[150:153], v[182:185], v[118:121]
	s_barrier
	v_mfma_f32_16x16x32_bf16 v[114:117], v[154:157], v[178:181], v[114:117]
	v_mfma_f32_16x16x32_bf16 v[114:117], v[158:161], v[182:185], v[114:117]
	v_mfma_f32_16x16x32_bf16 v[126:129], v[162:165], v[178:181], v[126:129]
	v_mfma_f32_16x16x32_bf16 v[126:129], v[166:169], v[182:185], v[126:129]
	v_mfma_f32_16x16x32_bf16 v[122:125], v[170:173], v[178:181], v[122:125]
	v_mfma_f32_16x16x32_bf16 v[122:125], v[174:177], v[182:185], v[122:125]
	v_mfma_f32_16x16x32_bf16 v[98:101], v[170:173], v[186:189], v[98:101]
	v_mfma_f32_16x16x32_bf16 v[98:101], v[174:177], v[190:193], v[98:101]
	v_mfma_f32_16x16x32_bf16 v[106:109], v[162:165], v[186:189], v[106:109]
	v_mfma_f32_16x16x32_bf16 v[106:109], v[166:169], v[190:193], v[106:109]
	v_mfma_f32_16x16x32_bf16 v[102:105], v[154:157], v[186:189], v[102:105]
	v_mfma_f32_16x16x32_bf16 v[102:105], v[158:161], v[190:193], v[102:105]
	v_mfma_f32_16x16x32_bf16 v[110:113], v[146:149], v[186:189], v[110:113]
	v_mfma_f32_16x16x32_bf16 v[110:113], v[150:153], v[190:193], v[110:113]
	v_mfma_f32_16x16x32_bf16 v[94:97], v[146:149], v[194:197], v[94:97]
	v_mfma_f32_16x16x32_bf16 v[94:97], v[150:153], v[198:201], v[94:97]
	v_mfma_f32_16x16x32_bf16 v[86:89], v[154:157], v[194:197], v[86:89]
	v_mfma_f32_16x16x32_bf16 v[86:89], v[158:161], v[198:201], v[86:89]
	v_mfma_f32_16x16x32_bf16 v[90:93], v[162:165], v[194:197], v[90:93]
	v_mfma_f32_16x16x32_bf16 v[90:93], v[166:169], v[198:201], v[90:93]
	v_mfma_f32_16x16x32_bf16 v[82:85], v[170:173], v[194:197], v[82:85]
	v_mfma_f32_16x16x32_bf16 v[82:85], v[174:177], v[198:201], v[82:85]
	v_mfma_f32_16x16x32_bf16 v[70:73], v[170:173], v[202:205], v[70:73]
	v_mfma_f32_16x16x32_bf16 v[70:73], v[174:177], v[206:209], v[70:73]
	v_mfma_f32_16x16x32_bf16 v[74:77], v[162:165], v[202:205], v[74:77]
	v_mfma_f32_16x16x32_bf16 v[74:77], v[166:169], v[206:209], v[74:77]
	v_mfma_f32_16x16x32_bf16 v[66:69], v[154:157], v[202:205], v[66:69]
	v_mfma_f32_16x16x32_bf16 v[66:69], v[158:161], v[206:209], v[66:69]
	v_mfma_f32_16x16x32_bf16 v[78:81], v[146:149], v[202:205], v[78:81]
	v_mfma_f32_16x16x32_bf16 v[78:81], v[150:153], v[206:209], v[78:81]
	s_setprio 0
	s_barrier
	s_mov_b32 m0, s31
	s_mov_b32 s22, s18
	s_mov_b32 s23, s19
	ds_read_b128 v[178:181], v140 offset:16384
	ds_read_b128 v[182:185], v140 offset:17408
	ds_read_b128 v[186:189], v140 offset:18432
	ds_read_b128 v[190:193], v140 offset:19456
	ds_read_b128 v[194:197], v140 offset:20480
	ds_read_b128 v[198:201], v140 offset:21504
	ds_read_b128 v[202:205], v140 offset:22528
	ds_read_b128 v[206:209], v140 offset:23552
	buffer_load_dwordx4 v137, s[20:23], s80 offen lds
	s_add_i32 s81, s80, 0x80000
	s_mov_b32 m0, s48
	s_nop 0
	buffer_load_dwordx4 v137, s[20:23], s81 offen lds
	s_add_i32 s81, s80, 0x100000
	s_mov_b32 m0, s49
	s_nop 0
	buffer_load_dwordx4 v137, s[20:23], s81 offen lds
	s_add_i32 s81, s80, 0x180000
	s_mov_b32 m0, s50
	s_nop 0
	buffer_load_dwordx4 v137, s[20:23], s81 offen lds
	s_mov_b32 m0, s30
	s_add_i32 s81, s78, 0x80000
	buffer_load_dwordx4 v136, s[16:19], s78 offen lds
	s_mov_b32 m0, s51
	s_nop 0
	buffer_load_dwordx4 v136, s[16:19], s81 offen lds
	s_waitcnt vmcnt(8)
	s_waitcnt lgkmcnt(0)
	s_setprio 1
	v_mfma_f32_16x16x32_bf16 v[62:65], v[146:149], v[178:181], v[62:65]
	v_mfma_f32_16x16x32_bf16 v[62:65], v[150:153], v[182:185], v[62:65]
	s_barrier
	v_mfma_f32_16x16x32_bf16 v[54:57], v[154:157], v[178:181], v[54:57]
	v_mfma_f32_16x16x32_bf16 v[54:57], v[158:161], v[182:185], v[54:57]
	v_mfma_f32_16x16x32_bf16 v[58:61], v[162:165], v[178:181], v[58:61]
	v_mfma_f32_16x16x32_bf16 v[58:61], v[166:169], v[182:185], v[58:61]
	v_mfma_f32_16x16x32_bf16 v[50:53], v[170:173], v[178:181], v[50:53]
	v_mfma_f32_16x16x32_bf16 v[50:53], v[174:177], v[182:185], v[50:53]
	v_mfma_f32_16x16x32_bf16 v[34:37], v[170:173], v[186:189], v[34:37]
	v_mfma_f32_16x16x32_bf16 v[34:37], v[174:177], v[190:193], v[34:37]
	v_mfma_f32_16x16x32_bf16 v[42:45], v[162:165], v[186:189], v[42:45]
	v_mfma_f32_16x16x32_bf16 v[42:45], v[166:169], v[190:193], v[42:45]
	v_mfma_f32_16x16x32_bf16 v[38:41], v[154:157], v[186:189], v[38:41]
	v_mfma_f32_16x16x32_bf16 v[38:41], v[158:161], v[190:193], v[38:41]
	v_mfma_f32_16x16x32_bf16 v[46:49], v[146:149], v[186:189], v[46:49]
	v_mfma_f32_16x16x32_bf16 v[46:49], v[150:153], v[190:193], v[46:49]
	v_mfma_f32_16x16x32_bf16 v[30:33], v[146:149], v[194:197], v[30:33]
	v_mfma_f32_16x16x32_bf16 v[30:33], v[150:153], v[198:201], v[30:33]
	v_mfma_f32_16x16x32_bf16 v[22:25], v[154:157], v[194:197], v[22:25]
	v_mfma_f32_16x16x32_bf16 v[22:25], v[158:161], v[198:201], v[22:25]
	v_mfma_f32_16x16x32_bf16 v[26:29], v[162:165], v[194:197], v[26:29]
	v_mfma_f32_16x16x32_bf16 v[26:29], v[166:169], v[198:201], v[26:29]
	v_mfma_f32_16x16x32_bf16 v[18:21], v[170:173], v[194:197], v[18:21]
	v_mfma_f32_16x16x32_bf16 v[18:21], v[174:177], v[198:201], v[18:21]
	v_mfma_f32_16x16x32_bf16 v[2:5], v[170:173], v[202:205], v[2:5]
	v_mfma_f32_16x16x32_bf16 v[2:5], v[174:177], v[206:209], v[2:5]
	v_mfma_f32_16x16x32_bf16 v[10:13], v[162:165], v[202:205], v[10:13]
	v_mfma_f32_16x16x32_bf16 v[10:13], v[166:169], v[206:209], v[10:13]
	v_mfma_f32_16x16x32_bf16 v[6:9], v[154:157], v[202:205], v[6:9]
	v_mfma_f32_16x16x32_bf16 v[6:9], v[158:161], v[206:209], v[6:9]
	v_mfma_f32_16x16x32_bf16 v[14:17], v[146:149], v[202:205], v[14:17]
	v_mfma_f32_16x16x32_bf16 v[14:17], v[150:153], v[206:209], v[14:17]
	s_setprio 0
	s_barrier
	ds_read_b128 v[146:149], v141
	ds_read_b128 v[150:153], v141 offset:1024
	ds_read_b128 v[154:157], v141 offset:2048
	ds_read_b128 v[158:161], v141 offset:3072
	ds_read_b128 v[162:165], v142
	ds_read_b128 v[166:169], v142 offset:1024
	ds_read_b128 v[170:173], v142 offset:2048
	ds_read_b128 v[174:177], v142 offset:3072
	s_mov_b32 m0, s52
	s_add_i32 s81, s78, 0x100000
	ds_read_b128 v[178:181], v140 offset:32768
	ds_read_b128 v[182:185], v140 offset:33792
	ds_read_b128 v[186:189], v140 offset:34816
	ds_read_b128 v[190:193], v140 offset:35840
	ds_read_b128 v[194:197], v140 offset:36864
	ds_read_b128 v[198:201], v140 offset:37888
	ds_read_b128 v[202:205], v140 offset:38912
	ds_read_b128 v[206:209], v140 offset:39936
	buffer_load_dwordx4 v136, s[16:19], s81 offen lds
	s_add_i32 s81, s78, 0x180000
	s_mov_b32 m0, s53
	s_nop 0
	buffer_load_dwordx4 v136, s[16:19], s81 offen lds
	s_waitcnt vmcnt(8)
	s_waitcnt lgkmcnt(0)
	s_setprio 1
	v_mfma_f32_16x16x32_bf16 v[118:121], v[146:149], v[178:181], v[118:121]
	v_mfma_f32_16x16x32_bf16 v[118:121], v[150:153], v[182:185], v[118:121]
	s_barrier
	v_mfma_f32_16x16x32_bf16 v[114:117], v[154:157], v[178:181], v[114:117]
	v_mfma_f32_16x16x32_bf16 v[114:117], v[158:161], v[182:185], v[114:117]
	v_mfma_f32_16x16x32_bf16 v[126:129], v[162:165], v[178:181], v[126:129]
	v_mfma_f32_16x16x32_bf16 v[126:129], v[166:169], v[182:185], v[126:129]
	v_mfma_f32_16x16x32_bf16 v[122:125], v[170:173], v[178:181], v[122:125]
	v_mfma_f32_16x16x32_bf16 v[122:125], v[174:177], v[182:185], v[122:125]
	v_mfma_f32_16x16x32_bf16 v[98:101], v[170:173], v[186:189], v[98:101]
	v_mfma_f32_16x16x32_bf16 v[98:101], v[174:177], v[190:193], v[98:101]
	v_mfma_f32_16x16x32_bf16 v[106:109], v[162:165], v[186:189], v[106:109]
	v_mfma_f32_16x16x32_bf16 v[106:109], v[166:169], v[190:193], v[106:109]
	v_mfma_f32_16x16x32_bf16 v[102:105], v[154:157], v[186:189], v[102:105]
	v_mfma_f32_16x16x32_bf16 v[102:105], v[158:161], v[190:193], v[102:105]
	v_mfma_f32_16x16x32_bf16 v[110:113], v[146:149], v[186:189], v[110:113]
	v_mfma_f32_16x16x32_bf16 v[110:113], v[150:153], v[190:193], v[110:113]
	v_mfma_f32_16x16x32_bf16 v[94:97], v[146:149], v[194:197], v[94:97]
	v_mfma_f32_16x16x32_bf16 v[94:97], v[150:153], v[198:201], v[94:97]
	v_mfma_f32_16x16x32_bf16 v[86:89], v[154:157], v[194:197], v[86:89]
	v_mfma_f32_16x16x32_bf16 v[86:89], v[158:161], v[198:201], v[86:89]
	v_mfma_f32_16x16x32_bf16 v[90:93], v[162:165], v[194:197], v[90:93]
	v_mfma_f32_16x16x32_bf16 v[90:93], v[166:169], v[198:201], v[90:93]
	v_mfma_f32_16x16x32_bf16 v[82:85], v[170:173], v[194:197], v[82:85]
	v_mfma_f32_16x16x32_bf16 v[82:85], v[174:177], v[198:201], v[82:85]
	v_mfma_f32_16x16x32_bf16 v[70:73], v[170:173], v[202:205], v[70:73]
	v_mfma_f32_16x16x32_bf16 v[70:73], v[174:177], v[206:209], v[70:73]
	v_mfma_f32_16x16x32_bf16 v[74:77], v[162:165], v[202:205], v[74:77]
	v_mfma_f32_16x16x32_bf16 v[74:77], v[166:169], v[206:209], v[74:77]
	v_mfma_f32_16x16x32_bf16 v[66:69], v[154:157], v[202:205], v[66:69]
	v_mfma_f32_16x16x32_bf16 v[66:69], v[158:161], v[206:209], v[66:69]
	v_mfma_f32_16x16x32_bf16 v[78:81], v[146:149], v[202:205], v[78:81]
	v_mfma_f32_16x16x32_bf16 v[78:81], v[150:153], v[206:209], v[78:81]
	s_setprio 0
	s_barrier
	s_mov_b32 m0, s54
	s_or_b32 s81, s80, 0x80
	ds_read_b128 v[178:181], v140 offset:49152
	ds_read_b128 v[182:185], v140 offset:50176
	ds_read_b128 v[186:189], v140 offset:51200
	ds_read_b128 v[190:193], v140 offset:52224
	ds_read_b128 v[194:197], v140 offset:53248
	ds_read_b128 v[198:201], v140 offset:54272
	ds_read_b128 v[202:205], v140 offset:55296
	ds_read_b128 v[206:209], v140 offset:56320
	buffer_load_dwordx4 v137, s[20:23], s81 offen lds
	s_add_i32 s81, s80, 0x80080
	s_mov_b32 m0, s55
	s_add_i32 s78, s78, 0x80080
	buffer_load_dwordx4 v137, s[20:23], s81 offen lds
	s_add_i32 s81, s80, 0x100080
	s_mov_b32 m0, s58
	s_add_i32 s80, s80, 0x180080
	buffer_load_dwordx4 v137, s[20:23], s81 offen lds
	s_mov_b32 m0, s59
	s_nop 0
	buffer_load_dwordx4 v137, s[20:23], s80 offen lds
	s_mov_b32 m0, s56
	s_nop 0
	buffer_load_dwordx4 v136, s[16:19], s79 offen lds
	s_mov_b32 m0, s57
	s_nop 0
	buffer_load_dwordx4 v136, s[16:19], s78 offen lds
	s_waitcnt vmcnt(8)
	s_waitcnt lgkmcnt(0)
	s_setprio 1
	v_mfma_f32_16x16x32_bf16 v[62:65], v[146:149], v[178:181], v[62:65]
	v_mfma_f32_16x16x32_bf16 v[62:65], v[150:153], v[182:185], v[62:65]
	s_barrier
	v_mfma_f32_16x16x32_bf16 v[54:57], v[154:157], v[178:181], v[54:57]
	v_mfma_f32_16x16x32_bf16 v[54:57], v[158:161], v[182:185], v[54:57]
	v_mfma_f32_16x16x32_bf16 v[58:61], v[162:165], v[178:181], v[58:61]
	v_mfma_f32_16x16x32_bf16 v[58:61], v[166:169], v[182:185], v[58:61]
	v_mfma_f32_16x16x32_bf16 v[50:53], v[170:173], v[178:181], v[50:53]
	v_mfma_f32_16x16x32_bf16 v[50:53], v[174:177], v[182:185], v[50:53]
	v_mfma_f32_16x16x32_bf16 v[34:37], v[170:173], v[186:189], v[34:37]
	v_mfma_f32_16x16x32_bf16 v[34:37], v[174:177], v[190:193], v[34:37]
	v_mfma_f32_16x16x32_bf16 v[42:45], v[162:165], v[186:189], v[42:45]
	v_mfma_f32_16x16x32_bf16 v[42:45], v[166:169], v[190:193], v[42:45]
	v_mfma_f32_16x16x32_bf16 v[38:41], v[154:157], v[186:189], v[38:41]
	v_mfma_f32_16x16x32_bf16 v[38:41], v[158:161], v[190:193], v[38:41]
	v_mfma_f32_16x16x32_bf16 v[46:49], v[146:149], v[186:189], v[46:49]
	v_mfma_f32_16x16x32_bf16 v[46:49], v[150:153], v[190:193], v[46:49]
	v_mfma_f32_16x16x32_bf16 v[30:33], v[146:149], v[194:197], v[30:33]
	v_mfma_f32_16x16x32_bf16 v[30:33], v[150:153], v[198:201], v[30:33]
	v_mfma_f32_16x16x32_bf16 v[22:25], v[154:157], v[194:197], v[22:25]
	v_mfma_f32_16x16x32_bf16 v[22:25], v[158:161], v[198:201], v[22:25]
	v_mfma_f32_16x16x32_bf16 v[26:29], v[162:165], v[194:197], v[26:29]
	v_mfma_f32_16x16x32_bf16 v[26:29], v[166:169], v[198:201], v[26:29]
	v_mfma_f32_16x16x32_bf16 v[18:21], v[170:173], v[194:197], v[18:21]
	v_mfma_f32_16x16x32_bf16 v[18:21], v[174:177], v[198:201], v[18:21]
	v_mfma_f32_16x16x32_bf16 v[2:5], v[170:173], v[202:205], v[2:5]
	v_mfma_f32_16x16x32_bf16 v[2:5], v[174:177], v[206:209], v[2:5]
	v_mfma_f32_16x16x32_bf16 v[10:13], v[162:165], v[202:205], v[10:13]
	v_mfma_f32_16x16x32_bf16 v[10:13], v[166:169], v[206:209], v[10:13]
	v_mfma_f32_16x16x32_bf16 v[6:9], v[154:157], v[202:205], v[6:9]
	v_mfma_f32_16x16x32_bf16 v[6:9], v[158:161], v[206:209], v[6:9]
	v_mfma_f32_16x16x32_bf16 v[14:17], v[146:149], v[202:205], v[14:17]
	v_mfma_f32_16x16x32_bf16 v[14:17], v[150:153], v[206:209], v[14:17]
	s_setprio 0
	s_barrier
	s_add_i32 s77, s77, 2
	s_addk_i32 s75, 0x100
	s_addk_i32 s76, 0x100
	s_cmp_ge_i32 s77, s13
	s_cbranch_scc0 .LBB0_1402
	s_and_b64 vcc, exec, s[46:47]
	s_cbranch_vccz .LBB0_1405

.LBB0_1519:
	ds_read_b128 v[134:137], v208
	ds_read_b128 v[138:141], v208 offset:1024
	ds_read_b128 v[142:145], v208 offset:2048
	ds_read_b128 v[146:149], v208 offset:3072
	ds_read_b128 v[150:153], v209
	ds_read_b128 v[154:157], v209 offset:1024
	ds_read_b128 v[158:161], v209 offset:2048
	ds_read_b128 v[162:165], v209 offset:3072
	s_add_i32 s18, s80, 0xffbf8080
	s_cmp_eq_u32 s65, s82
	s_cselect_b32 s83, s6, s18
	s_cselect_b32 s85, s7, s81
	s_or_b32 s84, s83, 0x80
	s_add_i32 s18, s80, 0xffea8000
	s_mov_b32 m0, s66
	ds_read_b128 v[166:169], v210
	ds_read_b128 v[170:173], v210 offset:1024
	ds_read_b128 v[174:177], v210 offset:2048
	ds_read_b128 v[178:181], v210 offset:3072
	ds_read_b128 v[182:185], v210 offset:4096
	ds_read_b128 v[186:189], v210 offset:5120
	ds_read_b128 v[190:193], v210 offset:6144
	ds_read_b128 v[194:197], v210 offset:7168
	buffer_load_dwordx4 v206, s[12:15], s18 offen lds
	s_mov_b32 m0, s69
	s_nop 0
	buffer_load_dwordx4 v206, s[12:15], s80 offen lds
	s_waitcnt vmcnt(8)
	s_waitcnt lgkmcnt(0)
	s_setprio 1
	v_mfma_f32_16x16x32_bf16 v[126:129], v[134:137], v[166:169], v[126:129]
	v_mfma_f32_16x16x32_bf16 v[126:129], v[138:141], v[170:173], v[126:129]
	s_barrier
	v_mfma_f32_16x16x32_bf16 v[122:125], v[142:145], v[166:169], v[122:125]
	v_mfma_f32_16x16x32_bf16 v[122:125], v[146:149], v[170:173], v[122:125]
	v_mfma_f32_16x16x32_bf16 v[110:113], v[150:153], v[166:169], v[110:113]
	v_mfma_f32_16x16x32_bf16 v[110:113], v[154:157], v[170:173], v[110:113]
	v_mfma_f32_16x16x32_bf16 v[102:105], v[158:161], v[166:169], v[102:105]
	v_mfma_f32_16x16x32_bf16 v[102:105], v[162:165], v[170:173], v[102:105]
	v_mfma_f32_16x16x32_bf16 v[86:89], v[158:161], v[174:177], v[86:89]
	v_mfma_f32_16x16x32_bf16 v[86:89], v[162:165], v[178:181], v[86:89]
	v_mfma_f32_16x16x32_bf16 v[94:97], v[150:153], v[174:177], v[94:97]
	v_mfma_f32_16x16x32_bf16 v[94:97], v[154:157], v[178:181], v[94:97]
	v_mfma_f32_16x16x32_bf16 v[114:117], v[142:145], v[174:177], v[114:117]
	v_mfma_f32_16x16x32_bf16 v[114:117], v[146:149], v[178:181], v[114:117]
	v_mfma_f32_16x16x32_bf16 v[118:121], v[134:137], v[174:177], v[118:121]
	v_mfma_f32_16x16x32_bf16 v[118:121], v[138:141], v[178:181], v[118:121]
	v_mfma_f32_16x16x32_bf16 v[106:109], v[134:137], v[182:185], v[106:109]
	v_mfma_f32_16x16x32_bf16 v[106:109], v[138:141], v[186:189], v[106:109]
	v_mfma_f32_16x16x32_bf16 v[98:101], v[142:145], v[182:185], v[98:101]
	v_mfma_f32_16x16x32_bf16 v[98:101], v[146:149], v[186:189], v[98:101]
	v_mfma_f32_16x16x32_bf16 v[78:81], v[150:153], v[182:185], v[78:81]
	v_mfma_f32_16x16x32_bf16 v[78:81], v[154:157], v[186:189], v[78:81]
	v_mfma_f32_16x16x32_bf16 v[74:77], v[158:161], v[182:185], v[74:77]
	v_mfma_f32_16x16x32_bf16 v[74:77], v[162:165], v[186:189], v[74:77]
	v_mfma_f32_16x16x32_bf16 v[66:69], v[158:161], v[190:193], v[66:69]
	v_mfma_f32_16x16x32_bf16 v[66:69], v[162:165], v[194:197], v[66:69]
	v_mfma_f32_16x16x32_bf16 v[70:73], v[150:153], v[190:193], v[70:73]
	v_mfma_f32_16x16x32_bf16 v[70:73], v[154:157], v[194:197], v[70:73]
	v_mfma_f32_16x16x32_bf16 v[82:85], v[142:145], v[190:193], v[82:85]
	v_mfma_f32_16x16x32_bf16 v[82:85], v[146:149], v[194:197], v[82:85]
	v_mfma_f32_16x16x32_bf16 v[90:93], v[134:137], v[190:193], v[90:93]
	v_mfma_f32_16x16x32_bf16 v[90:93], v[138:141], v[194:197], v[90:93]
	s_setprio 0
	s_barrier
	s_mov_b32 m0, s27
	s_mov_b32 s18, s14
	s_mov_b32 s19, s15
	ds_read_b128 v[166:169], v210 offset:16384
	ds_read_b128 v[170:173], v210 offset:17408
	ds_read_b128 v[174:177], v210 offset:18432
	ds_read_b128 v[178:181], v210 offset:19456
	ds_read_b128 v[182:185], v210 offset:20480
	ds_read_b128 v[186:189], v210 offset:21504
	ds_read_b128 v[190:193], v210 offset:22528
	ds_read_b128 v[194:197], v210 offset:23552
	buffer_load_dwordx4 v207, s[16:19], s85 offen lds
	s_add_i32 s86, s85, 0x158000
	s_mov_b32 m0, s30
	s_nop 0
	buffer_load_dwordx4 v207, s[16:19], s86 offen lds
	s_add_i32 s86, s85, 0x2b0000
	s_mov_b32 m0, s31
	s_nop 0
	buffer_load_dwordx4 v207, s[16:19], s86 offen lds
	s_add_i32 s86, s85, 0x408000
	s_mov_b32 m0, s50
	s_nop 0
	buffer_load_dwordx4 v207, s[16:19], s86 offen lds
	s_mov_b32 m0, s25
	s_add_i32 s86, s83, 0x158000
	buffer_load_dwordx4 v206, s[12:15], s83 offen lds
	s_mov_b32 m0, s51
	s_nop 0
	buffer_load_dwordx4 v206, s[12:15], s86 offen lds
	s_waitcnt vmcnt(8)
	s_waitcnt lgkmcnt(0)
	s_setprio 1
	v_mfma_f32_16x16x32_bf16 v[62:65], v[134:137], v[166:169], v[62:65]
	v_mfma_f32_16x16x32_bf16 v[62:65], v[138:141], v[170:173], v[62:65]
	s_barrier
	v_mfma_f32_16x16x32_bf16 v[58:61], v[142:145], v[166:169], v[58:61]
	v_mfma_f32_16x16x32_bf16 v[58:61], v[146:149], v[170:173], v[58:61]
	v_mfma_f32_16x16x32_bf16 v[46:49], v[150:153], v[166:169], v[46:49]
	v_mfma_f32_16x16x32_bf16 v[46:49], v[154:157], v[170:173], v[46:49]
	v_mfma_f32_16x16x32_bf16 v[38:41], v[158:161], v[166:169], v[38:41]
	v_mfma_f32_16x16x32_bf16 v[38:41], v[162:165], v[170:173], v[38:41]
	v_mfma_f32_16x16x32_bf16 v[22:25], v[158:161], v[174:177], v[22:25]
	v_mfma_f32_16x16x32_bf16 v[22:25], v[162:165], v[178:181], v[22:25]
	v_mfma_f32_16x16x32_bf16 v[30:33], v[150:153], v[174:177], v[30:33]
	v_mfma_f32_16x16x32_bf16 v[30:33], v[154:157], v[178:181], v[30:33]
	v_mfma_f32_16x16x32_bf16 v[50:53], v[142:145], v[174:177], v[50:53]
	v_mfma_f32_16x16x32_bf16 v[50:53], v[146:149], v[178:181], v[50:53]
	v_mfma_f32_16x16x32_bf16 v[54:57], v[134:137], v[174:177], v[54:57]
	v_mfma_f32_16x16x32_bf16 v[54:57], v[138:141], v[178:181], v[54:57]
	v_mfma_f32_16x16x32_bf16 v[42:45], v[134:137], v[182:185], v[42:45]
	v_mfma_f32_16x16x32_bf16 v[42:45], v[138:141], v[186:189], v[42:45]
	v_mfma_f32_16x16x32_bf16 v[34:37], v[142:145], v[182:185], v[34:37]
	v_mfma_f32_16x16x32_bf16 v[34:37], v[146:149], v[186:189], v[34:37]
	v_mfma_f32_16x16x32_bf16 v[14:17], v[150:153], v[182:185], v[14:17]
	v_mfma_f32_16x16x32_bf16 v[14:17], v[154:157], v[186:189], v[14:17]
	v_mfma_f32_16x16x32_bf16 v[10:13], v[158:161], v[182:185], v[10:13]
	v_mfma_f32_16x16x32_bf16 v[10:13], v[162:165], v[186:189], v[10:13]
	v_mfma_f32_16x16x32_bf16 v[2:5], v[158:161], v[190:193], v[2:5]
	v_mfma_f32_16x16x32_bf16 v[2:5], v[162:165], v[194:197], v[2:5]
	v_mfma_f32_16x16x32_bf16 v[6:9], v[150:153], v[190:193], v[6:9]
	v_mfma_f32_16x16x32_bf16 v[6:9], v[154:157], v[194:197], v[6:9]
	v_mfma_f32_16x16x32_bf16 v[18:21], v[142:145], v[190:193], v[18:21]
	v_mfma_f32_16x16x32_bf16 v[18:21], v[146:149], v[194:197], v[18:21]
	v_mfma_f32_16x16x32_bf16 v[26:29], v[134:137], v[190:193], v[26:29]
	v_mfma_f32_16x16x32_bf16 v[26:29], v[138:141], v[194:197], v[26:29]
	s_setprio 0
	s_barrier
	ds_read_b128 v[134:137], v211
	ds_read_b128 v[138:141], v211 offset:1024
	ds_read_b128 v[142:145], v211 offset:2048
	ds_read_b128 v[146:149], v211 offset:3072
	ds_read_b128 v[150:153], v212
	ds_read_b128 v[154:157], v212 offset:1024
	ds_read_b128 v[158:161], v212 offset:2048
	ds_read_b128 v[162:165], v212 offset:3072
	s_mov_b32 m0, s52
	s_add_i32 s86, s83, 0x2b0000
	ds_read_b128 v[166:169], v210 offset:32768
	ds_read_b128 v[170:173], v210 offset:33792
	ds_read_b128 v[174:177], v210 offset:34816
	ds_read_b128 v[178:181], v210 offset:35840
	ds_read_b128 v[182:185], v210 offset:36864
	ds_read_b128 v[186:189], v210 offset:37888
	ds_read_b128 v[190:193], v210 offset:38912
	ds_read_b128 v[194:197], v210 offset:39936
	buffer_load_dwordx4 v206, s[12:15], s86 offen lds
	s_add_i32 s86, s83, 0x408000
	s_mov_b32 m0, s53
	s_nop 0
	buffer_load_dwordx4 v206, s[12:15], s86 offen lds
	s_waitcnt vmcnt(8)
	s_waitcnt lgkmcnt(0)
	s_setprio 1
	v_mfma_f32_16x16x32_bf16 v[126:129], v[134:137], v[166:169], v[126:129]
	v_mfma_f32_16x16x32_bf16 v[126:129], v[138:141], v[170:173], v[126:129]
	s_barrier
	v_mfma_f32_16x16x32_bf16 v[122:125], v[142:145], v[166:169], v[122:125]
	v_mfma_f32_16x16x32_bf16 v[122:125], v[146:149], v[170:173], v[122:125]
	v_mfma_f32_16x16x32_bf16 v[110:113], v[150:153], v[166:169], v[110:113]
	v_mfma_f32_16x16x32_bf16 v[110:113], v[154:157], v[170:173], v[110:113]
	v_mfma_f32_16x16x32_bf16 v[102:105], v[158:161], v[166:169], v[102:105]
	v_mfma_f32_16x16x32_bf16 v[102:105], v[162:165], v[170:173], v[102:105]
	v_mfma_f32_16x16x32_bf16 v[86:89], v[158:161], v[174:177], v[86:89]
	v_mfma_f32_16x16x32_bf16 v[86:89], v[162:165], v[178:181], v[86:89]
	v_mfma_f32_16x16x32_bf16 v[94:97], v[150:153], v[174:177], v[94:97]
	v_mfma_f32_16x16x32_bf16 v[94:97], v[154:157], v[178:181], v[94:97]
	v_mfma_f32_16x16x32_bf16 v[114:117], v[142:145], v[174:177], v[114:117]
	v_mfma_f32_16x16x32_bf16 v[114:117], v[146:149], v[178:181], v[114:117]
	v_mfma_f32_16x16x32_bf16 v[118:121], v[134:137], v[174:177], v[118:121]
	v_mfma_f32_16x16x32_bf16 v[118:121], v[138:141], v[178:181], v[118:121]
	v_mfma_f32_16x16x32_bf16 v[106:109], v[134:137], v[182:185], v[106:109]
	v_mfma_f32_16x16x32_bf16 v[106:109], v[138:141], v[186:189], v[106:109]
	v_mfma_f32_16x16x32_bf16 v[98:101], v[142:145], v[182:185], v[98:101]
	v_mfma_f32_16x16x32_bf16 v[98:101], v[146:149], v[186:189], v[98:101]
	v_mfma_f32_16x16x32_bf16 v[78:81], v[150:153], v[182:185], v[78:81]
	v_mfma_f32_16x16x32_bf16 v[78:81], v[154:157], v[186:189], v[78:81]
	v_mfma_f32_16x16x32_bf16 v[74:77], v[158:161], v[182:185], v[74:77]
	v_mfma_f32_16x16x32_bf16 v[74:77], v[162:165], v[186:189], v[74:77]
	v_mfma_f32_16x16x32_bf16 v[66:69], v[158:161], v[190:193], v[66:69]
	v_mfma_f32_16x16x32_bf16 v[66:69], v[162:165], v[194:197], v[66:69]
	v_mfma_f32_16x16x32_bf16 v[70:73], v[150:153], v[190:193], v[70:73]
	v_mfma_f32_16x16x32_bf16 v[70:73], v[154:157], v[194:197], v[70:73]
	v_mfma_f32_16x16x32_bf16 v[82:85], v[142:145], v[190:193], v[82:85]
	v_mfma_f32_16x16x32_bf16 v[82:85], v[146:149], v[194:197], v[82:85]
	v_mfma_f32_16x16x32_bf16 v[90:93], v[134:137], v[190:193], v[90:93]
	v_mfma_f32_16x16x32_bf16 v[90:93], v[138:141], v[194:197], v[90:93]
	s_setprio 0
	s_barrier
	s_mov_b32 m0, s57
	s_or_b32 s86, s85, 0x80
	ds_read_b128 v[166:169], v210 offset:49152
	ds_read_b128 v[170:173], v210 offset:50176
	ds_read_b128 v[174:177], v210 offset:51200
	ds_read_b128 v[178:181], v210 offset:52224
	ds_read_b128 v[182:185], v210 offset:53248
	ds_read_b128 v[186:189], v210 offset:54272
	ds_read_b128 v[190:193], v210 offset:55296
	ds_read_b128 v[194:197], v210 offset:56320
	buffer_load_dwordx4 v207, s[16:19], s86 offen lds
	s_add_i32 s86, s85, 0x158080
	s_mov_b32 m0, s58
	s_add_i32 s83, s83, 0x158080
	buffer_load_dwordx4 v207, s[16:19], s86 offen lds
	s_add_i32 s86, s85, 0x2b0080
	s_mov_b32 m0, s61
	s_add_i32 s85, s85, 0x408080
	buffer_load_dwordx4 v207, s[16:19], s86 offen lds
	s_mov_b32 m0, s62
	s_nop 0
	buffer_load_dwordx4 v207, s[16:19], s85 offen lds
	s_mov_b32 m0, s59
	s_nop 0
	buffer_load_dwordx4 v206, s[12:15], s84 offen lds
	s_mov_b32 m0, s60
	s_nop 0
	buffer_load_dwordx4 v206, s[12:15], s83 offen lds
	s_waitcnt vmcnt(8)
	s_waitcnt lgkmcnt(0)
	s_setprio 1
	v_mfma_f32_16x16x32_bf16 v[62:65], v[134:137], v[166:169], v[62:65]
	v_mfma_f32_16x16x32_bf16 v[62:65], v[138:141], v[170:173], v[62:65]
	s_barrier
	v_mfma_f32_16x16x32_bf16 v[58:61], v[142:145], v[166:169], v[58:61]
	v_mfma_f32_16x16x32_bf16 v[58:61], v[146:149], v[170:173], v[58:61]
	v_mfma_f32_16x16x32_bf16 v[46:49], v[150:153], v[166:169], v[46:49]
	v_mfma_f32_16x16x32_bf16 v[46:49], v[154:157], v[170:173], v[46:49]
	v_mfma_f32_16x16x32_bf16 v[38:41], v[158:161], v[166:169], v[38:41]
	v_mfma_f32_16x16x32_bf16 v[38:41], v[162:165], v[170:173], v[38:41]
	v_mfma_f32_16x16x32_bf16 v[22:25], v[158:161], v[174:177], v[22:25]
	v_mfma_f32_16x16x32_bf16 v[22:25], v[162:165], v[178:181], v[22:25]
	v_mfma_f32_16x16x32_bf16 v[30:33], v[150:153], v[174:177], v[30:33]
	v_mfma_f32_16x16x32_bf16 v[30:33], v[154:157], v[178:181], v[30:33]
	v_mfma_f32_16x16x32_bf16 v[50:53], v[142:145], v[174:177], v[50:53]
	v_mfma_f32_16x16x32_bf16 v[50:53], v[146:149], v[178:181], v[50:53]
	v_mfma_f32_16x16x32_bf16 v[54:57], v[134:137], v[174:177], v[54:57]
	v_mfma_f32_16x16x32_bf16 v[54:57], v[138:141], v[178:181], v[54:57]
	v_mfma_f32_16x16x32_bf16 v[42:45], v[134:137], v[182:185], v[42:45]
	v_mfma_f32_16x16x32_bf16 v[42:45], v[138:141], v[186:189], v[42:45]
	v_mfma_f32_16x16x32_bf16 v[34:37], v[142:145], v[182:185], v[34:37]
	v_mfma_f32_16x16x32_bf16 v[34:37], v[146:149], v[186:189], v[34:37]
	v_mfma_f32_16x16x32_bf16 v[14:17], v[150:153], v[182:185], v[14:17]
	v_mfma_f32_16x16x32_bf16 v[14:17], v[154:157], v[186:189], v[14:17]
	v_mfma_f32_16x16x32_bf16 v[10:13], v[158:161], v[182:185], v[10:13]
	v_mfma_f32_16x16x32_bf16 v[10:13], v[162:165], v[186:189], v[10:13]
	v_mfma_f32_16x16x32_bf16 v[2:5], v[158:161], v[190:193], v[2:5]
	v_mfma_f32_16x16x32_bf16 v[2:5], v[162:165], v[194:197], v[2:5]
	v_mfma_f32_16x16x32_bf16 v[6:9], v[150:153], v[190:193], v[6:9]
	v_mfma_f32_16x16x32_bf16 v[6:9], v[154:157], v[194:197], v[6:9]
	v_mfma_f32_16x16x32_bf16 v[18:21], v[142:145], v[190:193], v[18:21]
	v_mfma_f32_16x16x32_bf16 v[18:21], v[146:149], v[194:197], v[18:21]
	v_mfma_f32_16x16x32_bf16 v[26:29], v[134:137], v[190:193], v[26:29]
	v_mfma_f32_16x16x32_bf16 v[26:29], v[138:141], v[194:197], v[26:29]
	s_setprio 0
	s_barrier
	s_add_i32 s82, s82, 2
	s_addk_i32 s80, 0x100
	s_addk_i32 s81, 0x100
	s_cmp_ge_i32 s82, s3
	s_cbranch_scc0 .LBB0_1519
	v_pk_mul_f32 v[182:183], v[128:129], 0.5 op_sel_hi:[1,0]
	v_pk_mul_f32 v[184:185], v[126:127], 0.5 op_sel_hi:[1,0]
	v_pk_mul_f32 v[186:187], v[124:125], 0.5 op_sel_hi:[1,0]
	v_pk_mul_f32 v[188:189], v[122:123], 0.5 op_sel_hi:[1,0]
	v_pk_mul_f32 v[196:197], v[112:113], 0.5 op_sel_hi:[1,0]
	v_pk_mul_f32 v[194:195], v[110:111], 0.5 op_sel_hi:[1,0]
	v_pk_mul_f32 v[192:193], v[104:105], 0.5 op_sel_hi:[1,0]
	v_pk_mul_f32 v[190:191], v[102:103], 0.5 op_sel_hi:[1,0]
	v_pk_mul_f32 v[180:181], v[120:121], 0.5 op_sel_hi:[1,0]
	v_pk_mul_f32 v[178:179], v[118:119], 0.5 op_sel_hi:[1,0]
	v_pk_mul_f32 v[176:177], v[116:117], 0.5 op_sel_hi:[1,0]
	v_pk_mul_f32 v[174:175], v[114:115], 0.5 op_sel_hi:[1,0]
	v_pk_mul_f32 v[170:171], v[96:97], 0.5 op_sel_hi:[1,0]
	v_pk_mul_f32 v[168:169], v[94:95], 0.5 op_sel_hi:[1,0]
	v_pk_mul_f32 v[166:167], v[88:89], 0.5 op_sel_hi:[1,0]
	v_pk_mul_f32 v[164:165], v[86:87], 0.5 op_sel_hi:[1,0]
	v_pk_mul_f32 v[162:163], v[108:109], 0.5 op_sel_hi:[1,0]
	v_pk_mul_f32 v[160:161], v[106:107], 0.5 op_sel_hi:[1,0]
	v_pk_mul_f32 v[158:159], v[100:101], 0.5 op_sel_hi:[1,0]
	v_pk_mul_f32 v[156:157], v[98:99], 0.5 op_sel_hi:[1,0]
	v_pk_mul_f32 v[154:155], v[80:81], 0.5 op_sel_hi:[1,0]
	v_pk_mul_f32 v[152:153], v[78:79], 0.5 op_sel_hi:[1,0]
	v_pk_mul_f32 v[150:151], v[76:77], 0.5 op_sel_hi:[1,0]
	v_pk_mul_f32 v[148:149], v[74:75], 0.5 op_sel_hi:[1,0]
	v_pk_mul_f32 v[144:145], v[92:93], 0.5 op_sel_hi:[1,0]
	v_pk_mul_f32 v[142:143], v[90:91], 0.5 op_sel_hi:[1,0]
	v_pk_mul_f32 v[140:141], v[84:85], 0.5 op_sel_hi:[1,0]
	v_pk_mul_f32 v[138:139], v[82:83], 0.5 op_sel_hi:[1,0]
	v_pk_mul_f32 v[136:137], v[72:73], 0.5 op_sel_hi:[1,0]
	v_pk_mul_f32 v[134:135], v[70:71], 0.5 op_sel_hi:[1,0]
	v_pk_mul_f32 v[128:129], v[68:69], 0.5 op_sel_hi:[1,0]
	v_pk_mul_f32 v[126:127], v[66:67], 0.5 op_sel_hi:[1,0]
	v_pk_mul_f32 v[122:123], v[64:65], 0.5 op_sel_hi:[1,0]
	v_pk_mul_f32 v[120:121], v[62:63], 0.5 op_sel_hi:[1,0]
	v_pk_mul_f32 v[118:119], v[60:61], 0.5 op_sel_hi:[1,0]
	v_pk_mul_f32 v[116:117], v[58:59], 0.5 op_sel_hi:[1,0]
	v_pk_mul_f32 v[112:113], v[48:49], 0.5 op_sel_hi:[1,0]
	v_pk_mul_f32 v[110:111], v[46:47], 0.5 op_sel_hi:[1,0]
	v_pk_mul_f32 v[108:109], v[40:41], 0.5 op_sel_hi:[1,0]
	v_pk_mul_f32 v[106:107], v[38:39], 0.5 op_sel_hi:[1,0]
	v_pk_mul_f32 v[104:105], v[56:57], 0.5 op_sel_hi:[1,0]
	v_pk_mul_f32 v[102:103], v[54:55], 0.5 op_sel_hi:[1,0]
	v_pk_mul_f32 v[100:101], v[52:53], 0.5 op_sel_hi:[1,0]
	v_pk_mul_f32 v[98:99], v[50:51], 0.5 op_sel_hi:[1,0]
	v_pk_mul_f32 v[96:97], v[32:33], 0.5 op_sel_hi:[1,0]
	v_pk_mul_f32 v[94:95], v[30:31], 0.5 op_sel_hi:[1,0]
	v_pk_mul_f32 v[92:93], v[24:25], 0.5 op_sel_hi:[1,0]
	v_pk_mul_f32 v[90:91], v[22:23], 0.5 op_sel_hi:[1,0]
	v_pk_mul_f32 v[88:89], v[44:45], 0.5 op_sel_hi:[1,0]
	v_pk_mul_f32 v[86:87], v[42:43], 0.5 op_sel_hi:[1,0]
	v_pk_mul_f32 v[84:85], v[36:37], 0.5 op_sel_hi:[1,0]
	v_pk_mul_f32 v[82:83], v[34:35], 0.5 op_sel_hi:[1,0]
	v_pk_mul_f32 v[80:81], v[16:17], 0.5 op_sel_hi:[1,0]
	v_pk_mul_f32 v[78:79], v[14:15], 0.5 op_sel_hi:[1,0]
	v_pk_mul_f32 v[76:77], v[12:13], 0.5 op_sel_hi:[1,0]
	v_pk_mul_f32 v[74:75], v[10:11], 0.5 op_sel_hi:[1,0]
	v_pk_mul_f32 v[72:73], v[28:29], 0.5 op_sel_hi:[1,0]
	v_pk_mul_f32 v[70:71], v[26:27], 0.5 op_sel_hi:[1,0]
	v_pk_mul_f32 v[68:69], v[20:21], 0.5 op_sel_hi:[1,0]
	v_pk_mul_f32 v[66:67], v[18:19], 0.5 op_sel_hi:[1,0]
	v_pk_mul_f32 v[64:65], v[8:9], 0.5 op_sel_hi:[1,0]
	v_pk_mul_f32 v[62:63], v[6:7], 0.5 op_sel_hi:[1,0]
	v_pk_mul_f32 v[60:61], v[4:5], 0.5 op_sel_hi:[1,0]
	v_pk_mul_f32 v[58:59], v[2:3], 0.5 op_sel_hi:[1,0]
	s_and_b64 vcc, exec, s[40:41]
	s_cbranch_vccz .LBB0_1522
